# GEMM K-loops skip the two in-order vmcnt(8) waits that only wait for the epilogue stores' acknowledgements in the first iteration after an epilogue
# baseline (speedup 1.0000x reference)
; #define PG8_STAGE(bufoff, gbase, voff) do { _Pragma("unroll") for (int _i = 0; _i < 2; ++_i) \
;         __builtin_amdgcn_global_load_lds((const unsigned*)((const char*)(gbase) + (voff)[_i]), (PG8_LAS unsigned*)(lds + (bufoff) + ldsw + _i * 8192), 16, 0, 0); } while (0)
; #define PG8_WAIT_V(n) asm volatile("s_waitcnt vmcnt(" #n ")" ::: "memory")
; #define PG8_BAR __builtin_amdgcn_s_barrier()
; template <class Epi, class Sched, bool ALIGN_EPI = false, bool SP2 = false>
; __device__ __forceinline__ void gemm_phase(PG8_LAS unsigned char* lds, const Gemm g, const Sched& S, const Epi& E, const int wid) {
;     ...
;     for (int i = 0; i < 2; ++i) { int R, C; stage_rc(tid * 16 + i * 8192, R, C); const int Rb = Epi::PERM ? ((R & ~31) + perm32(R & 31)) : R;
;         voffA[i] = (unsigned)(R * K + C) * 2u; voffB[i] = (unsigned)(Rb * K + C) * 2u; }
;     const size_t kstep = (size_t)(BK * 2);
;     const size_t hstep = (size_t)HALF * K * 2;
;     const size_t tstep = 2 * hstep;
;     const unsigned ldsw = (unsigned)wid * 1024u;
;     const int aoff = lds_byte(wr * 64 + fr, fq * 8), boff = lds_byte(wc * 32 + fr, fq * 8);
;     ...
;         PG8_STAGE(PG8_SB(0, 0), cB, voffB); PG8_STAGE(PG8_SB(0, 1), cB + hstep, voffB); PG8_STAGE(PG8_SA(0, 0), cA, voffA); PG8_STAGE(PG8_SA(0, 1), cA + hstep, voffA);
;         if (wr == 1) PG8_BAR;
;         PG8_WAIT_V(2); PG8_BAR;
;         PG8_STAGE(PG8_SB(1, 0), cB + kstep, voffB); PG8_STAGE(PG8_SA(1, 0), cA + kstep, voffA); PG8_STAGE(PG8_SB(1, 1), cB + hstep + kstep, voffB);
;         PG8_WAIT_V(6); PG8_BAR;
.LBB0_271:
	v_readlane_b32 s10, v254, 7
	v_readlane_b32 s11, v254, 8
	s_load_dwordx2 s[38:39], s[10:11], 0x108
	v_readlane_b32 s48, v254, 10
	s_mov_b64 s[40:41], 0x80
	v_lshl_add_u64 v[6:7], v[6:7], 0, s[40:41]
	s_waitcnt vmcnt(2)
	s_waitcnt lgkmcnt(0)
	s_add_u32 s10, s38, 0x1a000000
	s_addc_u32 s11, s39, 0
	s_add_u32 s12, s38, 0x1e000000
	s_addc_u32 s13, s39, 0
	s_add_u32 s14, s38, 0x1f000000
	s_addc_u32 s15, s39, 0
	s_add_u32 s16, s38, 0x20000000
	s_addc_u32 s17, s39, 0
	s_add_u32 s18, s38, 0x24000000
	s_addc_u32 s19, s39, 0
	s_add_u32 s20, s38, 0x24400000
	s_addc_u32 s21, s39, 0
	s_add_u32 s22, s38, 0x28400000
	s_addc_u32 s23, s39, 0
	s_add_u32 s24, s38, 0x2c400000
	s_addc_u32 s25, s39, 0
	s_add_u32 s26, s38, 0x30400000
	s_addc_u32 s27, s39, 0
	s_add_u32 s28, s38, 0x32400000
	s_addc_u32 s29, s39, 0
	s_add_u32 s30, s38, 0xc00000
	s_addc_u32 s31, s39, 0
	s_add_u32 s34, s38, 0x100000
	s_addc_u32 s35, s39, 0
	s_add_u32 s36, s38, 0x400000
	s_addc_u32 s37, s39, 0
	s_add_u32 s38, s38, 0x800000
	s_addc_u32 s39, s39, 0
	s_bfe_u32 s5, s48, 0x20006
	s_add_i32 m0, s76, 0x18000
	s_lshl_b32 s81, s4, 6
	s_lshl_b32 s82, s5, 5
	s_barrier
	global_load_lds_dwordx4 v[6:7], off
	v_lshl_add_u64 v[4:5], v[4:5], 0, s[40:41]
	s_add_i32 m0, s76, 0x1a000
	s_add_i32 s83, s76, 0x8000
	s_add_i32 s84, s76, 0xa000
	global_load_lds_dwordx4 v[4:5], off
	v_lshl_add_u64 v[0:1], v[0:1], 0, s[40:41]
	s_mov_b32 m0, s83
	s_add_u32 s42, s62, 0x100080
	global_load_lds_dwordx4 v[0:1], off
	v_lshl_add_u64 v[0:1], v[2:3], 0, s[40:41]
	s_mov_b32 m0, s84
	s_addc_u32 s43, s63, 0
	global_load_lds_dwordx4 v[0:1], off
	s_add_i32 m0, s76, 0x1c000
	v_lshl_add_u64 v[0:1], s[42:43], 0, v[146:147]
	global_load_lds_dwordx4 v[0:1], off
	v_lshl_add_u64 v[0:1], s[42:43], 0, v[150:151]
	s_add_i32 m0, s76, 0x1e000
	v_lshlrev_b32_e32 v3, 6, v8
	global_load_lds_dwordx4 v[0:1], off
	v_and_b32_e32 v1, 0xfffffc00, v13
	v_and_b32_e32 v0, 48, v8
	v_lshl_add_u32 v2, s4, 13, v1
	s_movk_i32 s4, 0x3c0
	v_and_or_b32 v0, v3, s4, v0
	v_lshlrev_b32_e32 v3, 2, v8
	v_and_b32_e32 v3, 32, v3
	v_lshl_add_u32 v1, s5, 12, v1
	v_bitop3_b32 v2, v0, v2, v3 bitop3:0xde
	v_bitop3_b32 v161, v0, v1, v3 bitop3:0xde
	v_lshlrev_b32_e32 v0, 16, v9
	s_cmpk_lt_u32 s48, 0x100
	v_and_b32_e32 v0, 0xfffe0000, v0
	s_cselect_b64 s[42:43], -1, 0
	s_cmp_lt_u32 s5, 2
	v_lshl_add_u32 v0, v10, 13, v0
	v_and_b32_e32 v1, 1, v9
	s_cselect_b64 s[44:45], -1, 0
	s_cmp_eq_u32 s5, 2
	v_readlane_b32 s4, v254, 9
	v_lshl_or_b32 v0, v1, 6, v0
	s_cselect_b64 s[46:47], -1, 0
	s_ashr_i32 s87, s4, 31
	v_readlane_b32 s4, v254, 0
	v_lshl_add_u32 v152, v11, 1, v0
	v_lshlrev_b32_e32 v0, 16, v12
	s_and_b32 s85, s48, 0x80
	s_and_b32 s86, s82, 32
	s_ashr_i32 s88, s4, 31
	v_and_b32_e32 v0, 0xfffe0000, v0
	s_waitcnt vmcnt(6)
	s_mov_b32 s99, 0
	s_add_u32 s48, s6, 0x4000
	v_lshl_add_u32 v0, v14, 13, v0
	v_and_b32_e32 v1, 1, v12
	s_addc_u32 s49, s7, 0
	v_lshl_or_b32 v0, v1, 6, v0
	s_add_i32 s89, 0, 0x10000
	s_add_i32 s90, 0, 0x14000
	v_mov_b32_e32 v153, v147
	v_lshl_add_u32 v154, v15, 1, v0
	v_mov_b32_e32 v155, v147
	v_mov_b64_e32 v[156:157], 0x1440
	v_mov_b64_e32 v[158:159], 0x143f
	v_add_u32_e32 v163, s89, v161
	v_add_u32_e32 v165, s90, v161
	v_add_u32_e32 v167, 0, v2
	s_lshl_b32 s91, s82, 1
	s_barrier
	v_readlane_b32 s5, v254, 1
	s_branch .LBB0_274

; #define PG8_STAGE(bufoff, gbase, voff) do { _Pragma("unroll") for (int _i = 0; _i < 2; ++_i) \
;         __builtin_amdgcn_global_load_lds((const unsigned*)((const char*)(gbase) + (voff)[_i]), (PG8_LAS unsigned*)(lds + (bufoff) + ldsw + _i * 8192), 16, 0, 0); } while (0)
; #define PG8_LDA(dst, b, h) do { _Pragma("unroll") for (int m = 0; m < 4; ++m) _Pragma("unroll") for (int k = 0; k < 2; ++k) dst[m][k] = *(const PG8_LAS bf16x8*)(lds + PG8_SA(b, h) + aoff + m * 2048 + k * 1024); } while (0)
; #define PG8_LDB(dst, b, h) do { _Pragma("unroll") for (int n = 0; n < 2; ++n) _Pragma("unroll") for (int k = 0; k < 2; ++k) dst[n][k] = *(const PG8_LAS bf16x8*)(lds + PG8_SB(b, h) + boff + n * 2048 + k * 1024); } while (0)
; #define PG8_MMA(ai, bj, At, Bt) do { __builtin_amdgcn_s_setprio(1); _Pragma("unroll") for (int m = 0; m < 4; ++m) _Pragma("unroll") for (int n = 0; n < 2; ++n) _Pragma("unroll") for (int k = 0; k < 2; ++k) \
;         acc[ai][bj][m][n] = __builtin_amdgcn_mfma_f32_16x16x32_bf16(Bt[n][k], At[m][k], acc[ai][bj][m][n], 0, 0, 0); __builtin_amdgcn_s_setprio(0); } while (0)
; #define PG8_WAIT_V(n) asm volatile("s_waitcnt vmcnt(" #n ")" ::: "memory")
; #define PG8_WAIT_L(n) asm volatile("s_waitcnt lgkmcnt(" #n ")" ::: "memory")
; #define PG8_BAR __builtin_amdgcn_s_barrier()
; #define PG8_SCHED __builtin_amdgcn_sched_barrier(0)
; template <class Epi, class Sched, bool ALIGN_EPI = false, bool SP2 = false>
; __device__ __forceinline__ void gemm_phase(PG8_LAS unsigned char* lds, const Gemm g, const Sched& S, const Epi& E, const int wid) {
;     ...
;             PG8_LDB(B0, 0, 0); PG8_LDB(B1, 0, 1); PG8_SCHED; PG8_LDA(At, 0, 0); PG8_STAGE(PG8_SA(1, 1), a1 + hstep, voffA);
;             PG8_WAIT_V(8); PG8_WAIT_L(0); PG8_BAR; PG8_MMA(0, 0, At, B0); PG8_MMA(0, 1, At, B1); PG8_BAR; PG8_SCHED;
;             PG8_LDA(At, 0, 1); PG8_STAGE(PG8_SB(0, 0), b2, voffB); PG8_STAGE(PG8_SB(0, 1), b2 + hstep, voffB); PG8_STAGE(PG8_SA(0, 0), a2, voffA);
;             PG8_WAIT_V(8); PG8_WAIT_L(0); PG8_BAR; PG8_MMA(1, 0, At, B0); PG8_MMA(1, 1, At, B1); PG8_BAR; PG8_SCHED;
.LBB0_277:
	ds_read_b128 v[128:131], v163
	ds_read_b128 v[132:135], v163 offset:1024
	ds_read_b128 v[136:139], v163 offset:2048
	ds_read_b128 v[140:143], v163 offset:3072
	ds_read_b128 v[168:171], v165
	s_nop 0
	ds_read_b128 v[172:175], v165 offset:1024
	ds_read_b128 v[176:179], v165 offset:2048
	ds_read_b128 v[180:183], v165 offset:3072
	s_add_u32 s62, s60, 0xfff00080
	s_addc_u32 s63, s61, -1
	s_cmp_eq_u32 s70, 60
	s_cselect_b32 s67, s53, s63
	s_cselect_b32 s66, s59, s62
	s_cselect_b32 s63, s51, s69
	s_cselect_b32 s62, s65, s68
	v_lshl_add_u64 v[216:217], s[60:61], 0, v[152:153]
	s_add_i32 m0, s76, 0xc000
	ds_read_b128 v[184:187], v167
	ds_read_b128 v[188:191], v167 offset:1024
	ds_read_b128 v[192:195], v167 offset:2048
	ds_read_b128 v[196:199], v167 offset:3072
	ds_read_b128 v[200:203], v167 offset:4096
	ds_read_b128 v[204:207], v167 offset:5120
	ds_read_b128 v[208:211], v167 offset:6144
	ds_read_b128 v[212:215], v167 offset:7168
	global_load_lds_dwordx4 v[216:217], off
	v_lshl_add_u64 v[216:217], s[60:61], 0, v[154:155]
	s_add_i32 m0, s76, 0xe000
	s_nop 0
	global_load_lds_dwordx4 v[216:217], off
	s_cmp_lg_u32 s99, 0
	s_cbranch_scc1 .Lg277_skip1
	s_waitcnt vmcnt(8)
.Lg277_skip1:
	s_waitcnt lgkmcnt(0)
	s_barrier
	s_setprio 1
	s_waitcnt lgkmcnt(0)
	v_mfma_f32_16x16x32_bf16 v[124:127], v[128:131], v[184:187], v[124:127]
	v_mfma_f32_16x16x32_bf16 v[120:123], v[136:139], v[184:187], v[120:123]
	v_mfma_f32_16x16x32_bf16 v[108:111], v[128:131], v[192:195], v[108:111]
	v_mfma_f32_16x16x32_bf16 v[104:107], v[136:139], v[192:195], v[104:107]
	v_mfma_f32_16x16x32_bf16 v[92:95], v[128:131], v[200:203], v[92:95]
	v_mfma_f32_16x16x32_bf16 v[88:91], v[136:139], v[200:203], v[88:91]
	v_mfma_f32_16x16x32_bf16 v[76:79], v[128:131], v[208:211], v[76:79]
	v_mfma_f32_16x16x32_bf16 v[72:75], v[136:139], v[208:211], v[72:75]
	v_mfma_f32_16x16x32_bf16 v[124:127], v[132:135], v[188:191], v[124:127]
	v_mfma_f32_16x16x32_bf16 v[120:123], v[140:143], v[188:191], v[120:123]
	v_mfma_f32_16x16x32_bf16 v[108:111], v[132:135], v[196:199], v[108:111]
	v_mfma_f32_16x16x32_bf16 v[104:107], v[140:143], v[196:199], v[104:107]
	v_mfma_f32_16x16x32_bf16 v[92:95], v[132:135], v[204:207], v[92:95]
	v_mfma_f32_16x16x32_bf16 v[88:91], v[140:143], v[204:207], v[88:91]
	v_mfma_f32_16x16x32_bf16 v[76:79], v[132:135], v[212:215], v[76:79]
	v_mfma_f32_16x16x32_bf16 v[72:75], v[140:143], v[212:215], v[72:75]
	s_setprio 0
	s_setprio 1
	v_mfma_f32_16x16x32_bf16 v[116:119], v[168:171], v[184:187], v[116:119]
	v_mfma_f32_16x16x32_bf16 v[112:115], v[176:179], v[184:187], v[112:115]
	v_mfma_f32_16x16x32_bf16 v[100:103], v[168:171], v[192:195], v[100:103]
	v_mfma_f32_16x16x32_bf16 v[96:99], v[176:179], v[192:195], v[96:99]
	v_mfma_f32_16x16x32_bf16 v[84:87], v[168:171], v[200:203], v[84:87]
	v_mfma_f32_16x16x32_bf16 v[80:83], v[176:179], v[200:203], v[80:83]
	v_mfma_f32_16x16x32_bf16 v[68:71], v[168:171], v[208:211], v[68:71]
	v_mfma_f32_16x16x32_bf16 v[64:67], v[176:179], v[208:211], v[64:67]
	v_mfma_f32_16x16x32_bf16 v[116:119], v[172:175], v[188:191], v[116:119]
	v_mfma_f32_16x16x32_bf16 v[112:115], v[180:183], v[188:191], v[112:115]
	v_mfma_f32_16x16x32_bf16 v[100:103], v[172:175], v[196:199], v[100:103]
	v_mfma_f32_16x16x32_bf16 v[96:99], v[180:183], v[196:199], v[96:99]
	v_mfma_f32_16x16x32_bf16 v[84:87], v[172:175], v[204:207], v[84:87]
	v_mfma_f32_16x16x32_bf16 v[80:83], v[180:183], v[204:207], v[80:83]
	v_mfma_f32_16x16x32_bf16 v[68:71], v[172:175], v[212:215], v[68:71]
	v_mfma_f32_16x16x32_bf16 v[64:67], v[180:183], v[212:215], v[64:67]
	s_setprio 0
	s_barrier
	s_add_i32 s71, s89, s75
	v_lshl_add_u64 v[216:217], s[62:63], 0, v[146:147]
	s_mov_b32 m0, s71
	ds_read_b128 v[184:187], v167 offset:16384
	ds_read_b128 v[188:191], v167 offset:17408
	ds_read_b128 v[192:195], v167 offset:18432
	ds_read_b128 v[196:199], v167 offset:19456
	ds_read_b128 v[200:203], v167 offset:20480
	ds_read_b128 v[204:207], v167 offset:21504
	ds_read_b128 v[208:211], v167 offset:22528
	ds_read_b128 v[212:215], v167 offset:23552
	global_load_lds_dwordx4 v[216:217], off
	s_add_i32 m0, s71, 0x2000
	s_add_u32 s72, s62, 0x100000
	v_lshl_add_u64 v[218:219], s[62:63], 0, v[150:151]
	s_addc_u32 s73, s63, 0
	s_add_i32 s71, s90, s75
	global_load_lds_dwordx4 v[218:219], off
	v_lshl_add_u64 v[220:221], s[72:73], 0, v[146:147]
	s_mov_b32 m0, s71
	v_lshl_add_u64 v[222:223], s[66:67], 0, v[148:149]
	global_load_lds_dwordx4 v[220:221], off
	v_lshl_add_u64 v[220:221], s[72:73], 0, v[150:151]
	s_add_i32 m0, s71, 0x2000
	s_nop 0
	global_load_lds_dwordx4 v[220:221], off
	v_lshl_add_u64 v[220:221], s[66:67], 0, v[144:145]
	s_mov_b32 m0, s76
	s_nop 0
	global_load_lds_dwordx4 v[220:221], off
	s_mov_b32 m0, s77
	s_nop 0
	global_load_lds_dwordx4 v[222:223], off
	s_cmp_lg_u32 s99, 0
	s_cbranch_scc1 .Lg277_skip2
	s_waitcnt vmcnt(8)
; #define PG8_STAGE(bufoff, gbase, voff) do { _Pragma("unroll") for (int _i = 0; _i < 2; ++_i) \
;         __builtin_amdgcn_global_load_lds((const unsigned*)((const char*)(gbase) + (voff)[_i]), (PG8_LAS unsigned*)(lds + (bufoff) + ldsw + _i * 8192), 16, 0, 0); } while (0)
; #define PG8_LDA(dst, b, h) do { _Pragma("unroll") for (int m = 0; m < 4; ++m) _Pragma("unroll") for (int k = 0; k < 2; ++k) dst[m][k] = *(const PG8_LAS bf16x8*)(lds + PG8_SA(b, h) + aoff + m * 2048 + k * 1024); } while (0)
; #define PG8_LDB(dst, b, h) do { _Pragma("unroll") for (int n = 0; n < 2; ++n) _Pragma("unroll") for (int k = 0; k < 2; ++k) dst[n][k] = *(const PG8_LAS bf16x8*)(lds + PG8_SB(b, h) + boff + n * 2048 + k * 1024); } while (0)
; #define PG8_MMA(ai, bj, At, Bt) do { __builtin_amdgcn_s_setprio(1); _Pragma("unroll") for (int m = 0; m < 4; ++m) _Pragma("unroll") for (int n = 0; n < 2; ++n) _Pragma("unroll") for (int k = 0; k < 2; ++k) \
;         acc[ai][bj][m][n] = __builtin_amdgcn_mfma_f32_16x16x32_bf16(Bt[n][k], At[m][k], acc[ai][bj][m][n], 0, 0, 0); __builtin_amdgcn_s_setprio(0); } while (0)
; #define PG8_WAIT_V(n) asm volatile("s_waitcnt vmcnt(" #n ")" ::: "memory")
; #define PG8_WAIT_L(n) asm volatile("s_waitcnt lgkmcnt(" #n ")" ::: "memory")
; #define PG8_BAR __builtin_amdgcn_s_barrier()
; #define PG8_SCHED __builtin_amdgcn_sched_barrier(0)
; template <class Epi, class Sched, bool ALIGN_EPI = false, bool SP2 = false>
; __device__ __forceinline__ void gemm_phase(PG8_LAS unsigned char* lds, const Gemm g, const Sched& S, const Epi& E, const int wid) {
;     ...
;             PG8_WAIT_V(8); PG8_WAIT_L(0); PG8_BAR; PG8_MMA(1, 0, At, B0); PG8_MMA(1, 1, At, B1); PG8_BAR; PG8_SCHED;
;             PG8_LDB(B0, 1, 0); PG8_LDB(B1, 1, 1); PG8_SCHED; PG8_LDA(At, 1, 0); PG8_STAGE(PG8_SA(0, 1), a2 + hstep, voffA);
;             PG8_WAIT_V(8); PG8_WAIT_L(0); PG8_BAR; PG8_MMA(0, 0, At, B0); PG8_MMA(0, 1, At, B1); PG8_BAR; PG8_SCHED;
.Lg277_skip2:
	s_mov_b32 s99, 0
	s_waitcnt lgkmcnt(0)
	s_barrier
	s_setprio 1
	s_waitcnt lgkmcnt(0)
	v_mfma_f32_16x16x32_bf16 v[60:63], v[128:131], v[184:187], v[60:63]
	v_mfma_f32_16x16x32_bf16 v[56:59], v[136:139], v[184:187], v[56:59]
	v_mfma_f32_16x16x32_bf16 v[44:47], v[128:131], v[192:195], v[44:47]
	v_mfma_f32_16x16x32_bf16 v[40:43], v[136:139], v[192:195], v[40:43]
	v_mfma_f32_16x16x32_bf16 v[28:31], v[128:131], v[200:203], v[28:31]
	v_mfma_f32_16x16x32_bf16 v[24:27], v[136:139], v[200:203], v[24:27]
	v_mfma_f32_16x16x32_bf16 v[12:15], v[128:131], v[208:211], v[12:15]
	v_mfma_f32_16x16x32_bf16 v[8:11], v[136:139], v[208:211], v[8:11]
	v_mfma_f32_16x16x32_bf16 v[60:63], v[132:135], v[188:191], v[60:63]
	v_mfma_f32_16x16x32_bf16 v[56:59], v[140:143], v[188:191], v[56:59]
	v_mfma_f32_16x16x32_bf16 v[44:47], v[132:135], v[196:199], v[44:47]
	v_mfma_f32_16x16x32_bf16 v[40:43], v[140:143], v[196:199], v[40:43]
	v_mfma_f32_16x16x32_bf16 v[28:31], v[132:135], v[204:207], v[28:31]
	v_mfma_f32_16x16x32_bf16 v[24:27], v[140:143], v[204:207], v[24:27]
	v_mfma_f32_16x16x32_bf16 v[12:15], v[132:135], v[212:215], v[12:15]
	v_mfma_f32_16x16x32_bf16 v[8:11], v[140:143], v[212:215], v[8:11]
	s_setprio 0
	s_setprio 1
	v_mfma_f32_16x16x32_bf16 v[52:55], v[168:171], v[184:187], v[52:55]
	v_mfma_f32_16x16x32_bf16 v[48:51], v[176:179], v[184:187], v[48:51]
	v_mfma_f32_16x16x32_bf16 v[36:39], v[168:171], v[192:195], v[36:39]
	v_mfma_f32_16x16x32_bf16 v[32:35], v[176:179], v[192:195], v[32:35]
	v_mfma_f32_16x16x32_bf16 v[20:23], v[168:171], v[200:203], v[20:23]
	v_mfma_f32_16x16x32_bf16 v[16:19], v[176:179], v[200:203], v[16:19]
	v_mfma_f32_16x16x32_bf16 v[4:7], v[168:171], v[208:211], v[4:7]
	v_mfma_f32_16x16x32_bf16 v[0:3], v[176:179], v[208:211], v[0:3]
	v_mfma_f32_16x16x32_bf16 v[52:55], v[172:175], v[188:191], v[52:55]
	v_mfma_f32_16x16x32_bf16 v[48:51], v[180:183], v[188:191], v[48:51]
	v_mfma_f32_16x16x32_bf16 v[36:39], v[172:175], v[196:199], v[36:39]
	v_mfma_f32_16x16x32_bf16 v[32:35], v[180:183], v[196:199], v[32:35]
	v_mfma_f32_16x16x32_bf16 v[20:23], v[172:175], v[204:207], v[20:23]
	v_mfma_f32_16x16x32_bf16 v[16:19], v[180:183], v[204:207], v[16:19]
	v_mfma_f32_16x16x32_bf16 v[4:7], v[172:175], v[212:215], v[4:7]
	v_mfma_f32_16x16x32_bf16 v[0:3], v[180:183], v[212:215], v[0:3]
	s_setprio 0
	s_barrier
	s_add_i32 s71, 0, 0x18000
	s_add_i32 s72, 0, 0x1c000
	v_add_u32_e32 v140, s71, v161
	v_add_u32_e32 v160, s72, v161
	ds_read_b128 v[128:131], v140
	ds_read_b128 v[132:135], v140 offset:1024
	ds_read_b128 v[136:139], v140 offset:2048
	ds_read_b128 v[140:143], v140 offset:3072
	ds_read_b128 v[168:171], v160
	ds_read_b128 v[172:175], v160 offset:1024
	ds_read_b128 v[176:179], v160 offset:2048
	ds_read_b128 v[180:183], v160 offset:3072
	s_add_u32 s66, s66, 0x100000
	s_addc_u32 s67, s67, 0
	s_mov_b32 m0, s78
	v_lshl_add_u64 v[224:225], s[66:67], 0, v[144:145]
	ds_read_b128 v[184:187], v167 offset:32768
	ds_read_b128 v[188:191], v167 offset:33792
	ds_read_b128 v[192:195], v167 offset:34816
	ds_read_b128 v[196:199], v167 offset:35840
	ds_read_b128 v[200:203], v167 offset:36864
	ds_read_b128 v[204:207], v167 offset:37888
	ds_read_b128 v[208:211], v167 offset:38912
	ds_read_b128 v[212:215], v167 offset:39936
	global_load_lds_dwordx4 v[224:225], off
	v_lshl_add_u64 v[224:225], s[66:67], 0, v[148:149]
	s_mov_b32 m0, s79
	s_nop 0
	global_load_lds_dwordx4 v[224:225], off
	s_waitcnt vmcnt(8)
	s_waitcnt lgkmcnt(0)
	s_barrier
	s_setprio 1
	s_waitcnt lgkmcnt(0)
	v_mfma_f32_16x16x32_bf16 v[124:127], v[128:131], v[184:187], v[124:127]
	v_mfma_f32_16x16x32_bf16 v[120:123], v[136:139], v[184:187], v[120:123]
	v_mfma_f32_16x16x32_bf16 v[108:111], v[128:131], v[192:195], v[108:111]
	v_mfma_f32_16x16x32_bf16 v[104:107], v[136:139], v[192:195], v[104:107]
	v_mfma_f32_16x16x32_bf16 v[92:95], v[128:131], v[200:203], v[92:95]
	v_mfma_f32_16x16x32_bf16 v[88:91], v[136:139], v[200:203], v[88:91]
	v_mfma_f32_16x16x32_bf16 v[76:79], v[128:131], v[208:211], v[76:79]
	v_mfma_f32_16x16x32_bf16 v[72:75], v[136:139], v[208:211], v[72:75]
	v_mfma_f32_16x16x32_bf16 v[124:127], v[132:135], v[188:191], v[124:127]
	v_mfma_f32_16x16x32_bf16 v[120:123], v[140:143], v[188:191], v[120:123]
	v_mfma_f32_16x16x32_bf16 v[108:111], v[132:135], v[196:199], v[108:111]
	v_mfma_f32_16x16x32_bf16 v[104:107], v[140:143], v[196:199], v[104:107]
	v_mfma_f32_16x16x32_bf16 v[92:95], v[132:135], v[204:207], v[92:95]
	v_mfma_f32_16x16x32_bf16 v[88:91], v[140:143], v[204:207], v[88:91]
	v_mfma_f32_16x16x32_bf16 v[76:79], v[132:135], v[212:215], v[76:79]
	v_mfma_f32_16x16x32_bf16 v[72:75], v[140:143], v[212:215], v[72:75]
	s_setprio 0
	s_setprio 1
	v_mfma_f32_16x16x32_bf16 v[116:119], v[168:171], v[184:187], v[116:119]
	v_mfma_f32_16x16x32_bf16 v[112:115], v[176:179], v[184:187], v[112:115]
	v_mfma_f32_16x16x32_bf16 v[100:103], v[168:171], v[192:195], v[100:103]
	v_mfma_f32_16x16x32_bf16 v[96:99], v[176:179], v[192:195], v[96:99]
	v_mfma_f32_16x16x32_bf16 v[84:87], v[168:171], v[200:203], v[84:87]
	v_mfma_f32_16x16x32_bf16 v[80:83], v[176:179], v[200:203], v[80:83]
	v_mfma_f32_16x16x32_bf16 v[68:71], v[168:171], v[208:211], v[68:71]
	v_mfma_f32_16x16x32_bf16 v[64:67], v[176:179], v[208:211], v[64:67]
	v_mfma_f32_16x16x32_bf16 v[116:119], v[172:175], v[188:191], v[116:119]
	v_mfma_f32_16x16x32_bf16 v[112:115], v[180:183], v[188:191], v[112:115]
	v_mfma_f32_16x16x32_bf16 v[100:103], v[172:175], v[196:199], v[100:103]
	v_mfma_f32_16x16x32_bf16 v[96:99], v[180:183], v[196:199], v[96:99]
	v_mfma_f32_16x16x32_bf16 v[84:87], v[172:175], v[204:207], v[84:87]
	v_mfma_f32_16x16x32_bf16 v[80:83], v[180:183], v[204:207], v[80:83]
	v_mfma_f32_16x16x32_bf16 v[68:71], v[172:175], v[212:215], v[68:71]
	v_mfma_f32_16x16x32_bf16 v[64:67], v[180:183], v[212:215], v[64:67]
	s_setprio 0
	s_barrier
; #define PG8_STAGE(bufoff, gbase, voff) do { _Pragma("unroll") for (int _i = 0; _i < 2; ++_i) \
;         __builtin_amdgcn_global_load_lds((const unsigned*)((const char*)(gbase) + (voff)[_i]), (PG8_LAS unsigned*)(lds + (bufoff) + ldsw + _i * 8192), 16, 0, 0); } while (0)
; #define PG8_LDA(dst, b, h) do { _Pragma("unroll") for (int m = 0; m < 4; ++m) _Pragma("unroll") for (int k = 0; k < 2; ++k) dst[m][k] = *(const PG8_LAS bf16x8*)(lds + PG8_SA(b, h) + aoff + m * 2048 + k * 1024); } while (0)
; #define PG8_MMA(ai, bj, At, Bt) do { __builtin_amdgcn_s_setprio(1); _Pragma("unroll") for (int m = 0; m < 4; ++m) _Pragma("unroll") for (int n = 0; n < 2; ++n) _Pragma("unroll") for (int k = 0; k < 2; ++k) \
;         acc[ai][bj][m][n] = __builtin_amdgcn_mfma_f32_16x16x32_bf16(Bt[n][k], At[m][k], acc[ai][bj][m][n], 0, 0, 0); __builtin_amdgcn_s_setprio(0); } while (0)
; #define PG8_WAIT_V(n) asm volatile("s_waitcnt vmcnt(" #n ")" ::: "memory")
; #define PG8_WAIT_L(n) asm volatile("s_waitcnt lgkmcnt(" #n ")" ::: "memory")
; #define PG8_BAR __builtin_amdgcn_s_barrier()
; #define PG8_SCHED __builtin_amdgcn_sched_barrier(0)
; template <class Epi, class Sched, bool ALIGN_EPI = false, bool SP2 = false>
; __device__ __forceinline__ void gemm_phase(PG8_LAS unsigned char* lds, const Gemm g, const Sched& S, const Epi& E, const int wid) {
;     ...
;             PG8_LDA(At, 1, 1); PG8_STAGE(PG8_SB(1, 0), b3, voffB); PG8_STAGE(PG8_SB(1, 1), b3 + hstep, voffB); PG8_STAGE(PG8_SA(1, 0), a3, voffA);
;             PG8_WAIT_V(8); PG8_WAIT_L(0); PG8_BAR; PG8_MMA(1, 0, At, B0); PG8_MMA(1, 1, At, B1); PG8_BAR; PG8_SCHED;
;     ...
;         if constexpr (ALIGN_EPI) { if (wr == 0) PG8_BAR; }
	s_add_i32 s66, s71, s75
	v_lshl_add_u64 v[216:217], v[216:217], 0, s[40:41]
	s_mov_b32 m0, s66
	ds_read_b128 v[184:187], v167 offset:49152
	ds_read_b128 v[188:191], v167 offset:50176
	ds_read_b128 v[192:195], v167 offset:51200
	ds_read_b128 v[196:199], v167 offset:52224
	ds_read_b128 v[200:203], v167 offset:53248
	ds_read_b128 v[204:207], v167 offset:54272
	ds_read_b128 v[208:211], v167 offset:55296
	ds_read_b128 v[212:215], v167 offset:56320
	global_load_lds_dwordx4 v[216:217], off
	s_add_i32 m0, s66, 0x2000
	s_add_u32 s62, s62, 0x100080
	v_lshl_add_u64 v[216:217], v[218:219], 0, s[40:41]
	s_addc_u32 s63, s63, 0
	s_add_i32 s66, s72, s75
	global_load_lds_dwordx4 v[216:217], off
	v_lshl_add_u64 v[216:217], s[62:63], 0, v[146:147]
	s_mov_b32 m0, s66
	s_nop 0
	global_load_lds_dwordx4 v[216:217], off
	v_lshl_add_u64 v[216:217], s[62:63], 0, v[150:151]
	s_add_i32 m0, s66, 0x2000
	s_nop 0
	global_load_lds_dwordx4 v[216:217], off
	v_lshl_add_u64 v[216:217], v[220:221], 0, s[40:41]
	s_mov_b32 m0, s83
	s_nop 0
	global_load_lds_dwordx4 v[216:217], off
	v_lshl_add_u64 v[216:217], v[222:223], 0, s[40:41]
	s_mov_b32 m0, s84
	s_nop 0
	global_load_lds_dwordx4 v[216:217], off
	s_waitcnt vmcnt(8)
	s_waitcnt lgkmcnt(0)
	s_barrier
	s_setprio 1
	s_waitcnt lgkmcnt(0)
	v_mfma_f32_16x16x32_bf16 v[60:63], v[128:131], v[184:187], v[60:63]
	v_mfma_f32_16x16x32_bf16 v[56:59], v[136:139], v[184:187], v[56:59]
	v_mfma_f32_16x16x32_bf16 v[44:47], v[128:131], v[192:195], v[44:47]
	v_mfma_f32_16x16x32_bf16 v[40:43], v[136:139], v[192:195], v[40:43]
	v_mfma_f32_16x16x32_bf16 v[28:31], v[128:131], v[200:203], v[28:31]
	v_mfma_f32_16x16x32_bf16 v[24:27], v[136:139], v[200:203], v[24:27]
	v_mfma_f32_16x16x32_bf16 v[12:15], v[128:131], v[208:211], v[12:15]
	v_mfma_f32_16x16x32_bf16 v[8:11], v[136:139], v[208:211], v[8:11]
	v_mfma_f32_16x16x32_bf16 v[60:63], v[132:135], v[188:191], v[60:63]
	v_mfma_f32_16x16x32_bf16 v[56:59], v[140:143], v[188:191], v[56:59]
	v_mfma_f32_16x16x32_bf16 v[44:47], v[132:135], v[196:199], v[44:47]
	v_mfma_f32_16x16x32_bf16 v[40:43], v[140:143], v[196:199], v[40:43]
	v_mfma_f32_16x16x32_bf16 v[28:31], v[132:135], v[204:207], v[28:31]
	v_mfma_f32_16x16x32_bf16 v[24:27], v[140:143], v[204:207], v[24:27]
	v_mfma_f32_16x16x32_bf16 v[12:15], v[132:135], v[212:215], v[12:15]
	v_mfma_f32_16x16x32_bf16 v[8:11], v[140:143], v[212:215], v[8:11]
	s_setprio 0
	s_setprio 1
	v_mfma_f32_16x16x32_bf16 v[52:55], v[168:171], v[184:187], v[52:55]
	v_mfma_f32_16x16x32_bf16 v[48:51], v[176:179], v[184:187], v[48:51]
	v_mfma_f32_16x16x32_bf16 v[36:39], v[168:171], v[192:195], v[36:39]
	v_mfma_f32_16x16x32_bf16 v[32:35], v[176:179], v[192:195], v[32:35]
	v_mfma_f32_16x16x32_bf16 v[20:23], v[168:171], v[200:203], v[20:23]
	v_mfma_f32_16x16x32_bf16 v[16:19], v[176:179], v[200:203], v[16:19]
	v_mfma_f32_16x16x32_bf16 v[4:7], v[168:171], v[208:211], v[4:7]
	v_mfma_f32_16x16x32_bf16 v[0:3], v[176:179], v[208:211], v[0:3]
	v_mfma_f32_16x16x32_bf16 v[52:55], v[172:175], v[188:191], v[52:55]
	v_mfma_f32_16x16x32_bf16 v[48:51], v[180:183], v[188:191], v[48:51]
	v_mfma_f32_16x16x32_bf16 v[36:39], v[172:175], v[196:199], v[36:39]
	v_mfma_f32_16x16x32_bf16 v[32:35], v[180:183], v[196:199], v[32:35]
	v_mfma_f32_16x16x32_bf16 v[20:23], v[172:175], v[204:207], v[20:23]
	v_mfma_f32_16x16x32_bf16 v[16:19], v[180:183], v[204:207], v[16:19]
	v_mfma_f32_16x16x32_bf16 v[4:7], v[172:175], v[212:215], v[4:7]
	v_mfma_f32_16x16x32_bf16 v[0:3], v[180:183], v[212:215], v[0:3]
	s_setprio 0
	s_barrier
	s_add_i32 s70, s70, 2
	s_add_u32 s60, s60, 0x100
	s_addc_u32 s61, s61, 0
	s_add_u32 s68, s68, 0x100
	s_addc_u32 s69, s69, 0
	s_cmp_gt_u32 s70, 61
	s_cbranch_scc0 .LBB0_277
	s_mov_b32 s99, 1
	s_and_b64 vcc, exec, s[42:43]
	s_cbranch_vccz .LBB0_280
	s_barrier

; #define PG8_STAGE(bufoff, gbase, voff) do { _Pragma("unroll") for (int _i = 0; _i < 2; ++_i) \
;         __builtin_amdgcn_global_load_lds((const unsigned*)((const char*)(gbase) + (voff)[_i]), (PG8_LAS unsigned*)(lds + (bufoff) + ldsw + _i * 8192), 16, 0, 0); } while (0)
; #define PG8_WAIT_V(n) asm volatile("s_waitcnt vmcnt(" #n ")" ::: "memory")
; #define PG8_BAR __builtin_amdgcn_s_barrier()
; template <class Epi, class Sched, bool ALIGN_EPI = false, bool SP2 = false>
; __device__ __forceinline__ void gemm_phase(PG8_LAS unsigned char* lds, const Gemm g, const Sched& S, const Epi& E, const int wid) {
;     ...
;     f32x4 acc[2][2][4][2];
; #pragma unroll
;     for (int a = 0; a < 2; ++a)
; #pragma unroll
;         for (int b = 0; b < 2; ++b)
; #pragma unroll
;             for (int m = 0; m < 4; ++m)
; #pragma unroll
;                 for (int n = 0; n < 2; ++n) acc[a][b][m][n] = (f32x4){0.f, 0.f, 0.f, 0.f};
;     bf16x8 At[4][2], B0[2][2], B1[2][2];
;     const char* cA = (const char*)g.A + (size_t)cur.pm * tstep; const char* cB = (const char*)g.Bt + (size_t)cur.pn * tstep;
;     S.a_ready(cur);
;     if constexpr (SP2) {
;         PG8_STAGE(PG8_SB(0, 0), cB, voffB); PG8_STAGE(PG8_SB(0, 1), cB + hstep, voffB); PG8_STAGE(PG8_SA(0, 0), cA, voffA); PG8_STAGE(PG8_SA(0, 1), cA + hstep, voffA);
;         if (wr == 1) PG8_BAR;
;         PG8_WAIT_V(2); PG8_BAR;
;         PG8_STAGE(PG8_SB(1, 0), cB + kstep, voffB); PG8_STAGE(PG8_SA(1, 0), cA + kstep, voffA); PG8_STAGE(PG8_SB(1, 1), cB + hstep + kstep, voffB);
;         PG8_WAIT_V(6); PG8_BAR;
.LBB0_2594:
	v_readlane_b32 s8, v254, 7
	v_readlane_b32 s9, v254, 8
	s_load_dwordx2 s[8:9], s[8:9], 0x108
	s_mov_b64 s[10:11], 0x80
	v_lshl_add_u64 v[8:9], v[8:9], 0, s[10:11]
	s_waitcnt vmcnt(2)
	s_barrier
	s_waitcnt lgkmcnt(0)
	s_add_u32 s39, s8, 0x32400000
	s_addc_u32 s40, s9, 0
	s_add_u32 s8, s8, 0x1a000000
	s_addc_u32 s9, s9, 0
	s_lshl_b32 s41, s4, 6
	s_lshl_b32 s7, s4, 13
	v_readlane_b32 s4, v254, 2
	s_lshl_b32 s4, s4, 5
	s_and_b32 s42, s4, 0x60
	s_add_i32 m0, s13, 0x18000
	s_lshr_b32 s14, s42, 3
	global_load_lds_dwordx4 v[8:9], off
	v_lshl_add_u64 v[6:7], v[6:7], 0, s[10:11]
	s_add_i32 m0, s13, 0x1a000
	s_add_i32 s43, s13, 0x8000
	s_add_i32 s44, s13, 0xa000
	global_load_lds_dwordx4 v[6:7], off
	v_lshl_add_u64 v[2:3], v[2:3], 0, s[10:11]
	s_mov_b32 m0, s43
	s_add_u32 s4, s26, 0x80080
	global_load_lds_dwordx4 v[2:3], off
	v_lshl_add_u64 v[2:3], v[4:5], 0, s[10:11]
	s_mov_b32 m0, s44
	s_addc_u32 s5, s27, 0
	global_load_lds_dwordx4 v[2:3], off
	s_add_i32 m0, s13, 0x1c000
	v_lshl_add_u64 v[2:3], s[4:5], 0, v[170:171]
	global_load_lds_dwordx4 v[2:3], off
	v_lshl_add_u64 v[2:3], s[4:5], 0, v[174:175]
	s_add_i32 m0, s13, 0x1e000
	v_lshlrev_b32_e32 v5, 6, v0
	global_load_lds_dwordx4 v[2:3], off
	v_ashrrev_i32_e32 v2, 6, v0
	v_and_b32_e32 v3, 48, v0
	s_movk_i32 s4, 0x3c0
	v_lshlrev_b32_e32 v0, 2, v0
	v_lshl_add_u32 v4, v2, 10, s7
	v_and_or_b32 v3, v5, s4, v3
	v_and_b32_e32 v0, 32, v0
	v_add_lshl_u32 v2, v2, s14, 10
	v_bitop3_b32 v4, v3, v4, v0 bitop3:0xde
	v_bitop3_b32 v194, v3, v2, v0 bitop3:0xde
	v_lshlrev_b32_e32 v0, 15, v10
	v_and_b32_e32 v0, 0xffff0000, v0
	v_lshl_add_u32 v0, v11, 12, v0
	v_and_b32_e32 v2, 1, v10
	v_lshl_or_b32 v0, v2, 6, v0
	v_lshl_add_u32 v176, v12, 1, v0
	v_lshlrev_b32_e32 v0, 15, v13
	v_and_b32_e32 v0, 0xffff0000, v0
	v_lshl_add_u32 v0, v14, 12, v0
	v_and_b32_e32 v2, 1, v13
	s_waitcnt vmcnt(6)
	s_mov_b32 s99, 0
	v_readlane_b32 s4, v254, 10
	v_lshl_or_b32 v0, v2, 6, v0
	v_mov_b32_e32 v2, v1
	v_mov_b32_e32 v3, v1
	s_cmpk_lt_u32 s4, 0x100
	v_readlane_b32 s4, v254, 0
	v_lshl_add_u32 v178, v15, 1, v0
	v_mov_b32_e32 v0, v1
	v_add_u32_e32 v195, 0, v4
	v_mov_b64_e32 v[6:7], v[2:3]
	v_mov_b64_e32 v[10:11], v[2:3]
	v_mov_b64_e32 v[22:23], v[2:3]
	v_mov_b64_e32 v[26:27], v[2:3]
	v_mov_b64_e32 v[38:39], v[2:3]
	v_mov_b64_e32 v[42:43], v[2:3]
	v_mov_b64_e32 v[54:55], v[2:3]
	v_mov_b64_e32 v[58:59], v[2:3]
	v_mov_b64_e32 v[14:15], v[2:3]
	v_mov_b64_e32 v[18:19], v[2:3]
	v_mov_b64_e32 v[30:31], v[2:3]
	v_mov_b64_e32 v[34:35], v[2:3]
	v_mov_b64_e32 v[46:47], v[2:3]
	v_mov_b64_e32 v[50:51], v[2:3]
	v_mov_b64_e32 v[70:71], v[2:3]
	v_mov_b64_e32 v[74:75], v[2:3]
	v_mov_b64_e32 v[94:95], v[2:3]
	v_mov_b64_e32 v[98:99], v[2:3]
	v_mov_b64_e32 v[126:127], v[2:3]
	v_mov_b64_e32 v[130:131], v[2:3]
	v_mov_b64_e32 v[150:151], v[2:3]
	v_mov_b64_e32 v[154:155], v[2:3]
	v_mov_b64_e32 v[158:159], v[2:3]
	v_mov_b64_e32 v[162:163], v[2:3]
	v_mov_b64_e32 v[110:111], v[2:3]
	v_mov_b64_e32 v[114:115], v[2:3]
	v_mov_b64_e32 v[134:135], v[2:3]
	v_mov_b64_e32 v[138:139], v[2:3]
	v_mov_b64_e32 v[102:103], v[2:3]
	v_mov_b64_e32 v[106:107], v[2:3]
	v_mov_b64_e32 v[78:79], v[2:3]
	v_mov_b64_e32 v[82:83], v[2:3]
	s_cselect_b64 s[14:15], -1, 0
	s_ashr_i32 s45, s4, 31
	v_mov_b32_e32 v177, v1
	v_mov_b32_e32 v179, v1
	s_mov_b32 s46, 0
	v_mov_b64_e32 v[180:181], 0x400
	v_mov_b64_e32 v[182:183], 0x3ff
	s_add_i32 s47, 0, 0x10000
	s_add_i32 s48, 0, 0x14000
	v_mov_b64_e32 v[4:5], v[0:1]
	v_mov_b64_e32 v[8:9], v[0:1]
	v_mov_b64_e32 v[20:21], v[0:1]
	v_mov_b64_e32 v[24:25], v[0:1]
	v_mov_b64_e32 v[36:37], v[0:1]
	v_mov_b64_e32 v[40:41], v[0:1]
	v_mov_b64_e32 v[52:53], v[0:1]
	v_mov_b64_e32 v[56:57], v[0:1]
	v_mov_b64_e32 v[12:13], v[0:1]
	v_mov_b64_e32 v[16:17], v[0:1]
	v_mov_b64_e32 v[28:29], v[0:1]
	v_mov_b64_e32 v[32:33], v[0:1]
	v_mov_b64_e32 v[44:45], v[0:1]
	v_mov_b64_e32 v[48:49], v[0:1]
	v_mov_b64_e32 v[68:69], v[0:1]
	v_mov_b64_e32 v[72:73], v[0:1]
	v_mov_b64_e32 v[92:93], v[0:1]
	v_mov_b64_e32 v[96:97], v[0:1]
	v_mov_b64_e32 v[124:125], v[0:1]
	v_mov_b64_e32 v[128:129], v[0:1]
	v_mov_b64_e32 v[148:149], v[0:1]
	v_mov_b64_e32 v[152:153], v[0:1]
	v_mov_b64_e32 v[156:157], v[0:1]
	v_mov_b64_e32 v[160:161], v[0:1]
	v_mov_b64_e32 v[108:109], v[0:1]
	v_mov_b64_e32 v[112:113], v[0:1]
	v_mov_b64_e32 v[132:133], v[0:1]
	v_mov_b64_e32 v[136:137], v[0:1]
	v_mov_b64_e32 v[100:101], v[0:1]
	v_mov_b64_e32 v[104:105], v[0:1]
	v_mov_b64_e32 v[76:77], v[0:1]
	v_mov_b64_e32 v[80:81], v[0:1]
	s_barrier
	v_readlane_b32 s5, v254, 1
	s_branch .LBB0_2597

; #define PG8_STAGE(bufoff, gbase, voff) do { _Pragma("unroll") for (int _i = 0; _i < 2; ++_i) \
;         __builtin_amdgcn_global_load_lds((const unsigned*)((const char*)(gbase) + (voff)[_i]), (PG8_LAS unsigned*)(lds + (bufoff) + ldsw + _i * 8192), 16, 0, 0); } while (0)
; #define PG8_LDA(dst, b, h) do { _Pragma("unroll") for (int m = 0; m < 4; ++m) _Pragma("unroll") for (int k = 0; k < 2; ++k) dst[m][k] = *(const PG8_LAS bf16x8*)(lds + PG8_SA(b, h) + aoff + m * 2048 + k * 1024); } while (0)
; #define PG8_LDB(dst, b, h) do { _Pragma("unroll") for (int n = 0; n < 2; ++n) _Pragma("unroll") for (int k = 0; k < 2; ++k) dst[n][k] = *(const PG8_LAS bf16x8*)(lds + PG8_SB(b, h) + boff + n * 2048 + k * 1024); } while (0)
; #define PG8_MMA(ai, bj, At, Bt) do { __builtin_amdgcn_s_setprio(1); _Pragma("unroll") for (int m = 0; m < 4; ++m) _Pragma("unroll") for (int n = 0; n < 2; ++n) _Pragma("unroll") for (int k = 0; k < 2; ++k) \
;         acc[ai][bj][m][n] = __builtin_amdgcn_mfma_f32_16x16x32_bf16(Bt[n][k], At[m][k], acc[ai][bj][m][n], 0, 0, 0); __builtin_amdgcn_s_setprio(0); } while (0)
; #define PG8_WAIT_V(n) asm volatile("s_waitcnt vmcnt(" #n ")" ::: "memory")
; #define PG8_WAIT_L(n) asm volatile("s_waitcnt lgkmcnt(" #n ")" ::: "memory")
; #define PG8_BAR __builtin_amdgcn_s_barrier()
; #define PG8_SCHED __builtin_amdgcn_sched_barrier(0)
; template <class Epi, class Sched, bool ALIGN_EPI = false, bool SP2 = false>
; __device__ __forceinline__ void gemm_phase(PG8_LAS unsigned char* lds, const Gemm g, const Sched& S, const Epi& E, const int wid) {
;     ...
;             PG8_LDB(B0, 0, 0); PG8_LDB(B1, 0, 1); PG8_SCHED; PG8_LDA(At, 0, 0); PG8_STAGE(PG8_SA(1, 1), a1 + hstep, voffA);
;             PG8_WAIT_V(8); PG8_WAIT_L(0); PG8_BAR; PG8_MMA(0, 0, At, B0); PG8_MMA(0, 1, At, B1); PG8_BAR; PG8_SCHED;
;             PG8_LDA(At, 0, 1); PG8_STAGE(PG8_SB(0, 0), b2, voffB); PG8_STAGE(PG8_SB(0, 1), b2 + hstep, voffB); PG8_STAGE(PG8_SA(0, 0), a2, voffA);
;             PG8_WAIT_V(8); PG8_WAIT_L(0); PG8_BAR; PG8_MMA(1, 0, At, B0); PG8_MMA(1, 1, At, B1); PG8_BAR; PG8_SCHED;
.LBB0_2604:
	v_add_u32_e32 v0, s47, v194
	ds_read_b128 v[60:63], v0
	ds_read_b128 v[64:67], v0 offset:1024
	ds_read_b128 v[84:87], v0 offset:2048
	ds_read_b128 v[88:91], v0 offset:3072
	v_add_u32_e32 v0, s48, v194
	ds_read_b128 v[116:119], v0
	ds_read_b128 v[120:123], v0 offset:1024
	ds_read_b128 v[140:143], v0 offset:2048
	ds_read_b128 v[144:147], v0 offset:3072
	s_add_u32 s26, s24, 0xfff80080
	s_addc_u32 s27, s25, -1
	s_cmp_eq_u32 s52, 28
	s_cselect_b32 s29, s7, s27
	s_cselect_b32 s28, s19, s26
	s_cselect_b32 s27, s17, s51
	s_cselect_b32 s26, s49, s50
	v_lshl_add_u64 v[2:3], s[24:25], 0, v[176:177]
	s_add_i32 m0, s13, 0xc000
	ds_read_b128 v[164:167], v195
	ds_read_b128 v[184:187], v195 offset:1024
	ds_read_b128 v[188:191], v195 offset:2048
	ds_read_b128 v[196:199], v195 offset:3072
	ds_read_b128 v[200:203], v195 offset:4096
	ds_read_b128 v[204:207], v195 offset:5120
	ds_read_b128 v[208:211], v195 offset:6144
	ds_read_b128 v[212:215], v195 offset:7168
	global_load_lds_dwordx4 v[2:3], off
	v_lshl_add_u64 v[2:3], s[24:25], 0, v[178:179]
	s_add_i32 m0, s13, 0xe000
	s_nop 0
	global_load_lds_dwordx4 v[2:3], off
	s_cmp_lg_u32 s99, 0
	s_cbranch_scc1 .Lg2604_skip1
	s_waitcnt vmcnt(8)
.Lg2604_skip1:
	s_waitcnt lgkmcnt(0)
	s_barrier
	s_setprio 1
	s_waitcnt lgkmcnt(0)
	v_mfma_f32_16x16x32_bf16 v[80:83], v[60:63], v[164:167], v[80:83]
	v_mfma_f32_16x16x32_bf16 v[76:79], v[84:87], v[164:167], v[76:79]
	v_mfma_f32_16x16x32_bf16 v[104:107], v[60:63], v[188:191], v[104:107]
	v_mfma_f32_16x16x32_bf16 v[100:103], v[84:87], v[188:191], v[100:103]
	v_mfma_f32_16x16x32_bf16 v[136:139], v[60:63], v[200:203], v[136:139]
	v_mfma_f32_16x16x32_bf16 v[132:135], v[84:87], v[200:203], v[132:135]
	v_mfma_f32_16x16x32_bf16 v[112:115], v[60:63], v[208:211], v[112:115]
	v_mfma_f32_16x16x32_bf16 v[108:111], v[84:87], v[208:211], v[108:111]
	v_mfma_f32_16x16x32_bf16 v[80:83], v[64:67], v[184:187], v[80:83]
	v_mfma_f32_16x16x32_bf16 v[76:79], v[88:91], v[184:187], v[76:79]
	v_mfma_f32_16x16x32_bf16 v[104:107], v[64:67], v[196:199], v[104:107]
	v_mfma_f32_16x16x32_bf16 v[100:103], v[88:91], v[196:199], v[100:103]
	v_mfma_f32_16x16x32_bf16 v[136:139], v[64:67], v[204:207], v[136:139]
	v_mfma_f32_16x16x32_bf16 v[132:135], v[88:91], v[204:207], v[132:135]
	v_mfma_f32_16x16x32_bf16 v[112:115], v[64:67], v[212:215], v[112:115]
	v_mfma_f32_16x16x32_bf16 v[108:111], v[88:91], v[212:215], v[108:111]
	s_setprio 0
	s_setprio 1
	v_mfma_f32_16x16x32_bf16 v[160:163], v[116:119], v[164:167], v[160:163]
	v_mfma_f32_16x16x32_bf16 v[156:159], v[140:143], v[164:167], v[156:159]
	v_mfma_f32_16x16x32_bf16 v[152:155], v[116:119], v[188:191], v[152:155]
	v_mfma_f32_16x16x32_bf16 v[148:151], v[140:143], v[188:191], v[148:151]
	v_mfma_f32_16x16x32_bf16 v[128:131], v[116:119], v[200:203], v[128:131]
	v_mfma_f32_16x16x32_bf16 v[124:127], v[140:143], v[200:203], v[124:127]
	v_mfma_f32_16x16x32_bf16 v[96:99], v[116:119], v[208:211], v[96:99]
	v_mfma_f32_16x16x32_bf16 v[92:95], v[140:143], v[208:211], v[92:95]
	v_mfma_f32_16x16x32_bf16 v[160:163], v[120:123], v[184:187], v[160:163]
	v_mfma_f32_16x16x32_bf16 v[156:159], v[144:147], v[184:187], v[156:159]
	v_mfma_f32_16x16x32_bf16 v[152:155], v[120:123], v[196:199], v[152:155]
	v_mfma_f32_16x16x32_bf16 v[148:151], v[144:147], v[196:199], v[148:151]
	v_mfma_f32_16x16x32_bf16 v[128:131], v[120:123], v[204:207], v[128:131]
	v_mfma_f32_16x16x32_bf16 v[124:127], v[144:147], v[204:207], v[124:127]
	v_mfma_f32_16x16x32_bf16 v[96:99], v[120:123], v[212:215], v[96:99]
	v_mfma_f32_16x16x32_bf16 v[92:95], v[144:147], v[212:215], v[92:95]
	s_setprio 0
	s_barrier
	s_add_i32 s53, s47, s35
	v_lshl_add_u64 v[192:193], s[26:27], 0, v[170:171]
	s_mov_b32 m0, s53
	ds_read_b128 v[164:167], v195 offset:16384
	ds_read_b128 v[184:187], v195 offset:17408
	ds_read_b128 v[188:191], v195 offset:18432
	ds_read_b128 v[196:199], v195 offset:19456
	ds_read_b128 v[200:203], v195 offset:20480
	ds_read_b128 v[204:207], v195 offset:21504
	ds_read_b128 v[208:211], v195 offset:22528
	ds_read_b128 v[212:215], v195 offset:23552
	global_load_lds_dwordx4 v[192:193], off
	s_add_i32 m0, s53, 0x2000
	s_add_u32 s54, s26, 0x80000
	v_lshl_add_u64 v[216:217], s[26:27], 0, v[174:175]
	s_addc_u32 s55, s27, 0
	s_add_i32 s53, s48, s35
	global_load_lds_dwordx4 v[216:217], off
	v_lshl_add_u64 v[2:3], s[54:55], 0, v[170:171]
	s_mov_b32 m0, s53
	v_lshl_add_u64 v[218:219], s[28:29], 0, v[168:169]
	global_load_lds_dwordx4 v[2:3], off
	v_lshl_add_u64 v[2:3], s[54:55], 0, v[174:175]
	s_add_i32 m0, s53, 0x2000
	v_lshl_add_u64 v[220:221], s[28:29], 0, v[172:173]
	global_load_lds_dwordx4 v[2:3], off
	s_mov_b32 m0, s13
	s_nop 0
	global_load_lds_dwordx4 v[218:219], off
	s_mov_b32 m0, s36
	s_nop 0
	global_load_lds_dwordx4 v[220:221], off
	s_cmp_lg_u32 s99, 0
	s_cbranch_scc1 .Lg2604_skip2
	s_waitcnt vmcnt(8)
; #define PG8_STAGE(bufoff, gbase, voff) do { _Pragma("unroll") for (int _i = 0; _i < 2; ++_i) \
;         __builtin_amdgcn_global_load_lds((const unsigned*)((const char*)(gbase) + (voff)[_i]), (PG8_LAS unsigned*)(lds + (bufoff) + ldsw + _i * 8192), 16, 0, 0); } while (0)
; #define PG8_LDA(dst, b, h) do { _Pragma("unroll") for (int m = 0; m < 4; ++m) _Pragma("unroll") for (int k = 0; k < 2; ++k) dst[m][k] = *(const PG8_LAS bf16x8*)(lds + PG8_SA(b, h) + aoff + m * 2048 + k * 1024); } while (0)
; #define PG8_LDB(dst, b, h) do { _Pragma("unroll") for (int n = 0; n < 2; ++n) _Pragma("unroll") for (int k = 0; k < 2; ++k) dst[n][k] = *(const PG8_LAS bf16x8*)(lds + PG8_SB(b, h) + boff + n * 2048 + k * 1024); } while (0)
; #define PG8_MMA(ai, bj, At, Bt) do { __builtin_amdgcn_s_setprio(1); _Pragma("unroll") for (int m = 0; m < 4; ++m) _Pragma("unroll") for (int n = 0; n < 2; ++n) _Pragma("unroll") for (int k = 0; k < 2; ++k) \
;         acc[ai][bj][m][n] = __builtin_amdgcn_mfma_f32_16x16x32_bf16(Bt[n][k], At[m][k], acc[ai][bj][m][n], 0, 0, 0); __builtin_amdgcn_s_setprio(0); } while (0)
; #define PG8_WAIT_V(n) asm volatile("s_waitcnt vmcnt(" #n ")" ::: "memory")
; #define PG8_WAIT_L(n) asm volatile("s_waitcnt lgkmcnt(" #n ")" ::: "memory")
; #define PG8_BAR __builtin_amdgcn_s_barrier()
; #define PG8_SCHED __builtin_amdgcn_sched_barrier(0)
; template <class Epi, class Sched, bool ALIGN_EPI = false, bool SP2 = false>
; __device__ __forceinline__ void gemm_phase(PG8_LAS unsigned char* lds, const Gemm g, const Sched& S, const Epi& E, const int wid) {
;     ...
;             PG8_WAIT_V(8); PG8_WAIT_L(0); PG8_BAR; PG8_MMA(1, 0, At, B0); PG8_MMA(1, 1, At, B1); PG8_BAR; PG8_SCHED;
;             PG8_LDB(B0, 1, 0); PG8_LDB(B1, 1, 1); PG8_SCHED; PG8_LDA(At, 1, 0); PG8_STAGE(PG8_SA(0, 1), a2 + hstep, voffA);
;             PG8_WAIT_V(8); PG8_WAIT_L(0); PG8_BAR; PG8_MMA(0, 0, At, B0); PG8_MMA(0, 1, At, B1); PG8_BAR; PG8_SCHED;
.Lg2604_skip2:
	s_mov_b32 s99, 0
	s_waitcnt lgkmcnt(0)
	s_barrier
	s_setprio 1
	s_waitcnt lgkmcnt(0)
	v_mfma_f32_16x16x32_bf16 v[72:75], v[60:63], v[164:167], v[72:75]
	v_mfma_f32_16x16x32_bf16 v[68:71], v[84:87], v[164:167], v[68:71]
	v_mfma_f32_16x16x32_bf16 v[48:51], v[60:63], v[188:191], v[48:51]
	v_mfma_f32_16x16x32_bf16 v[44:47], v[84:87], v[188:191], v[44:47]
	v_mfma_f32_16x16x32_bf16 v[32:35], v[60:63], v[200:203], v[32:35]
	v_mfma_f32_16x16x32_bf16 v[28:31], v[84:87], v[200:203], v[28:31]
	v_mfma_f32_16x16x32_bf16 v[16:19], v[60:63], v[208:211], v[16:19]
	v_mfma_f32_16x16x32_bf16 v[12:15], v[84:87], v[208:211], v[12:15]
	v_mfma_f32_16x16x32_bf16 v[72:75], v[64:67], v[184:187], v[72:75]
	v_mfma_f32_16x16x32_bf16 v[68:71], v[88:91], v[184:187], v[68:71]
	v_mfma_f32_16x16x32_bf16 v[48:51], v[64:67], v[196:199], v[48:51]
	v_mfma_f32_16x16x32_bf16 v[44:47], v[88:91], v[196:199], v[44:47]
	v_mfma_f32_16x16x32_bf16 v[32:35], v[64:67], v[204:207], v[32:35]
	v_mfma_f32_16x16x32_bf16 v[28:31], v[88:91], v[204:207], v[28:31]
	v_mfma_f32_16x16x32_bf16 v[16:19], v[64:67], v[212:215], v[16:19]
	v_mfma_f32_16x16x32_bf16 v[12:15], v[88:91], v[212:215], v[12:15]
	s_setprio 0
	s_setprio 1
	v_mfma_f32_16x16x32_bf16 v[56:59], v[116:119], v[164:167], v[56:59]
	v_mfma_f32_16x16x32_bf16 v[52:55], v[140:143], v[164:167], v[52:55]
	v_mfma_f32_16x16x32_bf16 v[40:43], v[116:119], v[188:191], v[40:43]
	v_mfma_f32_16x16x32_bf16 v[36:39], v[140:143], v[188:191], v[36:39]
	v_mfma_f32_16x16x32_bf16 v[24:27], v[116:119], v[200:203], v[24:27]
	v_mfma_f32_16x16x32_bf16 v[20:23], v[140:143], v[200:203], v[20:23]
	v_mfma_f32_16x16x32_bf16 v[8:11], v[116:119], v[208:211], v[8:11]
	v_mfma_f32_16x16x32_bf16 v[2:5], v[140:143], v[208:211], v[4:7]
	v_mfma_f32_16x16x32_bf16 v[56:59], v[120:123], v[184:187], v[56:59]
	v_mfma_f32_16x16x32_bf16 v[52:55], v[144:147], v[184:187], v[52:55]
	v_mfma_f32_16x16x32_bf16 v[40:43], v[120:123], v[196:199], v[40:43]
	v_mfma_f32_16x16x32_bf16 v[36:39], v[144:147], v[196:199], v[36:39]
	v_mfma_f32_16x16x32_bf16 v[24:27], v[120:123], v[204:207], v[24:27]
	v_mfma_f32_16x16x32_bf16 v[20:23], v[144:147], v[204:207], v[20:23]
	v_mfma_f32_16x16x32_bf16 v[8:11], v[120:123], v[212:215], v[8:11]
	v_mfma_f32_16x16x32_bf16 v[2:5], v[144:147], v[212:215], v[2:5]
	s_setprio 0
	s_barrier
	s_add_i32 s53, 0, 0x18000
	v_add_u32_e32 v0, s53, v194
	s_add_i32 s54, 0, 0x1c000
	ds_read_b128 v[60:63], v0
	ds_read_b128 v[64:67], v0 offset:1024
	ds_read_b128 v[84:87], v0 offset:2048
	ds_read_b128 v[88:91], v0 offset:3072
	v_add_u32_e32 v0, s54, v194
	ds_read_b128 v[116:119], v0
	ds_read_b128 v[120:123], v0 offset:1024
	ds_read_b128 v[140:143], v0 offset:2048
	ds_read_b128 v[144:147], v0 offset:3072
	s_add_u32 s28, s28, 0x80000
	s_addc_u32 s29, s29, 0
	s_mov_b32 m0, s37
	v_lshl_add_u64 v[6:7], s[28:29], 0, v[168:169]
	ds_read_b128 v[164:167], v195 offset:32768
	ds_read_b128 v[184:187], v195 offset:33792
	ds_read_b128 v[188:191], v195 offset:34816
	ds_read_b128 v[196:199], v195 offset:35840
	ds_read_b128 v[200:203], v195 offset:36864
	ds_read_b128 v[204:207], v195 offset:37888
	ds_read_b128 v[208:211], v195 offset:38912
	ds_read_b128 v[212:215], v195 offset:39936
	global_load_lds_dwordx4 v[6:7], off
	v_lshl_add_u64 v[6:7], s[28:29], 0, v[172:173]
	s_mov_b32 m0, s38
	s_nop 0
	global_load_lds_dwordx4 v[6:7], off
	s_waitcnt vmcnt(8)
	s_waitcnt lgkmcnt(0)
	s_barrier
	s_setprio 1
	s_waitcnt lgkmcnt(0)
	v_mfma_f32_16x16x32_bf16 v[80:83], v[60:63], v[164:167], v[80:83]
	v_mfma_f32_16x16x32_bf16 v[76:79], v[84:87], v[164:167], v[76:79]
	v_mfma_f32_16x16x32_bf16 v[104:107], v[60:63], v[188:191], v[104:107]
	v_mfma_f32_16x16x32_bf16 v[100:103], v[84:87], v[188:191], v[100:103]
	v_mfma_f32_16x16x32_bf16 v[136:139], v[60:63], v[200:203], v[136:139]
	v_mfma_f32_16x16x32_bf16 v[132:135], v[84:87], v[200:203], v[132:135]
	v_mfma_f32_16x16x32_bf16 v[112:115], v[60:63], v[208:211], v[112:115]
	v_mfma_f32_16x16x32_bf16 v[108:111], v[84:87], v[208:211], v[108:111]
	v_mfma_f32_16x16x32_bf16 v[80:83], v[64:67], v[184:187], v[80:83]
	v_mfma_f32_16x16x32_bf16 v[76:79], v[88:91], v[184:187], v[76:79]
	v_mfma_f32_16x16x32_bf16 v[104:107], v[64:67], v[196:199], v[104:107]
	v_mfma_f32_16x16x32_bf16 v[100:103], v[88:91], v[196:199], v[100:103]
	v_mfma_f32_16x16x32_bf16 v[136:139], v[64:67], v[204:207], v[136:139]
	v_mfma_f32_16x16x32_bf16 v[132:135], v[88:91], v[204:207], v[132:135]
	v_mfma_f32_16x16x32_bf16 v[112:115], v[64:67], v[212:215], v[112:115]
	v_mfma_f32_16x16x32_bf16 v[108:111], v[88:91], v[212:215], v[108:111]
	s_setprio 0
	s_setprio 1
	v_mfma_f32_16x16x32_bf16 v[160:163], v[116:119], v[164:167], v[160:163]
	v_mfma_f32_16x16x32_bf16 v[156:159], v[140:143], v[164:167], v[156:159]
	v_mfma_f32_16x16x32_bf16 v[152:155], v[116:119], v[188:191], v[152:155]
	v_mfma_f32_16x16x32_bf16 v[148:151], v[140:143], v[188:191], v[148:151]
	v_mfma_f32_16x16x32_bf16 v[128:131], v[116:119], v[200:203], v[128:131]
	v_mfma_f32_16x16x32_bf16 v[124:127], v[140:143], v[200:203], v[124:127]
	v_mfma_f32_16x16x32_bf16 v[96:99], v[116:119], v[208:211], v[96:99]
	v_mfma_f32_16x16x32_bf16 v[92:95], v[140:143], v[208:211], v[92:95]
	v_mfma_f32_16x16x32_bf16 v[160:163], v[120:123], v[184:187], v[160:163]
	v_mfma_f32_16x16x32_bf16 v[156:159], v[144:147], v[184:187], v[156:159]
	v_mfma_f32_16x16x32_bf16 v[152:155], v[120:123], v[196:199], v[152:155]
	v_mfma_f32_16x16x32_bf16 v[148:151], v[144:147], v[196:199], v[148:151]
	v_mfma_f32_16x16x32_bf16 v[128:131], v[120:123], v[204:207], v[128:131]
	v_mfma_f32_16x16x32_bf16 v[124:127], v[144:147], v[204:207], v[124:127]
	v_mfma_f32_16x16x32_bf16 v[96:99], v[120:123], v[212:215], v[96:99]
	v_mfma_f32_16x16x32_bf16 v[92:95], v[144:147], v[212:215], v[92:95]
	s_setprio 0
	s_barrier
; #define PG8_STAGE(bufoff, gbase, voff) do { _Pragma("unroll") for (int _i = 0; _i < 2; ++_i) \
;         __builtin_amdgcn_global_load_lds((const unsigned*)((const char*)(gbase) + (voff)[_i]), (PG8_LAS unsigned*)(lds + (bufoff) + ldsw + _i * 8192), 16, 0, 0); } while (0)
; #define PG8_LDA(dst, b, h) do { _Pragma("unroll") for (int m = 0; m < 4; ++m) _Pragma("unroll") for (int k = 0; k < 2; ++k) dst[m][k] = *(const PG8_LAS bf16x8*)(lds + PG8_SA(b, h) + aoff + m * 2048 + k * 1024); } while (0)
; #define PG8_MMA(ai, bj, At, Bt) do { __builtin_amdgcn_s_setprio(1); _Pragma("unroll") for (int m = 0; m < 4; ++m) _Pragma("unroll") for (int n = 0; n < 2; ++n) _Pragma("unroll") for (int k = 0; k < 2; ++k) \
;         acc[ai][bj][m][n] = __builtin_amdgcn_mfma_f32_16x16x32_bf16(Bt[n][k], At[m][k], acc[ai][bj][m][n], 0, 0, 0); __builtin_amdgcn_s_setprio(0); } while (0)
; #define PG8_WAIT_V(n) asm volatile("s_waitcnt vmcnt(" #n ")" ::: "memory")
; #define PG8_WAIT_L(n) asm volatile("s_waitcnt lgkmcnt(" #n ")" ::: "memory")
; #define PG8_BAR __builtin_amdgcn_s_barrier()
; #define PG8_SCHED __builtin_amdgcn_sched_barrier(0)
; template <class Epi, class Sched, bool ALIGN_EPI = false, bool SP2 = false>
; __device__ __forceinline__ void gemm_phase(PG8_LAS unsigned char* lds, const Gemm g, const Sched& S, const Epi& E, const int wid) {
;     ...
;             PG8_LDA(At, 1, 1); PG8_STAGE(PG8_SB(1, 0), b3, voffB); PG8_STAGE(PG8_SB(1, 1), b3 + hstep, voffB); PG8_STAGE(PG8_SA(1, 0), a3, voffA);
;             PG8_WAIT_V(8); PG8_WAIT_L(0); PG8_BAR; PG8_MMA(1, 0, At, B0); PG8_MMA(1, 1, At, B1); PG8_BAR; PG8_SCHED;
;     ...
;         if constexpr (ALIGN_EPI) { if (wr == 0) PG8_BAR; }
	s_add_i32 s28, s53, s35
	v_lshl_add_u64 v[6:7], v[192:193], 0, s[10:11]
	s_mov_b32 m0, s28
	ds_read_b128 v[164:167], v195 offset:49152
	ds_read_b128 v[184:187], v195 offset:50176
	ds_read_b128 v[188:191], v195 offset:51200
	ds_read_b128 v[196:199], v195 offset:52224
	ds_read_b128 v[200:203], v195 offset:53248
	ds_read_b128 v[204:207], v195 offset:54272
	ds_read_b128 v[208:211], v195 offset:55296
	ds_read_b128 v[212:215], v195 offset:56320
	global_load_lds_dwordx4 v[6:7], off
	s_add_i32 m0, s28, 0x2000
	s_add_u32 s26, s26, 0x80080
	v_lshl_add_u64 v[6:7], v[216:217], 0, s[10:11]
	s_addc_u32 s27, s27, 0
	s_add_i32 s28, s54, s35
	global_load_lds_dwordx4 v[6:7], off
	v_lshl_add_u64 v[6:7], s[26:27], 0, v[170:171]
	s_mov_b32 m0, s28
	s_nop 0
	global_load_lds_dwordx4 v[6:7], off
	v_lshl_add_u64 v[6:7], s[26:27], 0, v[174:175]
	s_add_i32 m0, s28, 0x2000
	s_nop 0
	global_load_lds_dwordx4 v[6:7], off
	v_lshl_add_u64 v[6:7], v[218:219], 0, s[10:11]
	s_mov_b32 m0, s43
	s_nop 0
	global_load_lds_dwordx4 v[6:7], off
	v_lshl_add_u64 v[6:7], v[220:221], 0, s[10:11]
	s_mov_b32 m0, s44
	s_nop 0
	global_load_lds_dwordx4 v[6:7], off
	s_waitcnt vmcnt(8)
	s_waitcnt lgkmcnt(0)
	s_barrier
	s_setprio 1
	s_waitcnt lgkmcnt(0)
	v_mfma_f32_16x16x32_bf16 v[72:75], v[60:63], v[164:167], v[72:75]
	v_mfma_f32_16x16x32_bf16 v[68:71], v[84:87], v[164:167], v[68:71]
	v_mfma_f32_16x16x32_bf16 v[48:51], v[60:63], v[188:191], v[48:51]
	v_mfma_f32_16x16x32_bf16 v[44:47], v[84:87], v[188:191], v[44:47]
	v_mfma_f32_16x16x32_bf16 v[32:35], v[60:63], v[200:203], v[32:35]
	v_mfma_f32_16x16x32_bf16 v[28:31], v[84:87], v[200:203], v[28:31]
	v_mfma_f32_16x16x32_bf16 v[16:19], v[60:63], v[208:211], v[16:19]
	v_mfma_f32_16x16x32_bf16 v[12:15], v[84:87], v[208:211], v[12:15]
	v_mfma_f32_16x16x32_bf16 v[72:75], v[64:67], v[184:187], v[72:75]
	v_mfma_f32_16x16x32_bf16 v[68:71], v[88:91], v[184:187], v[68:71]
	v_mfma_f32_16x16x32_bf16 v[48:51], v[64:67], v[196:199], v[48:51]
	v_mfma_f32_16x16x32_bf16 v[44:47], v[88:91], v[196:199], v[44:47]
	v_mfma_f32_16x16x32_bf16 v[32:35], v[64:67], v[204:207], v[32:35]
	v_mfma_f32_16x16x32_bf16 v[28:31], v[88:91], v[204:207], v[28:31]
	v_mfma_f32_16x16x32_bf16 v[16:19], v[64:67], v[212:215], v[16:19]
	v_mfma_f32_16x16x32_bf16 v[12:15], v[88:91], v[212:215], v[12:15]
	s_setprio 0
	s_setprio 1
	v_mfma_f32_16x16x32_bf16 v[56:59], v[116:119], v[164:167], v[56:59]
	v_mfma_f32_16x16x32_bf16 v[52:55], v[140:143], v[164:167], v[52:55]
	v_mfma_f32_16x16x32_bf16 v[40:43], v[116:119], v[188:191], v[40:43]
	v_mfma_f32_16x16x32_bf16 v[36:39], v[140:143], v[188:191], v[36:39]
	v_mfma_f32_16x16x32_bf16 v[24:27], v[116:119], v[200:203], v[24:27]
	v_mfma_f32_16x16x32_bf16 v[20:23], v[140:143], v[200:203], v[20:23]
	v_mfma_f32_16x16x32_bf16 v[6:9], v[116:119], v[208:211], v[8:11]
	v_mfma_f32_16x16x32_bf16 v[2:5], v[140:143], v[208:211], v[2:5]
	v_mfma_f32_16x16x32_bf16 v[56:59], v[120:123], v[184:187], v[56:59]
	v_mfma_f32_16x16x32_bf16 v[52:55], v[144:147], v[184:187], v[52:55]
	v_mfma_f32_16x16x32_bf16 v[40:43], v[120:123], v[196:199], v[40:43]
	v_mfma_f32_16x16x32_bf16 v[36:39], v[144:147], v[196:199], v[36:39]
	v_mfma_f32_16x16x32_bf16 v[24:27], v[120:123], v[204:207], v[24:27]
	v_mfma_f32_16x16x32_bf16 v[20:23], v[144:147], v[204:207], v[20:23]
	v_mfma_f32_16x16x32_bf16 v[8:11], v[120:123], v[212:215], v[6:9]
	v_mfma_f32_16x16x32_bf16 v[4:7], v[144:147], v[212:215], v[2:5]
	s_setprio 0
	s_barrier
	s_add_i32 s52, s52, 2
	s_add_u32 s24, s24, 0x100
	s_addc_u32 s25, s25, 0
	s_add_u32 s50, s50, 0x100
	s_addc_u32 s51, s51, 0
	s_cmp_gt_u32 s52, 29
	s_cbranch_scc0 .LBB0_2604
	s_mov_b32 s99, 1
	s_and_b64 vcc, exec, s[14:15]
	s_cbranch_vccz .LBB0_2607
	s_barrier

; #define PG8_STAGE(bufoff, gbase, voff) do { _Pragma("unroll") for (int _i = 0; _i < 2; ++_i) \
;         __builtin_amdgcn_global_load_lds((const unsigned*)((const char*)(gbase) + (voff)[_i]), (PG8_LAS unsigned*)(lds + (bufoff) + ldsw + _i * 8192), 16, 0, 0); } while (0)
; #define PG8_WAIT_V(n) asm volatile("s_waitcnt vmcnt(" #n ")" ::: "memory")
; #define PG8_BAR __builtin_amdgcn_s_barrier()
; template <class Epi, class Sched, bool ALIGN_EPI = false, bool SP2 = false>
; __device__ __forceinline__ void gemm_phase(PG8_LAS unsigned char* lds, const Gemm g, const Sched& S, const Epi& E, const int wid) {
;     ...
;     for (int i = 0; i < 2; ++i) { int R, C; stage_rc(tid * 16 + i * 8192, R, C); const int Rb = Epi::PERM ? ((R & ~31) + perm32(R & 31)) : R;
;         voffA[i] = (unsigned)(R * K + C) * 2u; voffB[i] = (unsigned)(Rb * K + C) * 2u; }
;     const size_t kstep = (size_t)(BK * 2);
;     const size_t hstep = (size_t)HALF * K * 2;
;     const size_t tstep = 2 * hstep;
;     const unsigned ldsw = (unsigned)wid * 1024u;
;     const int aoff = lds_byte(wr * 64 + fr, fq * 8), boff = lds_byte(wc * 32 + fr, fq * 8);
;     ...
;         PG8_STAGE(PG8_SB(0, 0), cB, voffB); PG8_STAGE(PG8_SB(0, 1), cB + hstep, voffB); PG8_STAGE(PG8_SA(0, 0), cA, voffA); PG8_STAGE(PG8_SA(0, 1), cA + hstep, voffA);
;         if (wr == 1) PG8_BAR;
;         PG8_WAIT_V(2); PG8_BAR;
;         PG8_STAGE(PG8_SB(1, 0), cB + kstep, voffB); PG8_STAGE(PG8_SA(1, 0), cA + kstep, voffA); PG8_STAGE(PG8_SB(1, 1), cB + hstep + kstep, voffB);
;         PG8_WAIT_V(6); PG8_BAR;
.LBB0_2707:
	v_readlane_b32 s10, v254, 7
	v_readlane_b32 s11, v254, 8
	s_load_dwordx2 s[12:13], s[10:11], 0x108
	s_mov_b64 s[14:15], 0x80
	v_lshl_add_u64 v[6:7], v[6:7], 0, s[14:15]
	s_waitcnt vmcnt(2)
	s_barrier
	s_waitcnt lgkmcnt(0)
	s_add_u32 s10, s12, 0x22000000
	s_addc_u32 s11, s13, 0
	s_add_u32 s12, s12, 0x40000
	s_addc_u32 s13, s13, 0
	s_lshl_b32 s44, s4, 6
	s_lshl_b32 s1, s4, 13
	v_readlane_b32 s4, v254, 2
	s_lshl_b32 s4, s4, 5
	s_and_b32 s45, s4, 0x60
	s_add_i32 m0, s27, 0x18000
	s_lshr_b32 s16, s45, 3
	global_load_lds_dwordx4 v[6:7], off
	v_lshl_add_u64 v[4:5], v[4:5], 0, s[14:15]
	s_add_i32 m0, s27, 0x1a000
	s_add_i32 s46, s27, 0x8000
	s_add_i32 s47, s27, 0xa000
	global_load_lds_dwordx4 v[4:5], off
	v_lshl_add_u64 v[0:1], v[0:1], 0, s[14:15]
	s_mov_b32 m0, s46
	s_add_u32 s4, s30, 0x100080
	global_load_lds_dwordx4 v[0:1], off
	v_lshl_add_u64 v[0:1], v[2:3], 0, s[14:15]
	s_mov_b32 m0, s47
	s_addc_u32 s5, s31, 0
	global_load_lds_dwordx4 v[0:1], off
	s_add_i32 m0, s27, 0x1c000
	v_lshl_add_u64 v[0:1], s[4:5], 0, v[154:155]
	global_load_lds_dwordx4 v[0:1], off
	v_lshl_add_u64 v[0:1], s[4:5], 0, v[158:159]
	s_add_i32 m0, s27, 0x1e000
	v_lshlrev_b32_e32 v3, 6, v8
	global_load_lds_dwordx4 v[0:1], off
	v_ashrrev_i32_e32 v0, 6, v8
	v_and_b32_e32 v1, 48, v8
	v_lshl_add_u32 v2, v0, 10, s1
	s_movk_i32 s1, 0x3c0
	v_and_or_b32 v1, v3, s1, v1
	v_lshlrev_b32_e32 v3, 2, v8
	v_and_b32_e32 v3, 32, v3
	v_add_lshl_u32 v0, v0, s16, 10
	v_bitop3_b32 v186, v1, v0, v3 bitop3:0xde
	v_lshlrev_b32_e32 v0, 16, v9
	v_and_b32_e32 v0, 0xfffe0000, v0
	v_bitop3_b32 v2, v1, v2, v3 bitop3:0xde
	v_lshl_add_u32 v0, v10, 13, v0
	v_and_b32_e32 v1, 1, v9
	v_lshl_or_b32 v0, v1, 6, v0
	v_lshl_add_u32 v160, v11, 1, v0
	v_lshlrev_b32_e32 v0, 16, v12
	v_and_b32_e32 v0, 0xfffe0000, v0
	v_readlane_b32 s1, v254, 10
	v_lshl_add_u32 v0, v13, 13, v0
	v_and_b32_e32 v1, 1, v12
	s_waitcnt vmcnt(6)
	s_mov_b32 s99, 0
	s_cmpk_lt_u32 s1, 0x100
	v_lshl_or_b32 v0, v1, 6, v0
	s_cselect_b64 s[16:17], -1, 0
	v_readlane_b32 s1, v254, 9
	v_readlane_b32 s4, v254, 0
	v_lshl_add_u32 v162, v14, 1, v0
	s_add_i32 s50, 0, 0x10000
	s_add_i32 s51, 0, 0x14000
	v_mbcnt_lo_u32_b32 v0, -1, 0
	s_ashr_i32 s48, s1, 31
	s_ashr_i32 s49, s4, 31
	v_mov_b32_e32 v161, v155
	v_mov_b32_e32 v163, v155
	v_mov_b64_e32 v[164:165], 0x400
	v_mov_b64_e32 v[166:167], 0x3ff
	v_add_u32_e32 v187, s50, v186
	v_add_u32_e32 v188, s51, v186
	v_add_u32_e32 v189, 0, v2
	v_mbcnt_hi_u32_b32 v190, -1, v0
	s_barrier
	v_readlane_b32 s5, v254, 1
	s_branch .LBB0_2710

; #define PG8_STAGE(bufoff, gbase, voff) do { _Pragma("unroll") for (int _i = 0; _i < 2; ++_i) \
;         __builtin_amdgcn_global_load_lds((const unsigned*)((const char*)(gbase) + (voff)[_i]), (PG8_LAS unsigned*)(lds + (bufoff) + ldsw + _i * 8192), 16, 0, 0); } while (0)
; #define PG8_LDA(dst, b, h) do { _Pragma("unroll") for (int m = 0; m < 4; ++m) _Pragma("unroll") for (int k = 0; k < 2; ++k) dst[m][k] = *(const PG8_LAS bf16x8*)(lds + PG8_SA(b, h) + aoff + m * 2048 + k * 1024); } while (0)
; #define PG8_LDB(dst, b, h) do { _Pragma("unroll") for (int n = 0; n < 2; ++n) _Pragma("unroll") for (int k = 0; k < 2; ++k) dst[n][k] = *(const PG8_LAS bf16x8*)(lds + PG8_SB(b, h) + boff + n * 2048 + k * 1024); } while (0)
; #define PG8_MMA(ai, bj, At, Bt) do { __builtin_amdgcn_s_setprio(1); _Pragma("unroll") for (int m = 0; m < 4; ++m) _Pragma("unroll") for (int n = 0; n < 2; ++n) _Pragma("unroll") for (int k = 0; k < 2; ++k) \
;         acc[ai][bj][m][n] = __builtin_amdgcn_mfma_f32_16x16x32_bf16(Bt[n][k], At[m][k], acc[ai][bj][m][n], 0, 0, 0); __builtin_amdgcn_s_setprio(0); } while (0)
; #define PG8_WAIT_V(n) asm volatile("s_waitcnt vmcnt(" #n ")" ::: "memory")
; #define PG8_WAIT_L(n) asm volatile("s_waitcnt lgkmcnt(" #n ")" ::: "memory")
; #define PG8_BAR __builtin_amdgcn_s_barrier()
; #define PG8_SCHED __builtin_amdgcn_sched_barrier(0)
; template <class Epi, class Sched, bool ALIGN_EPI = false, bool SP2 = false>
; __device__ __forceinline__ void gemm_phase(PG8_LAS unsigned char* lds, const Gemm g, const Sched& S, const Epi& E, const int wid) {
;     ...
;             PG8_LDB(B0, 0, 0); PG8_LDB(B1, 0, 1); PG8_SCHED; PG8_LDA(At, 0, 0); PG8_STAGE(PG8_SA(1, 1), a1 + hstep, voffA);
;             PG8_WAIT_V(8); PG8_WAIT_L(0); PG8_BAR; PG8_MMA(0, 0, At, B0); PG8_MMA(0, 1, At, B1); PG8_BAR; PG8_SCHED;
;             PG8_LDA(At, 0, 1); PG8_STAGE(PG8_SB(0, 0), b2, voffB); PG8_STAGE(PG8_SB(0, 1), b2 + hstep, voffB); PG8_STAGE(PG8_SA(0, 0), a2, voffA);
;             PG8_WAIT_V(8); PG8_WAIT_L(0); PG8_BAR; PG8_MMA(1, 0, At, B0); PG8_MMA(1, 1, At, B1); PG8_BAR; PG8_SCHED;
.LBB0_2717:
	ds_read_b128 v[128:131], v187
	ds_read_b128 v[132:135], v187 offset:1024
	ds_read_b128 v[136:139], v187 offset:2048
	ds_read_b128 v[140:143], v187 offset:3072
	ds_read_b128 v[144:147], v188
	ds_read_b128 v[148:151], v188 offset:1024
	ds_read_b128 v[168:171], v188 offset:2048
	ds_read_b128 v[172:175], v188 offset:3072
	s_add_u32 s30, s28, 0xfff00080
	s_addc_u32 s31, s29, -1
	s_cmp_eq_u32 s55, 60
	s_cselect_b32 s35, s1, s31
	s_cselect_b32 s34, s21, s30
	s_cselect_b32 s31, s19, s54
	s_cselect_b32 s30, s52, s53
	v_lshl_add_u64 v[184:185], s[28:29], 0, v[160:161]
	s_add_i32 m0, s27, 0xc000
	ds_read_b128 v[176:179], v189
	ds_read_b128 v[180:183], v189 offset:1024
	ds_read_b128 v[192:195], v189 offset:2048
	ds_read_b128 v[196:199], v189 offset:3072
	ds_read_b128 v[200:203], v189 offset:4096
	ds_read_b128 v[204:207], v189 offset:5120
	ds_read_b128 v[208:211], v189 offset:6144
	ds_read_b128 v[212:215], v189 offset:7168
	global_load_lds_dwordx4 v[184:185], off
	v_lshl_add_u64 v[184:185], s[28:29], 0, v[162:163]
	s_add_i32 m0, s27, 0xe000
	s_nop 0
	global_load_lds_dwordx4 v[184:185], off
	s_cmp_lg_u32 s99, 0
	s_cbranch_scc1 .Lg2717_skip1
	s_waitcnt vmcnt(8)
.Lg2717_skip1:
	s_waitcnt lgkmcnt(0)
	s_barrier
	s_setprio 1
	s_waitcnt lgkmcnt(0)
	v_mfma_f32_16x16x32_bf16 v[124:127], v[128:131], v[176:179], v[124:127]
	v_mfma_f32_16x16x32_bf16 v[120:123], v[136:139], v[176:179], v[120:123]
	v_mfma_f32_16x16x32_bf16 v[108:111], v[128:131], v[192:195], v[108:111]
	v_mfma_f32_16x16x32_bf16 v[104:107], v[136:139], v[192:195], v[104:107]
	v_mfma_f32_16x16x32_bf16 v[92:95], v[128:131], v[200:203], v[92:95]
	v_mfma_f32_16x16x32_bf16 v[88:91], v[136:139], v[200:203], v[88:91]
	v_mfma_f32_16x16x32_bf16 v[76:79], v[128:131], v[208:211], v[76:79]
	v_mfma_f32_16x16x32_bf16 v[72:75], v[136:139], v[208:211], v[72:75]
	v_mfma_f32_16x16x32_bf16 v[124:127], v[132:135], v[180:183], v[124:127]
	v_mfma_f32_16x16x32_bf16 v[120:123], v[140:143], v[180:183], v[120:123]
	v_mfma_f32_16x16x32_bf16 v[108:111], v[132:135], v[196:199], v[108:111]
	v_mfma_f32_16x16x32_bf16 v[104:107], v[140:143], v[196:199], v[104:107]
	v_mfma_f32_16x16x32_bf16 v[92:95], v[132:135], v[204:207], v[92:95]
	v_mfma_f32_16x16x32_bf16 v[88:91], v[140:143], v[204:207], v[88:91]
	v_mfma_f32_16x16x32_bf16 v[76:79], v[132:135], v[212:215], v[76:79]
	v_mfma_f32_16x16x32_bf16 v[72:75], v[140:143], v[212:215], v[72:75]
	s_setprio 0
	s_setprio 1
	v_mfma_f32_16x16x32_bf16 v[116:119], v[144:147], v[176:179], v[116:119]
	v_mfma_f32_16x16x32_bf16 v[112:115], v[168:171], v[176:179], v[112:115]
	v_mfma_f32_16x16x32_bf16 v[100:103], v[144:147], v[192:195], v[100:103]
	v_mfma_f32_16x16x32_bf16 v[96:99], v[168:171], v[192:195], v[96:99]
	v_mfma_f32_16x16x32_bf16 v[84:87], v[144:147], v[200:203], v[84:87]
	v_mfma_f32_16x16x32_bf16 v[80:83], v[168:171], v[200:203], v[80:83]
	v_mfma_f32_16x16x32_bf16 v[68:71], v[144:147], v[208:211], v[68:71]
	v_mfma_f32_16x16x32_bf16 v[64:67], v[168:171], v[208:211], v[64:67]
	v_mfma_f32_16x16x32_bf16 v[116:119], v[148:151], v[180:183], v[116:119]
	v_mfma_f32_16x16x32_bf16 v[112:115], v[172:175], v[180:183], v[112:115]
	v_mfma_f32_16x16x32_bf16 v[100:103], v[148:151], v[196:199], v[100:103]
	v_mfma_f32_16x16x32_bf16 v[96:99], v[172:175], v[196:199], v[96:99]
	v_mfma_f32_16x16x32_bf16 v[84:87], v[148:151], v[204:207], v[84:87]
	v_mfma_f32_16x16x32_bf16 v[80:83], v[172:175], v[204:207], v[80:83]
	v_mfma_f32_16x16x32_bf16 v[68:71], v[148:151], v[212:215], v[68:71]
	v_mfma_f32_16x16x32_bf16 v[64:67], v[172:175], v[212:215], v[64:67]
	s_setprio 0
	s_barrier
	s_add_i32 s56, s50, s39
	v_lshl_add_u64 v[184:185], s[30:31], 0, v[154:155]
	s_mov_b32 m0, s56
	ds_read_b128 v[176:179], v189 offset:16384
	ds_read_b128 v[180:183], v189 offset:17408
	ds_read_b128 v[192:195], v189 offset:18432
	ds_read_b128 v[196:199], v189 offset:19456
	ds_read_b128 v[200:203], v189 offset:20480
	ds_read_b128 v[204:207], v189 offset:21504
	ds_read_b128 v[208:211], v189 offset:22528
	ds_read_b128 v[212:215], v189 offset:23552
	global_load_lds_dwordx4 v[184:185], off
	s_add_i32 m0, s56, 0x2000
	s_add_u32 s56, s30, 0x100000
	v_lshl_add_u64 v[216:217], s[30:31], 0, v[158:159]
	s_addc_u32 s57, s31, 0
	s_add_i32 s58, s51, s39
	global_load_lds_dwordx4 v[216:217], off
	v_lshl_add_u64 v[218:219], s[56:57], 0, v[154:155]
	s_mov_b32 m0, s58
	v_lshl_add_u64 v[220:221], s[34:35], 0, v[156:157]
	global_load_lds_dwordx4 v[218:219], off
	v_lshl_add_u64 v[218:219], s[56:57], 0, v[158:159]
	s_add_i32 m0, s58, 0x2000
	s_nop 0
	global_load_lds_dwordx4 v[218:219], off
	v_lshl_add_u64 v[218:219], s[34:35], 0, v[152:153]
	s_mov_b32 m0, s27
	s_nop 0
	global_load_lds_dwordx4 v[218:219], off
	s_mov_b32 m0, s40
	s_nop 0
	global_load_lds_dwordx4 v[220:221], off
	s_cmp_lg_u32 s99, 0
	s_cbranch_scc1 .Lg2717_skip2
	s_waitcnt vmcnt(8)
; #define PG8_STAGE(bufoff, gbase, voff) do { _Pragma("unroll") for (int _i = 0; _i < 2; ++_i) \
;         __builtin_amdgcn_global_load_lds((const unsigned*)((const char*)(gbase) + (voff)[_i]), (PG8_LAS unsigned*)(lds + (bufoff) + ldsw + _i * 8192), 16, 0, 0); } while (0)
; #define PG8_LDA(dst, b, h) do { _Pragma("unroll") for (int m = 0; m < 4; ++m) _Pragma("unroll") for (int k = 0; k < 2; ++k) dst[m][k] = *(const PG8_LAS bf16x8*)(lds + PG8_SA(b, h) + aoff + m * 2048 + k * 1024); } while (0)
; #define PG8_LDB(dst, b, h) do { _Pragma("unroll") for (int n = 0; n < 2; ++n) _Pragma("unroll") for (int k = 0; k < 2; ++k) dst[n][k] = *(const PG8_LAS bf16x8*)(lds + PG8_SB(b, h) + boff + n * 2048 + k * 1024); } while (0)
; #define PG8_MMA(ai, bj, At, Bt) do { __builtin_amdgcn_s_setprio(1); _Pragma("unroll") for (int m = 0; m < 4; ++m) _Pragma("unroll") for (int n = 0; n < 2; ++n) _Pragma("unroll") for (int k = 0; k < 2; ++k) \
;         acc[ai][bj][m][n] = __builtin_amdgcn_mfma_f32_16x16x32_bf16(Bt[n][k], At[m][k], acc[ai][bj][m][n], 0, 0, 0); __builtin_amdgcn_s_setprio(0); } while (0)
; #define PG8_WAIT_V(n) asm volatile("s_waitcnt vmcnt(" #n ")" ::: "memory")
; #define PG8_WAIT_L(n) asm volatile("s_waitcnt lgkmcnt(" #n ")" ::: "memory")
; #define PG8_BAR __builtin_amdgcn_s_barrier()
; #define PG8_SCHED __builtin_amdgcn_sched_barrier(0)
; template <class Epi, class Sched, bool ALIGN_EPI = false, bool SP2 = false>
; __device__ __forceinline__ void gemm_phase(PG8_LAS unsigned char* lds, const Gemm g, const Sched& S, const Epi& E, const int wid) {
;     ...
;             PG8_WAIT_V(8); PG8_WAIT_L(0); PG8_BAR; PG8_MMA(1, 0, At, B0); PG8_MMA(1, 1, At, B1); PG8_BAR; PG8_SCHED;
;             PG8_LDB(B0, 1, 0); PG8_LDB(B1, 1, 1); PG8_SCHED; PG8_LDA(At, 1, 0); PG8_STAGE(PG8_SA(0, 1), a2 + hstep, voffA);
;             PG8_WAIT_V(8); PG8_WAIT_L(0); PG8_BAR; PG8_MMA(0, 0, At, B0); PG8_MMA(0, 1, At, B1); PG8_BAR; PG8_SCHED;
.Lg2717_skip2:
	s_mov_b32 s99, 0
	s_waitcnt lgkmcnt(0)
	s_barrier
	s_setprio 1
	s_waitcnt lgkmcnt(0)
	v_mfma_f32_16x16x32_bf16 v[60:63], v[128:131], v[176:179], v[60:63]
	v_mfma_f32_16x16x32_bf16 v[56:59], v[136:139], v[176:179], v[56:59]
	v_mfma_f32_16x16x32_bf16 v[44:47], v[128:131], v[192:195], v[44:47]
	v_mfma_f32_16x16x32_bf16 v[40:43], v[136:139], v[192:195], v[40:43]
	v_mfma_f32_16x16x32_bf16 v[28:31], v[128:131], v[200:203], v[28:31]
	v_mfma_f32_16x16x32_bf16 v[24:27], v[136:139], v[200:203], v[24:27]
	v_mfma_f32_16x16x32_bf16 v[12:15], v[128:131], v[208:211], v[12:15]
	v_mfma_f32_16x16x32_bf16 v[8:11], v[136:139], v[208:211], v[8:11]
	v_mfma_f32_16x16x32_bf16 v[60:63], v[132:135], v[180:183], v[60:63]
	v_mfma_f32_16x16x32_bf16 v[56:59], v[140:143], v[180:183], v[56:59]
	v_mfma_f32_16x16x32_bf16 v[44:47], v[132:135], v[196:199], v[44:47]
	v_mfma_f32_16x16x32_bf16 v[40:43], v[140:143], v[196:199], v[40:43]
	v_mfma_f32_16x16x32_bf16 v[28:31], v[132:135], v[204:207], v[28:31]
	v_mfma_f32_16x16x32_bf16 v[24:27], v[140:143], v[204:207], v[24:27]
	v_mfma_f32_16x16x32_bf16 v[12:15], v[132:135], v[212:215], v[12:15]
	v_mfma_f32_16x16x32_bf16 v[8:11], v[140:143], v[212:215], v[8:11]
	s_setprio 0
	s_setprio 1
	v_mfma_f32_16x16x32_bf16 v[52:55], v[144:147], v[176:179], v[52:55]
	v_mfma_f32_16x16x32_bf16 v[48:51], v[168:171], v[176:179], v[48:51]
	v_mfma_f32_16x16x32_bf16 v[36:39], v[144:147], v[192:195], v[36:39]
	v_mfma_f32_16x16x32_bf16 v[32:35], v[168:171], v[192:195], v[32:35]
	v_mfma_f32_16x16x32_bf16 v[20:23], v[144:147], v[200:203], v[20:23]
	v_mfma_f32_16x16x32_bf16 v[16:19], v[168:171], v[200:203], v[16:19]
	v_mfma_f32_16x16x32_bf16 v[4:7], v[144:147], v[208:211], v[4:7]
	v_mfma_f32_16x16x32_bf16 v[0:3], v[168:171], v[208:211], v[0:3]
	v_mfma_f32_16x16x32_bf16 v[52:55], v[148:151], v[180:183], v[52:55]
	v_mfma_f32_16x16x32_bf16 v[48:51], v[172:175], v[180:183], v[48:51]
	v_mfma_f32_16x16x32_bf16 v[36:39], v[148:151], v[196:199], v[36:39]
	v_mfma_f32_16x16x32_bf16 v[32:35], v[172:175], v[196:199], v[32:35]
	v_mfma_f32_16x16x32_bf16 v[20:23], v[148:151], v[204:207], v[20:23]
	v_mfma_f32_16x16x32_bf16 v[16:19], v[172:175], v[204:207], v[16:19]
	v_mfma_f32_16x16x32_bf16 v[4:7], v[148:151], v[212:215], v[4:7]
	v_mfma_f32_16x16x32_bf16 v[0:3], v[172:175], v[212:215], v[0:3]
	s_setprio 0
	s_barrier
	s_add_i32 s56, 0, 0x18000
	s_add_i32 s57, 0, 0x1c000
	v_add_u32_e32 v140, s56, v186
	v_add_u32_e32 v172, s57, v186
	ds_read_b128 v[128:131], v140
	ds_read_b128 v[132:135], v140 offset:1024
	ds_read_b128 v[136:139], v140 offset:2048
	ds_read_b128 v[140:143], v140 offset:3072
	ds_read_b128 v[144:147], v172
	ds_read_b128 v[148:151], v172 offset:1024
	ds_read_b128 v[168:171], v172 offset:2048
	ds_read_b128 v[172:175], v172 offset:3072
	s_add_u32 s34, s34, 0x100000
	s_addc_u32 s35, s35, 0
	s_mov_b32 m0, s41
	v_lshl_add_u64 v[222:223], s[34:35], 0, v[152:153]
	ds_read_b128 v[176:179], v189 offset:32768
	ds_read_b128 v[180:183], v189 offset:33792
	ds_read_b128 v[192:195], v189 offset:34816
	ds_read_b128 v[196:199], v189 offset:35840
	ds_read_b128 v[200:203], v189 offset:36864
	ds_read_b128 v[204:207], v189 offset:37888
	ds_read_b128 v[208:211], v189 offset:38912
	ds_read_b128 v[212:215], v189 offset:39936
	global_load_lds_dwordx4 v[222:223], off
	v_lshl_add_u64 v[222:223], s[34:35], 0, v[156:157]
	s_mov_b32 m0, s42
	s_nop 0
	global_load_lds_dwordx4 v[222:223], off
	s_waitcnt vmcnt(8)
	s_waitcnt lgkmcnt(0)
	s_barrier
	s_setprio 1
	s_waitcnt lgkmcnt(0)
	v_mfma_f32_16x16x32_bf16 v[124:127], v[128:131], v[176:179], v[124:127]
	v_mfma_f32_16x16x32_bf16 v[120:123], v[136:139], v[176:179], v[120:123]
	v_mfma_f32_16x16x32_bf16 v[108:111], v[128:131], v[192:195], v[108:111]
	v_mfma_f32_16x16x32_bf16 v[104:107], v[136:139], v[192:195], v[104:107]
	v_mfma_f32_16x16x32_bf16 v[92:95], v[128:131], v[200:203], v[92:95]
	v_mfma_f32_16x16x32_bf16 v[88:91], v[136:139], v[200:203], v[88:91]
	v_mfma_f32_16x16x32_bf16 v[76:79], v[128:131], v[208:211], v[76:79]
	v_mfma_f32_16x16x32_bf16 v[72:75], v[136:139], v[208:211], v[72:75]
	v_mfma_f32_16x16x32_bf16 v[124:127], v[132:135], v[180:183], v[124:127]
	v_mfma_f32_16x16x32_bf16 v[120:123], v[140:143], v[180:183], v[120:123]
	v_mfma_f32_16x16x32_bf16 v[108:111], v[132:135], v[196:199], v[108:111]
	v_mfma_f32_16x16x32_bf16 v[104:107], v[140:143], v[196:199], v[104:107]
	v_mfma_f32_16x16x32_bf16 v[92:95], v[132:135], v[204:207], v[92:95]
	v_mfma_f32_16x16x32_bf16 v[88:91], v[140:143], v[204:207], v[88:91]
	v_mfma_f32_16x16x32_bf16 v[76:79], v[132:135], v[212:215], v[76:79]
	v_mfma_f32_16x16x32_bf16 v[72:75], v[140:143], v[212:215], v[72:75]
	s_setprio 0
	s_setprio 1
	v_mfma_f32_16x16x32_bf16 v[116:119], v[144:147], v[176:179], v[116:119]
	v_mfma_f32_16x16x32_bf16 v[112:115], v[168:171], v[176:179], v[112:115]
	v_mfma_f32_16x16x32_bf16 v[100:103], v[144:147], v[192:195], v[100:103]
	v_mfma_f32_16x16x32_bf16 v[96:99], v[168:171], v[192:195], v[96:99]
	v_mfma_f32_16x16x32_bf16 v[84:87], v[144:147], v[200:203], v[84:87]
	v_mfma_f32_16x16x32_bf16 v[80:83], v[168:171], v[200:203], v[80:83]
	v_mfma_f32_16x16x32_bf16 v[68:71], v[144:147], v[208:211], v[68:71]
	v_mfma_f32_16x16x32_bf16 v[64:67], v[168:171], v[208:211], v[64:67]
	v_mfma_f32_16x16x32_bf16 v[116:119], v[148:151], v[180:183], v[116:119]
	v_mfma_f32_16x16x32_bf16 v[112:115], v[172:175], v[180:183], v[112:115]
	v_mfma_f32_16x16x32_bf16 v[100:103], v[148:151], v[196:199], v[100:103]
	v_mfma_f32_16x16x32_bf16 v[96:99], v[172:175], v[196:199], v[96:99]
	v_mfma_f32_16x16x32_bf16 v[84:87], v[148:151], v[204:207], v[84:87]
	v_mfma_f32_16x16x32_bf16 v[80:83], v[172:175], v[204:207], v[80:83]
	v_mfma_f32_16x16x32_bf16 v[68:71], v[148:151], v[212:215], v[68:71]
	v_mfma_f32_16x16x32_bf16 v[64:67], v[172:175], v[212:215], v[64:67]
	s_setprio 0
	s_barrier
; #define PG8_STAGE(bufoff, gbase, voff) do { _Pragma("unroll") for (int _i = 0; _i < 2; ++_i) \
;         __builtin_amdgcn_global_load_lds((const unsigned*)((const char*)(gbase) + (voff)[_i]), (PG8_LAS unsigned*)(lds + (bufoff) + ldsw + _i * 8192), 16, 0, 0); } while (0)
; #define PG8_LDA(dst, b, h) do { _Pragma("unroll") for (int m = 0; m < 4; ++m) _Pragma("unroll") for (int k = 0; k < 2; ++k) dst[m][k] = *(const PG8_LAS bf16x8*)(lds + PG8_SA(b, h) + aoff + m * 2048 + k * 1024); } while (0)
; #define PG8_MMA(ai, bj, At, Bt) do { __builtin_amdgcn_s_setprio(1); _Pragma("unroll") for (int m = 0; m < 4; ++m) _Pragma("unroll") for (int n = 0; n < 2; ++n) _Pragma("unroll") for (int k = 0; k < 2; ++k) \
;         acc[ai][bj][m][n] = __builtin_amdgcn_mfma_f32_16x16x32_bf16(Bt[n][k], At[m][k], acc[ai][bj][m][n], 0, 0, 0); __builtin_amdgcn_s_setprio(0); } while (0)
; #define PG8_WAIT_V(n) asm volatile("s_waitcnt vmcnt(" #n ")" ::: "memory")
; #define PG8_WAIT_L(n) asm volatile("s_waitcnt lgkmcnt(" #n ")" ::: "memory")
; #define PG8_BAR __builtin_amdgcn_s_barrier()
; #define PG8_SCHED __builtin_amdgcn_sched_barrier(0)
; template <class Epi, class Sched, bool ALIGN_EPI = false, bool SP2 = false>
; __device__ __forceinline__ void gemm_phase(PG8_LAS unsigned char* lds, const Gemm g, const Sched& S, const Epi& E, const int wid) {
;     ...
;         for (int t = 0; t < nt; t += 2) {
;             const bool last = (t == nt - 2);
;     ...
;             PG8_LDA(At, 1, 1); PG8_STAGE(PG8_SB(1, 0), b3, voffB); PG8_STAGE(PG8_SB(1, 1), b3 + hstep, voffB); PG8_STAGE(PG8_SA(1, 0), a3, voffA);
;             PG8_WAIT_V(8); PG8_WAIT_L(0); PG8_BAR; PG8_MMA(1, 0, At, B0); PG8_MMA(1, 1, At, B1); PG8_BAR; PG8_SCHED;
	s_add_i32 s34, s56, s39
	v_lshl_add_u64 v[184:185], v[184:185], 0, s[14:15]
	s_mov_b32 m0, s34
	ds_read_b128 v[176:179], v189 offset:49152
	ds_read_b128 v[180:183], v189 offset:50176
	ds_read_b128 v[192:195], v189 offset:51200
	ds_read_b128 v[196:199], v189 offset:52224
	ds_read_b128 v[200:203], v189 offset:53248
	ds_read_b128 v[204:207], v189 offset:54272
	ds_read_b128 v[208:211], v189 offset:55296
	ds_read_b128 v[212:215], v189 offset:56320
	global_load_lds_dwordx4 v[184:185], off
	s_add_i32 m0, s34, 0x2000
	s_add_u32 s30, s30, 0x100080
	v_lshl_add_u64 v[184:185], v[216:217], 0, s[14:15]
	s_addc_u32 s31, s31, 0
	s_add_i32 s34, s57, s39
	global_load_lds_dwordx4 v[184:185], off
	v_lshl_add_u64 v[184:185], s[30:31], 0, v[154:155]
	s_mov_b32 m0, s34
	s_nop 0
	global_load_lds_dwordx4 v[184:185], off
	v_lshl_add_u64 v[184:185], s[30:31], 0, v[158:159]
	s_add_i32 m0, s34, 0x2000
	s_nop 0
	global_load_lds_dwordx4 v[184:185], off
	v_lshl_add_u64 v[184:185], v[218:219], 0, s[14:15]
	s_mov_b32 m0, s46
	s_nop 0
	global_load_lds_dwordx4 v[184:185], off
	v_lshl_add_u64 v[184:185], v[220:221], 0, s[14:15]
	s_mov_b32 m0, s47
	s_nop 0
	global_load_lds_dwordx4 v[184:185], off
	s_waitcnt vmcnt(8)
	s_waitcnt lgkmcnt(0)
	s_barrier
	s_setprio 1
	s_waitcnt lgkmcnt(0)
	v_mfma_f32_16x16x32_bf16 v[60:63], v[128:131], v[176:179], v[60:63]
	v_mfma_f32_16x16x32_bf16 v[56:59], v[136:139], v[176:179], v[56:59]
	v_mfma_f32_16x16x32_bf16 v[44:47], v[128:131], v[192:195], v[44:47]
	v_mfma_f32_16x16x32_bf16 v[40:43], v[136:139], v[192:195], v[40:43]
	v_mfma_f32_16x16x32_bf16 v[28:31], v[128:131], v[200:203], v[28:31]
	v_mfma_f32_16x16x32_bf16 v[24:27], v[136:139], v[200:203], v[24:27]
	v_mfma_f32_16x16x32_bf16 v[12:15], v[128:131], v[208:211], v[12:15]
	v_mfma_f32_16x16x32_bf16 v[8:11], v[136:139], v[208:211], v[8:11]
	v_mfma_f32_16x16x32_bf16 v[60:63], v[132:135], v[180:183], v[60:63]
	v_mfma_f32_16x16x32_bf16 v[56:59], v[140:143], v[180:183], v[56:59]
	v_mfma_f32_16x16x32_bf16 v[44:47], v[132:135], v[196:199], v[44:47]
	v_mfma_f32_16x16x32_bf16 v[40:43], v[140:143], v[196:199], v[40:43]
	v_mfma_f32_16x16x32_bf16 v[28:31], v[132:135], v[204:207], v[28:31]
	v_mfma_f32_16x16x32_bf16 v[24:27], v[140:143], v[204:207], v[24:27]
	v_mfma_f32_16x16x32_bf16 v[12:15], v[132:135], v[212:215], v[12:15]
	v_mfma_f32_16x16x32_bf16 v[8:11], v[140:143], v[212:215], v[8:11]
	s_setprio 0
	s_setprio 1
	v_mfma_f32_16x16x32_bf16 v[52:55], v[144:147], v[176:179], v[52:55]
	v_mfma_f32_16x16x32_bf16 v[48:51], v[168:171], v[176:179], v[48:51]
	v_mfma_f32_16x16x32_bf16 v[36:39], v[144:147], v[192:195], v[36:39]
	v_mfma_f32_16x16x32_bf16 v[32:35], v[168:171], v[192:195], v[32:35]
	v_mfma_f32_16x16x32_bf16 v[20:23], v[144:147], v[200:203], v[20:23]
	v_mfma_f32_16x16x32_bf16 v[16:19], v[168:171], v[200:203], v[16:19]
	v_mfma_f32_16x16x32_bf16 v[4:7], v[144:147], v[208:211], v[4:7]
	v_mfma_f32_16x16x32_bf16 v[0:3], v[168:171], v[208:211], v[0:3]
	v_mfma_f32_16x16x32_bf16 v[52:55], v[148:151], v[180:183], v[52:55]
	v_mfma_f32_16x16x32_bf16 v[48:51], v[172:175], v[180:183], v[48:51]
	v_mfma_f32_16x16x32_bf16 v[36:39], v[148:151], v[196:199], v[36:39]
	v_mfma_f32_16x16x32_bf16 v[32:35], v[172:175], v[196:199], v[32:35]
	v_mfma_f32_16x16x32_bf16 v[20:23], v[148:151], v[204:207], v[20:23]
	v_mfma_f32_16x16x32_bf16 v[16:19], v[172:175], v[204:207], v[16:19]
	v_mfma_f32_16x16x32_bf16 v[4:7], v[148:151], v[212:215], v[4:7]
	v_mfma_f32_16x16x32_bf16 v[0:3], v[172:175], v[212:215], v[0:3]
	s_setprio 0
	s_barrier
	s_add_i32 s55, s55, 2
	s_add_u32 s28, s28, 0x100
	s_addc_u32 s29, s29, 0
	s_add_u32 s53, s53, 0x100
	s_addc_u32 s54, s54, 0
	s_cmp_gt_u32 s55, 61
	s_cbranch_scc0 .LBB0_2717
	s_mov_b32 s99, 1
	s_and_b64 vcc, exec, s[16:17]
	s_cbranch_vccz .LBB0_2720
	s_barrier

; #define PG8_STAGE(bufoff, gbase, voff) do { _Pragma("unroll") for (int _i = 0; _i < 2; ++_i) \
;         __builtin_amdgcn_global_load_lds((const unsigned*)((const char*)(gbase) + (voff)[_i]), (PG8_LAS unsigned*)(lds + (bufoff) + ldsw + _i * 8192), 16, 0, 0); } while (0)
; #define PG8_WAIT_V(n) asm volatile("s_waitcnt vmcnt(" #n ")" ::: "memory")
; #define PG8_BAR __builtin_amdgcn_s_barrier()
; template <class Epi, class Sched, bool ALIGN_EPI = false, bool SP2 = false>
; __device__ __forceinline__ void gemm_phase(PG8_LAS unsigned char* lds, const Gemm g, const Sched& S, const Epi& E, const int wid) {
;     ...
;     for (int i = 0; i < 2; ++i) { int R, C; stage_rc(tid * 16 + i * 8192, R, C); const int Rb = Epi::PERM ? ((R & ~31) + perm32(R & 31)) : R;
;         voffA[i] = (unsigned)(R * K + C) * 2u; voffB[i] = (unsigned)(Rb * K + C) * 2u; }
;     const size_t kstep = (size_t)(BK * 2);
;     const size_t hstep = (size_t)HALF * K * 2;
;     const size_t tstep = 2 * hstep;
;     const unsigned ldsw = (unsigned)wid * 1024u;
;     const int aoff = lds_byte(wr * 64 + fr, fq * 8), boff = lds_byte(wc * 32 + fr, fq * 8);
;     ...
;         PG8_WAIT_V(2); PG8_BAR;
;         PG8_STAGE(PG8_SB(1, 0), cB + kstep, voffB); PG8_STAGE(PG8_SA(1, 0), cA + kstep, voffA); PG8_STAGE(PG8_SB(1, 1), cB + hstep + kstep, voffB);
;         PG8_WAIT_V(6); PG8_BAR;
.LBB0_2800:
	v_readlane_b32 s14, v254, 7
	v_readlane_b32 s15, v254, 8
	s_load_dwordx2 s[14:15], s[14:15], 0x108
	s_mov_b64 s[16:17], 0x80
	v_lshl_add_u64 v[6:7], v[6:7], 0, s[16:17]
	s_waitcnt vmcnt(2)
	s_barrier
	s_waitcnt lgkmcnt(0)
	s_add_u32 s14, s14, 0x2a000000
	s_addc_u32 s15, s15, 0
	s_add_i32 m0, s42, 0x18000
	v_lshl_add_u64 v[4:5], v[4:5], 0, s[16:17]
	global_load_lds_dwordx4 v[6:7], off
	s_add_i32 m0, s42, 0x1a000
	s_add_i32 s47, s42, 0x8000
	s_add_i32 s48, s42, 0xa000
	global_load_lds_dwordx4 v[4:5], off
	v_lshl_add_u64 v[0:1], v[0:1], 0, s[16:17]
	s_mov_b32 m0, s47
	s_add_u32 s18, s6, 0x100080
	global_load_lds_dwordx4 v[0:1], off
	v_lshl_add_u64 v[0:1], v[2:3], 0, s[16:17]
	s_mov_b32 m0, s48
	s_addc_u32 s19, s7, 0
	global_load_lds_dwordx4 v[0:1], off
	s_add_i32 m0, s42, 0x1c000
	v_lshl_add_u64 v[0:1], s[18:19], 0, v[130:131]
	global_load_lds_dwordx4 v[0:1], off
	v_lshl_add_u64 v[0:1], s[18:19], 0, v[134:135]
	s_add_i32 m0, s42, 0x1e000
	s_sext_i32_i16 s1, s4
	global_load_lds_dwordx4 v[0:1], off
	v_and_b32_e32 v0, 15, v8
	v_or_b32_e32 v1, s36, v0
	v_ashrrev_i32_e32 v2, 6, v8
	v_lshlrev_b32_e32 v3, 6, v1
	v_and_b32_e32 v4, 48, v8
	s_movk_i32 s4, 0x3c0
	v_lshlrev_b32_e32 v1, 2, v1
	v_and_or_b32 v3, v3, s4, v4
	v_lshl_add_u32 v5, v2, 10, s39
	v_and_b32_e32 v1, 32, v1
	v_bitop3_b32 v1, v3, v5, v1 bitop3:0xde
	v_lshlrev_b32_e32 v3, 2, v8
	v_lshl_or_b32 v0, v0, 6, v4
	v_add_lshl_u32 v2, v2, s38, 10
	v_and_b32_e32 v3, 32, v3
	v_bitop3_b32 v150, v0, v2, v3 bitop3:0xde
	v_lshlrev_b32_e32 v0, 16, v9
	v_and_b32_e32 v0, 0xfffe0000, v0
	v_lshl_add_u32 v0, v10, 13, v0
	v_and_b32_e32 v2, 1, v9
	v_lshl_or_b32 v0, v2, 6, v0
	v_lshl_add_u32 v136, v11, 1, v0
	v_lshlrev_b32_e32 v0, 16, v12
	v_readlane_b32 s4, v254, 10
	v_and_b32_e32 v0, 0xfffe0000, v0
	s_waitcnt vmcnt(6)
	s_mov_b32 s99, 0
	s_cmpk_lt_u32 s4, 0x100
	v_lshl_add_u32 v0, v13, 13, v0
	v_and_b32_e32 v2, 1, v12
	s_cselect_b64 s[18:19], -1, 0
	v_readlane_b32 s4, v254, 9
	v_lshl_or_b32 v0, v2, 6, v0
	s_add_i32 s50, 0, 0x10000
	s_add_i32 s51, 0, 0x14000
	s_ashr_i32 s49, s4, 31
	v_mov_b32_e32 v137, v131
	v_lshl_add_u32 v138, v14, 1, v0
	v_mov_b32_e32 v139, v131
	v_mov_b64_e32 v[140:141], 0x1000
	v_mov_b64_e32 v[142:143], 0xfff
	v_add_u32_e32 v151, s50, v150
	v_add_u32_e32 v152, s51, v150
	v_add_u32_e32 v153, 0, v1
	v_mov_b32_e32 v154, 0x358637bd
	s_movk_i32 s52, 0x5600
	s_barrier
	s_branch .LBB0_2803

; #define PG8_STAGE(bufoff, gbase, voff) do { _Pragma("unroll") for (int _i = 0; _i < 2; ++_i) \
;         __builtin_amdgcn_global_load_lds((const unsigned*)((const char*)(gbase) + (voff)[_i]), (PG8_LAS unsigned*)(lds + (bufoff) + ldsw + _i * 8192), 16, 0, 0); } while (0)
; #define PG8_LDA(dst, b, h) do { _Pragma("unroll") for (int m = 0; m < 4; ++m) _Pragma("unroll") for (int k = 0; k < 2; ++k) dst[m][k] = *(const PG8_LAS bf16x8*)(lds + PG8_SA(b, h) + aoff + m * 2048 + k * 1024); } while (0)
; #define PG8_LDB(dst, b, h) do { _Pragma("unroll") for (int n = 0; n < 2; ++n) _Pragma("unroll") for (int k = 0; k < 2; ++k) dst[n][k] = *(const PG8_LAS bf16x8*)(lds + PG8_SB(b, h) + boff + n * 2048 + k * 1024); } while (0)
; #define PG8_MMA(ai, bj, At, Bt) do { __builtin_amdgcn_s_setprio(1); _Pragma("unroll") for (int m = 0; m < 4; ++m) _Pragma("unroll") for (int n = 0; n < 2; ++n) _Pragma("unroll") for (int k = 0; k < 2; ++k) \
;         acc[ai][bj][m][n] = __builtin_amdgcn_mfma_f32_16x16x32_bf16(Bt[n][k], At[m][k], acc[ai][bj][m][n], 0, 0, 0); __builtin_amdgcn_s_setprio(0); } while (0)
; #define PG8_WAIT_V(n) asm volatile("s_waitcnt vmcnt(" #n ")" ::: "memory")
; #define PG8_WAIT_L(n) asm volatile("s_waitcnt lgkmcnt(" #n ")" ::: "memory")
; #define PG8_BAR __builtin_amdgcn_s_barrier()
; #define PG8_SCHED __builtin_amdgcn_sched_barrier(0)
; template <class Epi, class Sched, bool ALIGN_EPI = false, bool SP2 = false>
; __device__ __forceinline__ void gemm_phase(PG8_LAS unsigned char* lds, const Gemm g, const Sched& S, const Epi& E, const int wid) {
;     ...
;             const bool last = (t == nt - 2);
;             const char* a1 = cA + (size_t)(t + 1) * kstep;
;             const char* a2 = last ? nA : cA + (size_t)(t + 2) * kstep; const char* b2 = last ? nB : cB + (size_t)(t + 2) * kstep;
;             const char* a3 = a2 + kstep; const char* b3 = b2 + kstep;
;             if (last && has_next) S.a_ready(nxt);
;             if constexpr (SP2) {
;             PG8_LDB(B0, 0, 0); PG8_LDB(B1, 0, 1); PG8_SCHED; PG8_LDA(At, 0, 0); PG8_STAGE(PG8_SA(1, 1), a1 + hstep, voffA);
;             PG8_WAIT_V(8); PG8_WAIT_L(0); PG8_BAR; PG8_MMA(0, 0, At, B0); PG8_MMA(0, 1, At, B1); PG8_BAR; PG8_SCHED;
;             PG8_LDA(At, 0, 1); PG8_STAGE(PG8_SB(0, 0), b2, voffB); PG8_STAGE(PG8_SB(0, 1), b2 + hstep, voffB); PG8_STAGE(PG8_SA(0, 0), a2, voffA);
.LBB0_2810:
	ds_read_b128 v[144:147], v151
	ds_read_b128 v[156:159], v151 offset:1024
	ds_read_b128 v[160:163], v151 offset:2048
	ds_read_b128 v[164:167], v151 offset:3072
	ds_read_b128 v[168:171], v152
	ds_read_b128 v[172:175], v152 offset:1024
	ds_read_b128 v[176:179], v152 offset:2048
	ds_read_b128 v[180:183], v152 offset:3072
	s_add_u32 s6, s2, 0xfff00080
	s_addc_u32 s7, s3, -1
	s_cmp_eq_u32 s57, 60
	s_cselect_b32 s29, s23, s7
	s_cselect_b32 s28, s53, s6
	s_cselect_b32 s7, s21, s56
	s_cselect_b32 s6, s54, s55
	v_lshl_add_u64 v[148:149], s[2:3], 0, v[136:137]
	s_add_i32 m0, s42, 0xc000
	ds_read_b128 v[184:187], v153
	ds_read_b128 v[188:191], v153 offset:1024
	ds_read_b128 v[192:195], v153 offset:2048
	ds_read_b128 v[196:199], v153 offset:3072
	ds_read_b128 v[200:203], v153 offset:4096
	ds_read_b128 v[204:207], v153 offset:5120
	ds_read_b128 v[208:211], v153 offset:6144
	ds_read_b128 v[212:215], v153 offset:7168
	global_load_lds_dwordx4 v[148:149], off
	v_lshl_add_u64 v[148:149], s[2:3], 0, v[138:139]
	s_add_i32 m0, s42, 0xe000
	s_nop 0
	global_load_lds_dwordx4 v[148:149], off
	s_cmp_lg_u32 s99, 0
	s_cbranch_scc1 .Lg2810_skip1
	s_waitcnt vmcnt(8)
.Lg2810_skip1:
	s_waitcnt lgkmcnt(0)
	s_barrier
	s_setprio 1
	s_waitcnt lgkmcnt(0)
	v_mfma_f32_16x16x32_bf16 v[124:127], v[144:147], v[184:187], v[124:127]
	v_mfma_f32_16x16x32_bf16 v[116:119], v[160:163], v[184:187], v[116:119]
	v_mfma_f32_16x16x32_bf16 v[108:111], v[144:147], v[192:195], v[108:111]
	v_mfma_f32_16x16x32_bf16 v[100:103], v[160:163], v[192:195], v[100:103]
	v_mfma_f32_16x16x32_bf16 v[92:95], v[144:147], v[200:203], v[92:95]
	v_mfma_f32_16x16x32_bf16 v[84:87], v[160:163], v[200:203], v[84:87]
	v_mfma_f32_16x16x32_bf16 v[76:79], v[144:147], v[208:211], v[76:79]
	v_mfma_f32_16x16x32_bf16 v[68:71], v[160:163], v[208:211], v[68:71]
	v_mfma_f32_16x16x32_bf16 v[124:127], v[156:159], v[188:191], v[124:127]
	v_mfma_f32_16x16x32_bf16 v[116:119], v[164:167], v[188:191], v[116:119]
	v_mfma_f32_16x16x32_bf16 v[108:111], v[156:159], v[196:199], v[108:111]
	v_mfma_f32_16x16x32_bf16 v[100:103], v[164:167], v[196:199], v[100:103]
	v_mfma_f32_16x16x32_bf16 v[92:95], v[156:159], v[204:207], v[92:95]
	v_mfma_f32_16x16x32_bf16 v[84:87], v[164:167], v[204:207], v[84:87]
	v_mfma_f32_16x16x32_bf16 v[76:79], v[156:159], v[212:215], v[76:79]
	v_mfma_f32_16x16x32_bf16 v[68:71], v[164:167], v[212:215], v[68:71]
	s_setprio 0
	s_setprio 1
	v_mfma_f32_16x16x32_bf16 v[120:123], v[168:171], v[184:187], v[120:123]
	v_mfma_f32_16x16x32_bf16 v[112:115], v[176:179], v[184:187], v[112:115]
	v_mfma_f32_16x16x32_bf16 v[104:107], v[168:171], v[192:195], v[104:107]
	v_mfma_f32_16x16x32_bf16 v[96:99], v[176:179], v[192:195], v[96:99]
	v_mfma_f32_16x16x32_bf16 v[88:91], v[168:171], v[200:203], v[88:91]
	v_mfma_f32_16x16x32_bf16 v[80:83], v[176:179], v[200:203], v[80:83]
	v_mfma_f32_16x16x32_bf16 v[72:75], v[168:171], v[208:211], v[72:75]
	v_mfma_f32_16x16x32_bf16 v[64:67], v[176:179], v[208:211], v[64:67]
	v_mfma_f32_16x16x32_bf16 v[120:123], v[172:175], v[188:191], v[120:123]
	v_mfma_f32_16x16x32_bf16 v[112:115], v[180:183], v[188:191], v[112:115]
	v_mfma_f32_16x16x32_bf16 v[104:107], v[172:175], v[196:199], v[104:107]
	v_mfma_f32_16x16x32_bf16 v[96:99], v[180:183], v[196:199], v[96:99]
	v_mfma_f32_16x16x32_bf16 v[88:91], v[172:175], v[204:207], v[88:91]
	v_mfma_f32_16x16x32_bf16 v[80:83], v[180:183], v[204:207], v[80:83]
	v_mfma_f32_16x16x32_bf16 v[72:75], v[172:175], v[212:215], v[72:75]
	v_mfma_f32_16x16x32_bf16 v[64:67], v[180:183], v[212:215], v[64:67]
	s_setprio 0
	s_barrier
	s_add_i32 s58, s50, s33
	v_lshl_add_u64 v[148:149], s[6:7], 0, v[130:131]
	s_mov_b32 m0, s58
	ds_read_b128 v[184:187], v153 offset:16384
	ds_read_b128 v[188:191], v153 offset:17408
	ds_read_b128 v[192:195], v153 offset:18432
	ds_read_b128 v[196:199], v153 offset:19456
	ds_read_b128 v[200:203], v153 offset:20480
	ds_read_b128 v[204:207], v153 offset:21504
	ds_read_b128 v[208:211], v153 offset:22528
	ds_read_b128 v[212:215], v153 offset:23552
	global_load_lds_dwordx4 v[148:149], off
	s_add_i32 m0, s58, 0x2000
	s_add_u32 s58, s6, 0x100000
	v_lshl_add_u64 v[216:217], s[6:7], 0, v[134:135]
	s_addc_u32 s59, s7, 0
	s_add_i32 s60, s51, s33
	global_load_lds_dwordx4 v[216:217], off
	v_lshl_add_u64 v[218:219], s[58:59], 0, v[130:131]
	s_mov_b32 m0, s60
	v_lshl_add_u64 v[220:221], s[28:29], 0, v[132:133]
	global_load_lds_dwordx4 v[218:219], off
	v_lshl_add_u64 v[218:219], s[58:59], 0, v[134:135]
	s_add_i32 m0, s60, 0x2000
	s_nop 0
	global_load_lds_dwordx4 v[218:219], off
	v_lshl_add_u64 v[218:219], s[28:29], 0, v[128:129]
	s_mov_b32 m0, s42
	s_nop 0
	global_load_lds_dwordx4 v[218:219], off
	s_mov_b32 m0, s43
	s_nop 0
	global_load_lds_dwordx4 v[220:221], off
	s_cmp_lg_u32 s99, 0
	s_cbranch_scc1 .Lg2810_skip2
	s_waitcnt vmcnt(8)
; #define PG8_STAGE(bufoff, gbase, voff) do { _Pragma("unroll") for (int _i = 0; _i < 2; ++_i) \
;         __builtin_amdgcn_global_load_lds((const unsigned*)((const char*)(gbase) + (voff)[_i]), (PG8_LAS unsigned*)(lds + (bufoff) + ldsw + _i * 8192), 16, 0, 0); } while (0)
; #define PG8_LDA(dst, b, h) do { _Pragma("unroll") for (int m = 0; m < 4; ++m) _Pragma("unroll") for (int k = 0; k < 2; ++k) dst[m][k] = *(const PG8_LAS bf16x8*)(lds + PG8_SA(b, h) + aoff + m * 2048 + k * 1024); } while (0)
; #define PG8_LDB(dst, b, h) do { _Pragma("unroll") for (int n = 0; n < 2; ++n) _Pragma("unroll") for (int k = 0; k < 2; ++k) dst[n][k] = *(const PG8_LAS bf16x8*)(lds + PG8_SB(b, h) + boff + n * 2048 + k * 1024); } while (0)
; #define PG8_MMA(ai, bj, At, Bt) do { __builtin_amdgcn_s_setprio(1); _Pragma("unroll") for (int m = 0; m < 4; ++m) _Pragma("unroll") for (int n = 0; n < 2; ++n) _Pragma("unroll") for (int k = 0; k < 2; ++k) \
;         acc[ai][bj][m][n] = __builtin_amdgcn_mfma_f32_16x16x32_bf16(Bt[n][k], At[m][k], acc[ai][bj][m][n], 0, 0, 0); __builtin_amdgcn_s_setprio(0); } while (0)
; #define PG8_WAIT_V(n) asm volatile("s_waitcnt vmcnt(" #n ")" ::: "memory")
; #define PG8_WAIT_L(n) asm volatile("s_waitcnt lgkmcnt(" #n ")" ::: "memory")
; #define PG8_BAR __builtin_amdgcn_s_barrier()
; #define PG8_SCHED __builtin_amdgcn_sched_barrier(0)
; template <class Epi, class Sched, bool ALIGN_EPI = false, bool SP2 = false>
; __device__ __forceinline__ void gemm_phase(PG8_LAS unsigned char* lds, const Gemm g, const Sched& S, const Epi& E, const int wid) {
;     ...
;             PG8_WAIT_V(8); PG8_WAIT_L(0); PG8_BAR; PG8_MMA(1, 0, At, B0); PG8_MMA(1, 1, At, B1); PG8_BAR; PG8_SCHED;
;             PG8_LDB(B0, 1, 0); PG8_LDB(B1, 1, 1); PG8_SCHED; PG8_LDA(At, 1, 0); PG8_STAGE(PG8_SA(0, 1), a2 + hstep, voffA);
;             PG8_WAIT_V(8); PG8_WAIT_L(0); PG8_BAR; PG8_MMA(0, 0, At, B0); PG8_MMA(0, 1, At, B1); PG8_BAR; PG8_SCHED;
.Lg2810_skip2:
	s_mov_b32 s99, 0
	s_waitcnt lgkmcnt(0)
	s_barrier
	s_setprio 1
	s_waitcnt lgkmcnt(0)
	v_mfma_f32_16x16x32_bf16 v[60:63], v[144:147], v[184:187], v[60:63]
	v_mfma_f32_16x16x32_bf16 v[52:55], v[160:163], v[184:187], v[52:55]
	v_mfma_f32_16x16x32_bf16 v[44:47], v[144:147], v[192:195], v[44:47]
	v_mfma_f32_16x16x32_bf16 v[36:39], v[160:163], v[192:195], v[36:39]
	v_mfma_f32_16x16x32_bf16 v[28:31], v[144:147], v[200:203], v[28:31]
	v_mfma_f32_16x16x32_bf16 v[20:23], v[160:163], v[200:203], v[20:23]
	v_mfma_f32_16x16x32_bf16 v[12:15], v[144:147], v[208:211], v[12:15]
	v_mfma_f32_16x16x32_bf16 v[4:7], v[160:163], v[208:211], v[4:7]
	v_mfma_f32_16x16x32_bf16 v[60:63], v[156:159], v[188:191], v[60:63]
	v_mfma_f32_16x16x32_bf16 v[52:55], v[164:167], v[188:191], v[52:55]
	v_mfma_f32_16x16x32_bf16 v[44:47], v[156:159], v[196:199], v[44:47]
	v_mfma_f32_16x16x32_bf16 v[36:39], v[164:167], v[196:199], v[36:39]
	v_mfma_f32_16x16x32_bf16 v[28:31], v[156:159], v[204:207], v[28:31]
	v_mfma_f32_16x16x32_bf16 v[20:23], v[164:167], v[204:207], v[20:23]
	v_mfma_f32_16x16x32_bf16 v[12:15], v[156:159], v[212:215], v[12:15]
	v_mfma_f32_16x16x32_bf16 v[4:7], v[164:167], v[212:215], v[4:7]
	s_setprio 0
	s_setprio 1
	v_mfma_f32_16x16x32_bf16 v[56:59], v[168:171], v[184:187], v[56:59]
	v_mfma_f32_16x16x32_bf16 v[48:51], v[176:179], v[184:187], v[48:51]
	v_mfma_f32_16x16x32_bf16 v[40:43], v[168:171], v[192:195], v[40:43]
	v_mfma_f32_16x16x32_bf16 v[32:35], v[176:179], v[192:195], v[32:35]
	v_mfma_f32_16x16x32_bf16 v[24:27], v[168:171], v[200:203], v[24:27]
	v_mfma_f32_16x16x32_bf16 v[16:19], v[176:179], v[200:203], v[16:19]
	v_mfma_f32_16x16x32_bf16 v[8:11], v[168:171], v[208:211], v[8:11]
	v_mfma_f32_16x16x32_bf16 v[0:3], v[176:179], v[208:211], v[0:3]
	v_mfma_f32_16x16x32_bf16 v[56:59], v[172:175], v[188:191], v[56:59]
	v_mfma_f32_16x16x32_bf16 v[48:51], v[180:183], v[188:191], v[48:51]
	v_mfma_f32_16x16x32_bf16 v[40:43], v[172:175], v[196:199], v[40:43]
	v_mfma_f32_16x16x32_bf16 v[32:35], v[180:183], v[196:199], v[32:35]
	v_mfma_f32_16x16x32_bf16 v[24:27], v[172:175], v[204:207], v[24:27]
	v_mfma_f32_16x16x32_bf16 v[16:19], v[180:183], v[204:207], v[16:19]
	v_mfma_f32_16x16x32_bf16 v[8:11], v[172:175], v[212:215], v[8:11]
	v_mfma_f32_16x16x32_bf16 v[0:3], v[180:183], v[212:215], v[0:3]
	s_setprio 0
	s_barrier
	s_add_i32 s58, 0, 0x18000
	v_add_u32_e32 v155, s58, v150
	s_add_i32 s59, 0, 0x1c000
	ds_read_b128 v[144:147], v155
	ds_read_b128 v[156:159], v155 offset:1024
	ds_read_b128 v[160:163], v155 offset:2048
	ds_read_b128 v[164:167], v155 offset:3072
	v_add_u32_e32 v155, s59, v150
	ds_read_b128 v[168:171], v155
	ds_read_b128 v[172:175], v155 offset:1024
	ds_read_b128 v[176:179], v155 offset:2048
	ds_read_b128 v[180:183], v155 offset:3072
	s_add_u32 s28, s28, 0x100000
	s_addc_u32 s29, s29, 0
	s_mov_b32 m0, s44
	v_lshl_add_u64 v[222:223], s[28:29], 0, v[128:129]
	ds_read_b128 v[184:187], v153 offset:32768
	ds_read_b128 v[188:191], v153 offset:33792
	ds_read_b128 v[192:195], v153 offset:34816
	ds_read_b128 v[196:199], v153 offset:35840
	ds_read_b128 v[200:203], v153 offset:36864
	ds_read_b128 v[204:207], v153 offset:37888
	ds_read_b128 v[208:211], v153 offset:38912
	ds_read_b128 v[212:215], v153 offset:39936
	global_load_lds_dwordx4 v[222:223], off
	v_lshl_add_u64 v[222:223], s[28:29], 0, v[132:133]
	s_mov_b32 m0, s45
	s_nop 0
	global_load_lds_dwordx4 v[222:223], off
	s_waitcnt vmcnt(8)
	s_waitcnt lgkmcnt(0)
	s_barrier
	s_setprio 1
	s_waitcnt lgkmcnt(0)
	v_mfma_f32_16x16x32_bf16 v[124:127], v[144:147], v[184:187], v[124:127]
	v_mfma_f32_16x16x32_bf16 v[116:119], v[160:163], v[184:187], v[116:119]
	v_mfma_f32_16x16x32_bf16 v[108:111], v[144:147], v[192:195], v[108:111]
	v_mfma_f32_16x16x32_bf16 v[100:103], v[160:163], v[192:195], v[100:103]
	v_mfma_f32_16x16x32_bf16 v[92:95], v[144:147], v[200:203], v[92:95]
	v_mfma_f32_16x16x32_bf16 v[84:87], v[160:163], v[200:203], v[84:87]
	v_mfma_f32_16x16x32_bf16 v[76:79], v[144:147], v[208:211], v[76:79]
	v_mfma_f32_16x16x32_bf16 v[68:71], v[160:163], v[208:211], v[68:71]
	v_mfma_f32_16x16x32_bf16 v[124:127], v[156:159], v[188:191], v[124:127]
	v_mfma_f32_16x16x32_bf16 v[116:119], v[164:167], v[188:191], v[116:119]
	v_mfma_f32_16x16x32_bf16 v[108:111], v[156:159], v[196:199], v[108:111]
	v_mfma_f32_16x16x32_bf16 v[100:103], v[164:167], v[196:199], v[100:103]
	v_mfma_f32_16x16x32_bf16 v[92:95], v[156:159], v[204:207], v[92:95]
	v_mfma_f32_16x16x32_bf16 v[84:87], v[164:167], v[204:207], v[84:87]
	v_mfma_f32_16x16x32_bf16 v[76:79], v[156:159], v[212:215], v[76:79]
	v_mfma_f32_16x16x32_bf16 v[68:71], v[164:167], v[212:215], v[68:71]
	s_setprio 0
	s_setprio 1
	v_mfma_f32_16x16x32_bf16 v[120:123], v[168:171], v[184:187], v[120:123]
	v_mfma_f32_16x16x32_bf16 v[112:115], v[176:179], v[184:187], v[112:115]
	v_mfma_f32_16x16x32_bf16 v[104:107], v[168:171], v[192:195], v[104:107]
	v_mfma_f32_16x16x32_bf16 v[96:99], v[176:179], v[192:195], v[96:99]
	v_mfma_f32_16x16x32_bf16 v[88:91], v[168:171], v[200:203], v[88:91]
	v_mfma_f32_16x16x32_bf16 v[80:83], v[176:179], v[200:203], v[80:83]
	v_mfma_f32_16x16x32_bf16 v[72:75], v[168:171], v[208:211], v[72:75]
	v_mfma_f32_16x16x32_bf16 v[64:67], v[176:179], v[208:211], v[64:67]
	v_mfma_f32_16x16x32_bf16 v[120:123], v[172:175], v[188:191], v[120:123]
	v_mfma_f32_16x16x32_bf16 v[112:115], v[180:183], v[188:191], v[112:115]
	v_mfma_f32_16x16x32_bf16 v[104:107], v[172:175], v[196:199], v[104:107]
	v_mfma_f32_16x16x32_bf16 v[96:99], v[180:183], v[196:199], v[96:99]
	v_mfma_f32_16x16x32_bf16 v[88:91], v[172:175], v[204:207], v[88:91]
	v_mfma_f32_16x16x32_bf16 v[80:83], v[180:183], v[204:207], v[80:83]
	v_mfma_f32_16x16x32_bf16 v[72:75], v[172:175], v[212:215], v[72:75]
	v_mfma_f32_16x16x32_bf16 v[64:67], v[180:183], v[212:215], v[64:67]
	s_setprio 0
	s_barrier
; #define PG8_STAGE(bufoff, gbase, voff) do { _Pragma("unroll") for (int _i = 0; _i < 2; ++_i) \
;         __builtin_amdgcn_global_load_lds((const unsigned*)((const char*)(gbase) + (voff)[_i]), (PG8_LAS unsigned*)(lds + (bufoff) + ldsw + _i * 8192), 16, 0, 0); } while (0)
; #define PG8_LDA(dst, b, h) do { _Pragma("unroll") for (int m = 0; m < 4; ++m) _Pragma("unroll") for (int k = 0; k < 2; ++k) dst[m][k] = *(const PG8_LAS bf16x8*)(lds + PG8_SA(b, h) + aoff + m * 2048 + k * 1024); } while (0)
; #define PG8_MMA(ai, bj, At, Bt) do { __builtin_amdgcn_s_setprio(1); _Pragma("unroll") for (int m = 0; m < 4; ++m) _Pragma("unroll") for (int n = 0; n < 2; ++n) _Pragma("unroll") for (int k = 0; k < 2; ++k) \
;         acc[ai][bj][m][n] = __builtin_amdgcn_mfma_f32_16x16x32_bf16(Bt[n][k], At[m][k], acc[ai][bj][m][n], 0, 0, 0); __builtin_amdgcn_s_setprio(0); } while (0)
; #define PG8_WAIT_V(n) asm volatile("s_waitcnt vmcnt(" #n ")" ::: "memory")
; #define PG8_WAIT_L(n) asm volatile("s_waitcnt lgkmcnt(" #n ")" ::: "memory")
; #define PG8_BAR __builtin_amdgcn_s_barrier()
; #define PG8_SCHED __builtin_amdgcn_sched_barrier(0)
; template <class Epi, class Sched, bool ALIGN_EPI = false, bool SP2 = false>
; __device__ __forceinline__ void gemm_phase(PG8_LAS unsigned char* lds, const Gemm g, const Sched& S, const Epi& E, const int wid) {
;     ...
;         for (int t = 0; t < nt; t += 2) {
;             const bool last = (t == nt - 2);
;     ...
;             PG8_LDA(At, 1, 1); PG8_STAGE(PG8_SB(1, 0), b3, voffB); PG8_STAGE(PG8_SB(1, 1), b3 + hstep, voffB); PG8_STAGE(PG8_SA(1, 0), a3, voffA);
;             PG8_WAIT_V(8); PG8_WAIT_L(0); PG8_BAR; PG8_MMA(1, 0, At, B0); PG8_MMA(1, 1, At, B1); PG8_BAR; PG8_SCHED;
	s_add_i32 s28, s58, s33
	v_lshl_add_u64 v[148:149], v[148:149], 0, s[16:17]
	s_mov_b32 m0, s28
	ds_read_b128 v[184:187], v153 offset:49152
	ds_read_b128 v[188:191], v153 offset:50176
	ds_read_b128 v[192:195], v153 offset:51200
	ds_read_b128 v[196:199], v153 offset:52224
	ds_read_b128 v[200:203], v153 offset:53248
	ds_read_b128 v[204:207], v153 offset:54272
	ds_read_b128 v[208:211], v153 offset:55296
	ds_read_b128 v[212:215], v153 offset:56320
	global_load_lds_dwordx4 v[148:149], off
	s_add_i32 m0, s28, 0x2000
	s_add_u32 s6, s6, 0x100080
	v_lshl_add_u64 v[148:149], v[216:217], 0, s[16:17]
	s_addc_u32 s7, s7, 0
	s_add_i32 s28, s59, s33
	global_load_lds_dwordx4 v[148:149], off
	v_lshl_add_u64 v[148:149], s[6:7], 0, v[130:131]
	s_mov_b32 m0, s28
	s_nop 0
	global_load_lds_dwordx4 v[148:149], off
	v_lshl_add_u64 v[148:149], s[6:7], 0, v[134:135]
	s_add_i32 m0, s28, 0x2000
	s_nop 0
	global_load_lds_dwordx4 v[148:149], off
	v_lshl_add_u64 v[148:149], v[218:219], 0, s[16:17]
	s_mov_b32 m0, s47
	s_nop 0
	global_load_lds_dwordx4 v[148:149], off
	v_lshl_add_u64 v[148:149], v[220:221], 0, s[16:17]
	s_mov_b32 m0, s48
	s_nop 0
	global_load_lds_dwordx4 v[148:149], off
	s_waitcnt vmcnt(8)
	s_waitcnt lgkmcnt(0)
	s_barrier
	s_setprio 1
	s_waitcnt lgkmcnt(0)
	v_mfma_f32_16x16x32_bf16 v[60:63], v[144:147], v[184:187], v[60:63]
	v_mfma_f32_16x16x32_bf16 v[52:55], v[160:163], v[184:187], v[52:55]
	v_mfma_f32_16x16x32_bf16 v[44:47], v[144:147], v[192:195], v[44:47]
	v_mfma_f32_16x16x32_bf16 v[36:39], v[160:163], v[192:195], v[36:39]
	v_mfma_f32_16x16x32_bf16 v[28:31], v[144:147], v[200:203], v[28:31]
	v_mfma_f32_16x16x32_bf16 v[20:23], v[160:163], v[200:203], v[20:23]
	v_mfma_f32_16x16x32_bf16 v[12:15], v[144:147], v[208:211], v[12:15]
	v_mfma_f32_16x16x32_bf16 v[4:7], v[160:163], v[208:211], v[4:7]
	v_mfma_f32_16x16x32_bf16 v[60:63], v[156:159], v[188:191], v[60:63]
	v_mfma_f32_16x16x32_bf16 v[52:55], v[164:167], v[188:191], v[52:55]
	v_mfma_f32_16x16x32_bf16 v[44:47], v[156:159], v[196:199], v[44:47]
	v_mfma_f32_16x16x32_bf16 v[36:39], v[164:167], v[196:199], v[36:39]
	v_mfma_f32_16x16x32_bf16 v[28:31], v[156:159], v[204:207], v[28:31]
	v_mfma_f32_16x16x32_bf16 v[20:23], v[164:167], v[204:207], v[20:23]
	v_mfma_f32_16x16x32_bf16 v[12:15], v[156:159], v[212:215], v[12:15]
	v_mfma_f32_16x16x32_bf16 v[4:7], v[164:167], v[212:215], v[4:7]
	s_setprio 0
	s_setprio 1
	v_mfma_f32_16x16x32_bf16 v[56:59], v[168:171], v[184:187], v[56:59]
	v_mfma_f32_16x16x32_bf16 v[48:51], v[176:179], v[184:187], v[48:51]
	v_mfma_f32_16x16x32_bf16 v[40:43], v[168:171], v[192:195], v[40:43]
	v_mfma_f32_16x16x32_bf16 v[32:35], v[176:179], v[192:195], v[32:35]
	v_mfma_f32_16x16x32_bf16 v[24:27], v[168:171], v[200:203], v[24:27]
	v_mfma_f32_16x16x32_bf16 v[16:19], v[176:179], v[200:203], v[16:19]
	v_mfma_f32_16x16x32_bf16 v[8:11], v[168:171], v[208:211], v[8:11]
	v_mfma_f32_16x16x32_bf16 v[0:3], v[176:179], v[208:211], v[0:3]
	v_mfma_f32_16x16x32_bf16 v[56:59], v[172:175], v[188:191], v[56:59]
	v_mfma_f32_16x16x32_bf16 v[48:51], v[180:183], v[188:191], v[48:51]
	v_mfma_f32_16x16x32_bf16 v[40:43], v[172:175], v[196:199], v[40:43]
	v_mfma_f32_16x16x32_bf16 v[32:35], v[180:183], v[196:199], v[32:35]
	v_mfma_f32_16x16x32_bf16 v[24:27], v[172:175], v[204:207], v[24:27]
	v_mfma_f32_16x16x32_bf16 v[16:19], v[180:183], v[204:207], v[16:19]
	v_mfma_f32_16x16x32_bf16 v[8:11], v[172:175], v[212:215], v[8:11]
	v_mfma_f32_16x16x32_bf16 v[0:3], v[180:183], v[212:215], v[0:3]
	s_setprio 0
	s_barrier
	s_add_i32 s57, s57, 2
	s_add_u32 s2, s2, 0x100
	s_addc_u32 s3, s3, 0
	s_add_u32 s55, s55, 0x100
	s_addc_u32 s56, s56, 0
	s_cmp_gt_u32 s57, 61
	s_cbranch_scc0 .LBB0_2810
	s_mov_b32 s99, 1
	s_and_b64 vcc, exec, s[18:19]
	s_cbranch_vccz .LBB0_2813
	s_barrier

; #define PG8_STAGE(bufoff, gbase, voff) do { _Pragma("unroll") for (int _i = 0; _i < 2; ++_i) \
;         __builtin_amdgcn_global_load_lds((const unsigned*)((const char*)(gbase) + (voff)[_i]), (PG8_LAS unsigned*)(lds + (bufoff) + ldsw + _i * 8192), 16, 0, 0); } while (0)
; #define PG8_WAIT_V(n) asm volatile("s_waitcnt vmcnt(" #n ")" ::: "memory")
; #define PG8_BAR __builtin_amdgcn_s_barrier()
; template <class Epi, class Sched, bool ALIGN_EPI = false, bool SP2 = false>
; __device__ __forceinline__ void gemm_phase(PG8_LAS unsigned char* lds, const Gemm g, const Sched& S, const Epi& E, const int wid) {
;     ...
;     for (int i = 0; i < 2; ++i) { int R, C; stage_rc(tid * 16 + i * 8192, R, C); const int Rb = Epi::PERM ? ((R & ~31) + perm32(R & 31)) : R;
;         voffA[i] = (unsigned)(R * K + C) * 2u; voffB[i] = (unsigned)(Rb * K + C) * 2u; }
;     const size_t kstep = (size_t)(BK * 2);
;     const size_t hstep = (size_t)HALF * K * 2;
;     const size_t tstep = 2 * hstep;
;     const unsigned ldsw = (unsigned)wid * 1024u;
;     const int aoff = lds_byte(wr * 64 + fr, fq * 8), boff = lds_byte(wc * 32 + fr, fq * 8);
;     ...
;         PG8_WAIT_V(2); PG8_BAR;
;         PG8_STAGE(PG8_SB(1, 0), cB + kstep, voffB); PG8_STAGE(PG8_SA(1, 0), cA + kstep, voffA); PG8_STAGE(PG8_SB(1, 1), cB + hstep + kstep, voffB);
;         PG8_WAIT_V(6); PG8_BAR;
.LBB0_2820:
	v_readlane_b32 s14, v254, 7
	v_readlane_b32 s15, v254, 8
	s_load_dwordx2 s[14:15], s[14:15], 0x108
	s_mov_b64 s[16:17], 0x80
	v_lshl_add_u64 v[6:7], v[6:7], 0, s[16:17]
	s_waitcnt vmcnt(2)
	s_barrier
	s_waitcnt lgkmcnt(0)
	s_add_u32 s14, s14, 0x2a004000
	s_addc_u32 s15, s15, 0
	s_add_i32 m0, s43, 0x18000
	v_lshl_add_u64 v[4:5], v[4:5], 0, s[16:17]
	global_load_lds_dwordx4 v[6:7], off
	s_add_i32 m0, s43, 0x1a000
	s_add_i32 s48, s43, 0x8000
	s_add_i32 s49, s43, 0xa000
	global_load_lds_dwordx4 v[4:5], off
	v_lshl_add_u64 v[0:1], v[0:1], 0, s[16:17]
	s_mov_b32 m0, s48
	s_add_u32 s18, s6, 0x100080
	global_load_lds_dwordx4 v[0:1], off
	v_lshl_add_u64 v[0:1], v[2:3], 0, s[16:17]
	s_mov_b32 m0, s49
	s_addc_u32 s19, s7, 0
	global_load_lds_dwordx4 v[0:1], off
	s_add_i32 m0, s43, 0x1c000
	v_lshl_add_u64 v[0:1], s[18:19], 0, v[132:133]
	global_load_lds_dwordx4 v[0:1], off
	v_lshl_add_u64 v[0:1], s[18:19], 0, v[128:129]
	s_add_i32 m0, s43, 0x1e000
	s_sext_i32_i16 s1, s4
	global_load_lds_dwordx4 v[0:1], off
	v_and_b32_e32 v0, 15, v10
	v_or_b32_e32 v1, s36, v0
	v_ashrrev_i32_e32 v2, 6, v10
	v_lshlrev_b32_e32 v3, 6, v1
	v_and_b32_e32 v4, 48, v10
	s_movk_i32 s4, 0x3c0
	v_lshlrev_b32_e32 v1, 2, v1
	v_and_or_b32 v3, v3, s4, v4
	v_lshl_add_u32 v5, v2, 10, s39
	v_and_b32_e32 v1, 32, v1
	v_bitop3_b32 v1, v3, v5, v1 bitop3:0xde
	v_lshlrev_b32_e32 v3, 2, v10
	v_lshl_or_b32 v0, v0, 6, v4
	v_add_lshl_u32 v2, v2, s38, 10
	v_and_b32_e32 v3, 32, v3
	v_bitop3_b32 v150, v0, v2, v3 bitop3:0xde
	v_lshlrev_b32_e32 v0, 16, v12
	v_and_b32_e32 v0, 0xfffe0000, v0
	v_lshl_add_u32 v0, v13, 13, v0
	v_and_b32_e32 v2, 1, v12
	v_lshl_or_b32 v0, v2, 6, v0
	v_lshl_add_u32 v136, v14, 1, v0
	v_lshlrev_b32_e32 v0, 16, v8
	v_readlane_b32 s4, v254, 10
	v_and_b32_e32 v0, 0xfffe0000, v0
	s_waitcnt vmcnt(6)
	s_mov_b32 s99, 0
	s_cmpk_lt_u32 s4, 0x100
	v_lshl_add_u32 v0, v9, 13, v0
	v_and_b32_e32 v2, 1, v8
	s_cselect_b64 s[18:19], -1, 0
	v_readlane_b32 s4, v254, 9
	v_lshl_or_b32 v0, v2, 6, v0
	s_add_i32 s51, 0, 0x10000
	s_add_i32 s52, 0, 0x14000
	s_ashr_i32 s50, s4, 31
	v_mov_b32_e32 v137, v133
	v_lshl_add_u32 v138, v11, 1, v0
	v_mov_b32_e32 v139, v133
	v_mov_b64_e32 v[140:141], 0x580
	v_mov_b64_e32 v[142:143], 0x57f
	v_add_u32_e32 v151, s51, v150
	v_add_u32_e32 v152, s52, v150
	v_add_u32_e32 v153, 0, v1
	v_mov_b32_e32 v154, 0x358637bd
	s_movk_i32 s53, 0x5600
	s_barrier
	s_branch .LBB0_2823

; #define PG8_STAGE(bufoff, gbase, voff) do { _Pragma("unroll") for (int _i = 0; _i < 2; ++_i) \
;         __builtin_amdgcn_global_load_lds((const unsigned*)((const char*)(gbase) + (voff)[_i]), (PG8_LAS unsigned*)(lds + (bufoff) + ldsw + _i * 8192), 16, 0, 0); } while (0)
; #define PG8_LDA(dst, b, h) do { _Pragma("unroll") for (int m = 0; m < 4; ++m) _Pragma("unroll") for (int k = 0; k < 2; ++k) dst[m][k] = *(const PG8_LAS bf16x8*)(lds + PG8_SA(b, h) + aoff + m * 2048 + k * 1024); } while (0)
; #define PG8_LDB(dst, b, h) do { _Pragma("unroll") for (int n = 0; n < 2; ++n) _Pragma("unroll") for (int k = 0; k < 2; ++k) dst[n][k] = *(const PG8_LAS bf16x8*)(lds + PG8_SB(b, h) + boff + n * 2048 + k * 1024); } while (0)
; #define PG8_MMA(ai, bj, At, Bt) do { __builtin_amdgcn_s_setprio(1); _Pragma("unroll") for (int m = 0; m < 4; ++m) _Pragma("unroll") for (int n = 0; n < 2; ++n) _Pragma("unroll") for (int k = 0; k < 2; ++k) \
;         acc[ai][bj][m][n] = __builtin_amdgcn_mfma_f32_16x16x32_bf16(Bt[n][k], At[m][k], acc[ai][bj][m][n], 0, 0, 0); __builtin_amdgcn_s_setprio(0); } while (0)
; #define PG8_WAIT_V(n) asm volatile("s_waitcnt vmcnt(" #n ")" ::: "memory")
; #define PG8_WAIT_L(n) asm volatile("s_waitcnt lgkmcnt(" #n ")" ::: "memory")
; #define PG8_BAR __builtin_amdgcn_s_barrier()
; #define PG8_SCHED __builtin_amdgcn_sched_barrier(0)
; template <class Epi, class Sched, bool ALIGN_EPI = false, bool SP2 = false>
; __device__ __forceinline__ void gemm_phase(PG8_LAS unsigned char* lds, const Gemm g, const Sched& S, const Epi& E, const int wid) {
;     ...
;             const bool last = (t == nt - 2);
;             const char* a1 = cA + (size_t)(t + 1) * kstep;
;             const char* a2 = last ? nA : cA + (size_t)(t + 2) * kstep; const char* b2 = last ? nB : cB + (size_t)(t + 2) * kstep;
;             const char* a3 = a2 + kstep; const char* b3 = b2 + kstep;
;             if (last && has_next) S.a_ready(nxt);
;             if constexpr (SP2) {
;             PG8_LDB(B0, 0, 0); PG8_LDB(B1, 0, 1); PG8_SCHED; PG8_LDA(At, 0, 0); PG8_STAGE(PG8_SA(1, 1), a1 + hstep, voffA);
;             PG8_WAIT_V(8); PG8_WAIT_L(0); PG8_BAR; PG8_MMA(0, 0, At, B0); PG8_MMA(0, 1, At, B1); PG8_BAR; PG8_SCHED;
;             PG8_LDA(At, 0, 1); PG8_STAGE(PG8_SB(0, 0), b2, voffB); PG8_STAGE(PG8_SB(0, 1), b2 + hstep, voffB); PG8_STAGE(PG8_SA(0, 0), a2, voffA);
.LBB0_2826:
	ds_read_b128 v[144:147], v151
	ds_read_b128 v[156:159], v151 offset:1024
	ds_read_b128 v[160:163], v151 offset:2048
	ds_read_b128 v[164:167], v151 offset:3072
	ds_read_b128 v[168:171], v152
	ds_read_b128 v[172:175], v152 offset:1024
	ds_read_b128 v[176:179], v152 offset:2048
	ds_read_b128 v[180:183], v152 offset:3072
	s_add_u32 s6, s2, 0xfff00080
	s_addc_u32 s7, s3, -1
	s_cmp_eq_u32 s58, 60
	s_cselect_b32 s29, s23, s7
	s_cselect_b32 s28, s54, s6
	s_cselect_b32 s7, s21, s57
	s_cselect_b32 s6, s55, s56
	v_lshl_add_u64 v[148:149], s[2:3], 0, v[136:137]
	s_add_i32 m0, s43, 0xc000
	ds_read_b128 v[184:187], v153
	ds_read_b128 v[188:191], v153 offset:1024
	ds_read_b128 v[192:195], v153 offset:2048
	ds_read_b128 v[196:199], v153 offset:3072
	ds_read_b128 v[200:203], v153 offset:4096
	ds_read_b128 v[204:207], v153 offset:5120
	ds_read_b128 v[208:211], v153 offset:6144
	ds_read_b128 v[212:215], v153 offset:7168
	global_load_lds_dwordx4 v[148:149], off
	v_lshl_add_u64 v[148:149], s[2:3], 0, v[138:139]
	s_add_i32 m0, s43, 0xe000
	s_nop 0
	global_load_lds_dwordx4 v[148:149], off
	s_cmp_lg_u32 s99, 0
	s_cbranch_scc1 .Lg2826_skip1
	s_waitcnt vmcnt(8)
.Lg2826_skip1:
	s_waitcnt lgkmcnt(0)
	s_barrier
	s_setprio 1
	s_waitcnt lgkmcnt(0)
	v_mfma_f32_16x16x32_bf16 v[124:127], v[144:147], v[184:187], v[124:127]
	v_mfma_f32_16x16x32_bf16 v[116:119], v[160:163], v[184:187], v[116:119]
	v_mfma_f32_16x16x32_bf16 v[108:111], v[144:147], v[192:195], v[108:111]
	v_mfma_f32_16x16x32_bf16 v[100:103], v[160:163], v[192:195], v[100:103]
	v_mfma_f32_16x16x32_bf16 v[92:95], v[144:147], v[200:203], v[92:95]
	v_mfma_f32_16x16x32_bf16 v[84:87], v[160:163], v[200:203], v[84:87]
	v_mfma_f32_16x16x32_bf16 v[76:79], v[144:147], v[208:211], v[76:79]
	v_mfma_f32_16x16x32_bf16 v[68:71], v[160:163], v[208:211], v[68:71]
	v_mfma_f32_16x16x32_bf16 v[124:127], v[156:159], v[188:191], v[124:127]
	v_mfma_f32_16x16x32_bf16 v[116:119], v[164:167], v[188:191], v[116:119]
	v_mfma_f32_16x16x32_bf16 v[108:111], v[156:159], v[196:199], v[108:111]
	v_mfma_f32_16x16x32_bf16 v[100:103], v[164:167], v[196:199], v[100:103]
	v_mfma_f32_16x16x32_bf16 v[92:95], v[156:159], v[204:207], v[92:95]
	v_mfma_f32_16x16x32_bf16 v[84:87], v[164:167], v[204:207], v[84:87]
	v_mfma_f32_16x16x32_bf16 v[76:79], v[156:159], v[212:215], v[76:79]
	v_mfma_f32_16x16x32_bf16 v[68:71], v[164:167], v[212:215], v[68:71]
	s_setprio 0
	s_setprio 1
	v_mfma_f32_16x16x32_bf16 v[120:123], v[168:171], v[184:187], v[120:123]
	v_mfma_f32_16x16x32_bf16 v[112:115], v[176:179], v[184:187], v[112:115]
	v_mfma_f32_16x16x32_bf16 v[104:107], v[168:171], v[192:195], v[104:107]
	v_mfma_f32_16x16x32_bf16 v[96:99], v[176:179], v[192:195], v[96:99]
	v_mfma_f32_16x16x32_bf16 v[88:91], v[168:171], v[200:203], v[88:91]
	v_mfma_f32_16x16x32_bf16 v[80:83], v[176:179], v[200:203], v[80:83]
	v_mfma_f32_16x16x32_bf16 v[72:75], v[168:171], v[208:211], v[72:75]
	v_mfma_f32_16x16x32_bf16 v[64:67], v[176:179], v[208:211], v[64:67]
	v_mfma_f32_16x16x32_bf16 v[120:123], v[172:175], v[188:191], v[120:123]
	v_mfma_f32_16x16x32_bf16 v[112:115], v[180:183], v[188:191], v[112:115]
	v_mfma_f32_16x16x32_bf16 v[104:107], v[172:175], v[196:199], v[104:107]
	v_mfma_f32_16x16x32_bf16 v[96:99], v[180:183], v[196:199], v[96:99]
	v_mfma_f32_16x16x32_bf16 v[88:91], v[172:175], v[204:207], v[88:91]
	v_mfma_f32_16x16x32_bf16 v[80:83], v[180:183], v[204:207], v[80:83]
	v_mfma_f32_16x16x32_bf16 v[72:75], v[172:175], v[212:215], v[72:75]
	v_mfma_f32_16x16x32_bf16 v[64:67], v[180:183], v[212:215], v[64:67]
	s_setprio 0
	s_barrier
	s_add_i32 s59, s51, s33
	v_lshl_add_u64 v[148:149], s[6:7], 0, v[132:133]
	s_mov_b32 m0, s59
	ds_read_b128 v[184:187], v153 offset:16384
	ds_read_b128 v[188:191], v153 offset:17408
	ds_read_b128 v[192:195], v153 offset:18432
	ds_read_b128 v[196:199], v153 offset:19456
	ds_read_b128 v[200:203], v153 offset:20480
	ds_read_b128 v[204:207], v153 offset:21504
	ds_read_b128 v[208:211], v153 offset:22528
	ds_read_b128 v[212:215], v153 offset:23552
	global_load_lds_dwordx4 v[148:149], off
	s_add_i32 m0, s59, 0x2000
	s_add_u32 s60, s6, 0x100000
	v_lshl_add_u64 v[216:217], s[6:7], 0, v[128:129]
	s_addc_u32 s61, s7, 0
	s_add_i32 s59, s52, s33
	global_load_lds_dwordx4 v[216:217], off
	v_lshl_add_u64 v[218:219], s[60:61], 0, v[132:133]
	s_mov_b32 m0, s59
	v_lshl_add_u64 v[220:221], s[28:29], 0, v[130:131]
	global_load_lds_dwordx4 v[218:219], off
	v_lshl_add_u64 v[218:219], s[60:61], 0, v[128:129]
	s_add_i32 m0, s59, 0x2000
	s_nop 0
	global_load_lds_dwordx4 v[218:219], off
	v_lshl_add_u64 v[218:219], s[28:29], 0, v[134:135]
	s_mov_b32 m0, s43
	s_nop 0
	global_load_lds_dwordx4 v[218:219], off
	s_mov_b32 m0, s44
	s_nop 0
	global_load_lds_dwordx4 v[220:221], off
	s_cmp_lg_u32 s99, 0
	s_cbranch_scc1 .Lg2826_skip2
	s_waitcnt vmcnt(8)
; #define PG8_STAGE(bufoff, gbase, voff) do { _Pragma("unroll") for (int _i = 0; _i < 2; ++_i) \
;         __builtin_amdgcn_global_load_lds((const unsigned*)((const char*)(gbase) + (voff)[_i]), (PG8_LAS unsigned*)(lds + (bufoff) + ldsw + _i * 8192), 16, 0, 0); } while (0)
; #define PG8_LDA(dst, b, h) do { _Pragma("unroll") for (int m = 0; m < 4; ++m) _Pragma("unroll") for (int k = 0; k < 2; ++k) dst[m][k] = *(const PG8_LAS bf16x8*)(lds + PG8_SA(b, h) + aoff + m * 2048 + k * 1024); } while (0)
; #define PG8_LDB(dst, b, h) do { _Pragma("unroll") for (int n = 0; n < 2; ++n) _Pragma("unroll") for (int k = 0; k < 2; ++k) dst[n][k] = *(const PG8_LAS bf16x8*)(lds + PG8_SB(b, h) + boff + n * 2048 + k * 1024); } while (0)
; #define PG8_MMA(ai, bj, At, Bt) do { __builtin_amdgcn_s_setprio(1); _Pragma("unroll") for (int m = 0; m < 4; ++m) _Pragma("unroll") for (int n = 0; n < 2; ++n) _Pragma("unroll") for (int k = 0; k < 2; ++k) \
;         acc[ai][bj][m][n] = __builtin_amdgcn_mfma_f32_16x16x32_bf16(Bt[n][k], At[m][k], acc[ai][bj][m][n], 0, 0, 0); __builtin_amdgcn_s_setprio(0); } while (0)
; #define PG8_WAIT_V(n) asm volatile("s_waitcnt vmcnt(" #n ")" ::: "memory")
; #define PG8_WAIT_L(n) asm volatile("s_waitcnt lgkmcnt(" #n ")" ::: "memory")
; #define PG8_BAR __builtin_amdgcn_s_barrier()
; #define PG8_SCHED __builtin_amdgcn_sched_barrier(0)
; template <class Epi, class Sched, bool ALIGN_EPI = false, bool SP2 = false>
; __device__ __forceinline__ void gemm_phase(PG8_LAS unsigned char* lds, const Gemm g, const Sched& S, const Epi& E, const int wid) {
;     ...
;             PG8_WAIT_V(8); PG8_WAIT_L(0); PG8_BAR; PG8_MMA(1, 0, At, B0); PG8_MMA(1, 1, At, B1); PG8_BAR; PG8_SCHED;
;             PG8_LDB(B0, 1, 0); PG8_LDB(B1, 1, 1); PG8_SCHED; PG8_LDA(At, 1, 0); PG8_STAGE(PG8_SA(0, 1), a2 + hstep, voffA);
;             PG8_WAIT_V(8); PG8_WAIT_L(0); PG8_BAR; PG8_MMA(0, 0, At, B0); PG8_MMA(0, 1, At, B1); PG8_BAR; PG8_SCHED;
.Lg2826_skip2:
	s_mov_b32 s99, 0
	s_waitcnt lgkmcnt(0)
	s_barrier
	s_setprio 1
	s_waitcnt lgkmcnt(0)
	v_mfma_f32_16x16x32_bf16 v[60:63], v[144:147], v[184:187], v[60:63]
	v_mfma_f32_16x16x32_bf16 v[52:55], v[160:163], v[184:187], v[52:55]
	v_mfma_f32_16x16x32_bf16 v[44:47], v[144:147], v[192:195], v[44:47]
	v_mfma_f32_16x16x32_bf16 v[36:39], v[160:163], v[192:195], v[36:39]
	v_mfma_f32_16x16x32_bf16 v[28:31], v[144:147], v[200:203], v[28:31]
	v_mfma_f32_16x16x32_bf16 v[20:23], v[160:163], v[200:203], v[20:23]
	v_mfma_f32_16x16x32_bf16 v[12:15], v[144:147], v[208:211], v[12:15]
	v_mfma_f32_16x16x32_bf16 v[4:7], v[160:163], v[208:211], v[4:7]
	v_mfma_f32_16x16x32_bf16 v[60:63], v[156:159], v[188:191], v[60:63]
	v_mfma_f32_16x16x32_bf16 v[52:55], v[164:167], v[188:191], v[52:55]
	v_mfma_f32_16x16x32_bf16 v[44:47], v[156:159], v[196:199], v[44:47]
	v_mfma_f32_16x16x32_bf16 v[36:39], v[164:167], v[196:199], v[36:39]
	v_mfma_f32_16x16x32_bf16 v[28:31], v[156:159], v[204:207], v[28:31]
	v_mfma_f32_16x16x32_bf16 v[20:23], v[164:167], v[204:207], v[20:23]
	v_mfma_f32_16x16x32_bf16 v[12:15], v[156:159], v[212:215], v[12:15]
	v_mfma_f32_16x16x32_bf16 v[4:7], v[164:167], v[212:215], v[4:7]
	s_setprio 0
	s_setprio 1
	v_mfma_f32_16x16x32_bf16 v[56:59], v[168:171], v[184:187], v[56:59]
	v_mfma_f32_16x16x32_bf16 v[48:51], v[176:179], v[184:187], v[48:51]
	v_mfma_f32_16x16x32_bf16 v[40:43], v[168:171], v[192:195], v[40:43]
	v_mfma_f32_16x16x32_bf16 v[32:35], v[176:179], v[192:195], v[32:35]
	v_mfma_f32_16x16x32_bf16 v[24:27], v[168:171], v[200:203], v[24:27]
	v_mfma_f32_16x16x32_bf16 v[16:19], v[176:179], v[200:203], v[16:19]
	v_mfma_f32_16x16x32_bf16 v[8:11], v[168:171], v[208:211], v[8:11]
	v_mfma_f32_16x16x32_bf16 v[0:3], v[176:179], v[208:211], v[0:3]
	v_mfma_f32_16x16x32_bf16 v[56:59], v[172:175], v[188:191], v[56:59]
	v_mfma_f32_16x16x32_bf16 v[48:51], v[180:183], v[188:191], v[48:51]
	v_mfma_f32_16x16x32_bf16 v[40:43], v[172:175], v[196:199], v[40:43]
	v_mfma_f32_16x16x32_bf16 v[32:35], v[180:183], v[196:199], v[32:35]
	v_mfma_f32_16x16x32_bf16 v[24:27], v[172:175], v[204:207], v[24:27]
	v_mfma_f32_16x16x32_bf16 v[16:19], v[180:183], v[204:207], v[16:19]
	v_mfma_f32_16x16x32_bf16 v[8:11], v[172:175], v[212:215], v[8:11]
	v_mfma_f32_16x16x32_bf16 v[0:3], v[180:183], v[212:215], v[0:3]
	s_setprio 0
	s_barrier
	s_add_i32 s59, 0, 0x18000
	v_add_u32_e32 v155, s59, v150
	s_add_i32 s60, 0, 0x1c000
	ds_read_b128 v[144:147], v155
	ds_read_b128 v[156:159], v155 offset:1024
	ds_read_b128 v[160:163], v155 offset:2048
	ds_read_b128 v[164:167], v155 offset:3072
	v_add_u32_e32 v155, s60, v150
	ds_read_b128 v[168:171], v155
	ds_read_b128 v[172:175], v155 offset:1024
	ds_read_b128 v[176:179], v155 offset:2048
	ds_read_b128 v[180:183], v155 offset:3072
	s_add_u32 s28, s28, 0x100000
	s_addc_u32 s29, s29, 0
	s_mov_b32 m0, s45
	v_lshl_add_u64 v[222:223], s[28:29], 0, v[134:135]
	ds_read_b128 v[184:187], v153 offset:32768
	ds_read_b128 v[188:191], v153 offset:33792
	ds_read_b128 v[192:195], v153 offset:34816
	ds_read_b128 v[196:199], v153 offset:35840
	ds_read_b128 v[200:203], v153 offset:36864
	ds_read_b128 v[204:207], v153 offset:37888
	ds_read_b128 v[208:211], v153 offset:38912
	ds_read_b128 v[212:215], v153 offset:39936
	global_load_lds_dwordx4 v[222:223], off
	v_lshl_add_u64 v[222:223], s[28:29], 0, v[130:131]
	s_mov_b32 m0, s46
	s_nop 0
	global_load_lds_dwordx4 v[222:223], off
	s_waitcnt vmcnt(8)
	s_waitcnt lgkmcnt(0)
	s_barrier
	s_setprio 1
	s_waitcnt lgkmcnt(0)
	v_mfma_f32_16x16x32_bf16 v[124:127], v[144:147], v[184:187], v[124:127]
	v_mfma_f32_16x16x32_bf16 v[116:119], v[160:163], v[184:187], v[116:119]
	v_mfma_f32_16x16x32_bf16 v[108:111], v[144:147], v[192:195], v[108:111]
	v_mfma_f32_16x16x32_bf16 v[100:103], v[160:163], v[192:195], v[100:103]
	v_mfma_f32_16x16x32_bf16 v[92:95], v[144:147], v[200:203], v[92:95]
	v_mfma_f32_16x16x32_bf16 v[84:87], v[160:163], v[200:203], v[84:87]
	v_mfma_f32_16x16x32_bf16 v[76:79], v[144:147], v[208:211], v[76:79]
	v_mfma_f32_16x16x32_bf16 v[68:71], v[160:163], v[208:211], v[68:71]
	v_mfma_f32_16x16x32_bf16 v[124:127], v[156:159], v[188:191], v[124:127]
	v_mfma_f32_16x16x32_bf16 v[116:119], v[164:167], v[188:191], v[116:119]
	v_mfma_f32_16x16x32_bf16 v[108:111], v[156:159], v[196:199], v[108:111]
	v_mfma_f32_16x16x32_bf16 v[100:103], v[164:167], v[196:199], v[100:103]
	v_mfma_f32_16x16x32_bf16 v[92:95], v[156:159], v[204:207], v[92:95]
	v_mfma_f32_16x16x32_bf16 v[84:87], v[164:167], v[204:207], v[84:87]
	v_mfma_f32_16x16x32_bf16 v[76:79], v[156:159], v[212:215], v[76:79]
	v_mfma_f32_16x16x32_bf16 v[68:71], v[164:167], v[212:215], v[68:71]
	s_setprio 0
	s_setprio 1
	v_mfma_f32_16x16x32_bf16 v[120:123], v[168:171], v[184:187], v[120:123]
	v_mfma_f32_16x16x32_bf16 v[112:115], v[176:179], v[184:187], v[112:115]
	v_mfma_f32_16x16x32_bf16 v[104:107], v[168:171], v[192:195], v[104:107]
	v_mfma_f32_16x16x32_bf16 v[96:99], v[176:179], v[192:195], v[96:99]
	v_mfma_f32_16x16x32_bf16 v[88:91], v[168:171], v[200:203], v[88:91]
	v_mfma_f32_16x16x32_bf16 v[80:83], v[176:179], v[200:203], v[80:83]
	v_mfma_f32_16x16x32_bf16 v[72:75], v[168:171], v[208:211], v[72:75]
	v_mfma_f32_16x16x32_bf16 v[64:67], v[176:179], v[208:211], v[64:67]
	v_mfma_f32_16x16x32_bf16 v[120:123], v[172:175], v[188:191], v[120:123]
	v_mfma_f32_16x16x32_bf16 v[112:115], v[180:183], v[188:191], v[112:115]
	v_mfma_f32_16x16x32_bf16 v[104:107], v[172:175], v[196:199], v[104:107]
	v_mfma_f32_16x16x32_bf16 v[96:99], v[180:183], v[196:199], v[96:99]
	v_mfma_f32_16x16x32_bf16 v[88:91], v[172:175], v[204:207], v[88:91]
	v_mfma_f32_16x16x32_bf16 v[80:83], v[180:183], v[204:207], v[80:83]
	v_mfma_f32_16x16x32_bf16 v[72:75], v[172:175], v[212:215], v[72:75]
	v_mfma_f32_16x16x32_bf16 v[64:67], v[180:183], v[212:215], v[64:67]
	s_setprio 0
	s_barrier
; #define PG8_STAGE(bufoff, gbase, voff) do { _Pragma("unroll") for (int _i = 0; _i < 2; ++_i) \
;         __builtin_amdgcn_global_load_lds((const unsigned*)((const char*)(gbase) + (voff)[_i]), (PG8_LAS unsigned*)(lds + (bufoff) + ldsw + _i * 8192), 16, 0, 0); } while (0)
; #define PG8_LDA(dst, b, h) do { _Pragma("unroll") for (int m = 0; m < 4; ++m) _Pragma("unroll") for (int k = 0; k < 2; ++k) dst[m][k] = *(const PG8_LAS bf16x8*)(lds + PG8_SA(b, h) + aoff + m * 2048 + k * 1024); } while (0)
; #define PG8_MMA(ai, bj, At, Bt) do { __builtin_amdgcn_s_setprio(1); _Pragma("unroll") for (int m = 0; m < 4; ++m) _Pragma("unroll") for (int n = 0; n < 2; ++n) _Pragma("unroll") for (int k = 0; k < 2; ++k) \
;         acc[ai][bj][m][n] = __builtin_amdgcn_mfma_f32_16x16x32_bf16(Bt[n][k], At[m][k], acc[ai][bj][m][n], 0, 0, 0); __builtin_amdgcn_s_setprio(0); } while (0)
; #define PG8_WAIT_V(n) asm volatile("s_waitcnt vmcnt(" #n ")" ::: "memory")
; #define PG8_WAIT_L(n) asm volatile("s_waitcnt lgkmcnt(" #n ")" ::: "memory")
; #define PG8_BAR __builtin_amdgcn_s_barrier()
; #define PG8_SCHED __builtin_amdgcn_sched_barrier(0)
; template <class Epi, class Sched, bool ALIGN_EPI = false, bool SP2 = false>
; __device__ __forceinline__ void gemm_phase(PG8_LAS unsigned char* lds, const Gemm g, const Sched& S, const Epi& E, const int wid) {
;     ...
;         for (int t = 0; t < nt; t += 2) {
;             const bool last = (t == nt - 2);
;     ...
;             PG8_LDA(At, 1, 1); PG8_STAGE(PG8_SB(1, 0), b3, voffB); PG8_STAGE(PG8_SB(1, 1), b3 + hstep, voffB); PG8_STAGE(PG8_SA(1, 0), a3, voffA);
;             PG8_WAIT_V(8); PG8_WAIT_L(0); PG8_BAR; PG8_MMA(1, 0, At, B0); PG8_MMA(1, 1, At, B1); PG8_BAR; PG8_SCHED;
	s_add_i32 s28, s59, s33
	v_lshl_add_u64 v[148:149], v[148:149], 0, s[16:17]
	s_mov_b32 m0, s28
	ds_read_b128 v[184:187], v153 offset:49152
	ds_read_b128 v[188:191], v153 offset:50176
	ds_read_b128 v[192:195], v153 offset:51200
	ds_read_b128 v[196:199], v153 offset:52224
	ds_read_b128 v[200:203], v153 offset:53248
	ds_read_b128 v[204:207], v153 offset:54272
	ds_read_b128 v[208:211], v153 offset:55296
	ds_read_b128 v[212:215], v153 offset:56320
	global_load_lds_dwordx4 v[148:149], off
	s_add_i32 m0, s28, 0x2000
	s_add_u32 s6, s6, 0x100080
	v_lshl_add_u64 v[148:149], v[216:217], 0, s[16:17]
	s_addc_u32 s7, s7, 0
	s_add_i32 s28, s60, s33
	global_load_lds_dwordx4 v[148:149], off
	v_lshl_add_u64 v[148:149], s[6:7], 0, v[132:133]
	s_mov_b32 m0, s28
	s_nop 0
	global_load_lds_dwordx4 v[148:149], off
	v_lshl_add_u64 v[148:149], s[6:7], 0, v[128:129]
	s_add_i32 m0, s28, 0x2000
	s_nop 0
	global_load_lds_dwordx4 v[148:149], off
	v_lshl_add_u64 v[148:149], v[218:219], 0, s[16:17]
	s_mov_b32 m0, s48
	s_nop 0
	global_load_lds_dwordx4 v[148:149], off
	v_lshl_add_u64 v[148:149], v[220:221], 0, s[16:17]
	s_mov_b32 m0, s49
	s_nop 0
	global_load_lds_dwordx4 v[148:149], off
	s_waitcnt vmcnt(8)
	s_waitcnt lgkmcnt(0)
	s_barrier
	s_setprio 1
	s_waitcnt lgkmcnt(0)
	v_mfma_f32_16x16x32_bf16 v[60:63], v[144:147], v[184:187], v[60:63]
	v_mfma_f32_16x16x32_bf16 v[52:55], v[160:163], v[184:187], v[52:55]
	v_mfma_f32_16x16x32_bf16 v[44:47], v[144:147], v[192:195], v[44:47]
	v_mfma_f32_16x16x32_bf16 v[36:39], v[160:163], v[192:195], v[36:39]
	v_mfma_f32_16x16x32_bf16 v[28:31], v[144:147], v[200:203], v[28:31]
	v_mfma_f32_16x16x32_bf16 v[20:23], v[160:163], v[200:203], v[20:23]
	v_mfma_f32_16x16x32_bf16 v[12:15], v[144:147], v[208:211], v[12:15]
	v_mfma_f32_16x16x32_bf16 v[4:7], v[160:163], v[208:211], v[4:7]
	v_mfma_f32_16x16x32_bf16 v[60:63], v[156:159], v[188:191], v[60:63]
	v_mfma_f32_16x16x32_bf16 v[52:55], v[164:167], v[188:191], v[52:55]
	v_mfma_f32_16x16x32_bf16 v[44:47], v[156:159], v[196:199], v[44:47]
	v_mfma_f32_16x16x32_bf16 v[36:39], v[164:167], v[196:199], v[36:39]
	v_mfma_f32_16x16x32_bf16 v[28:31], v[156:159], v[204:207], v[28:31]
	v_mfma_f32_16x16x32_bf16 v[20:23], v[164:167], v[204:207], v[20:23]
	v_mfma_f32_16x16x32_bf16 v[12:15], v[156:159], v[212:215], v[12:15]
	v_mfma_f32_16x16x32_bf16 v[4:7], v[164:167], v[212:215], v[4:7]
	s_setprio 0
	s_setprio 1
	v_mfma_f32_16x16x32_bf16 v[56:59], v[168:171], v[184:187], v[56:59]
	v_mfma_f32_16x16x32_bf16 v[48:51], v[176:179], v[184:187], v[48:51]
	v_mfma_f32_16x16x32_bf16 v[40:43], v[168:171], v[192:195], v[40:43]
	v_mfma_f32_16x16x32_bf16 v[32:35], v[176:179], v[192:195], v[32:35]
	v_mfma_f32_16x16x32_bf16 v[24:27], v[168:171], v[200:203], v[24:27]
	v_mfma_f32_16x16x32_bf16 v[16:19], v[176:179], v[200:203], v[16:19]
	v_mfma_f32_16x16x32_bf16 v[8:11], v[168:171], v[208:211], v[8:11]
	v_mfma_f32_16x16x32_bf16 v[0:3], v[176:179], v[208:211], v[0:3]
	v_mfma_f32_16x16x32_bf16 v[56:59], v[172:175], v[188:191], v[56:59]
	v_mfma_f32_16x16x32_bf16 v[48:51], v[180:183], v[188:191], v[48:51]
	v_mfma_f32_16x16x32_bf16 v[40:43], v[172:175], v[196:199], v[40:43]
	v_mfma_f32_16x16x32_bf16 v[32:35], v[180:183], v[196:199], v[32:35]
	v_mfma_f32_16x16x32_bf16 v[24:27], v[172:175], v[204:207], v[24:27]
	v_mfma_f32_16x16x32_bf16 v[16:19], v[180:183], v[204:207], v[16:19]
	v_mfma_f32_16x16x32_bf16 v[8:11], v[172:175], v[212:215], v[8:11]
	v_mfma_f32_16x16x32_bf16 v[0:3], v[180:183], v[212:215], v[0:3]
	s_setprio 0
	s_barrier
	s_add_i32 s58, s58, 2
	s_add_u32 s2, s2, 0x100
	s_addc_u32 s3, s3, 0
	s_add_u32 s56, s56, 0x100
	s_addc_u32 s57, s57, 0
	s_cmp_gt_u32 s58, 61
	s_cbranch_scc0 .LBB0_2826
	s_mov_b32 s99, 1
	s_and_b64 vcc, exec, s[18:19]
	s_cbranch_vccz .LBB0_2829
	s_barrier

; #define PG8_STAGE(bufoff, gbase, voff) do { _Pragma("unroll") for (int _i = 0; _i < 2; ++_i) \
;         __builtin_amdgcn_global_load_lds((const unsigned*)((const char*)(gbase) + (voff)[_i]), (PG8_LAS unsigned*)(lds + (bufoff) + ldsw + _i * 8192), 16, 0, 0); } while (0)
; #define PG8_WAIT_V(n) asm volatile("s_waitcnt vmcnt(" #n ")" ::: "memory")
; #define PG8_BAR __builtin_amdgcn_s_barrier()
; template <class Epi, class Sched, bool ALIGN_EPI = false, bool SP2 = false>
; __device__ __forceinline__ void gemm_phase(PG8_LAS unsigned char* lds, const Gemm g, const Sched& S, const Epi& E, const int wid) {
;     ...
;     for (int i = 0; i < 2; ++i) { int R, C; stage_rc(tid * 16 + i * 8192, R, C); const int Rb = Epi::PERM ? ((R & ~31) + perm32(R & 31)) : R;
;         voffA[i] = (unsigned)(R * K + C) * 2u; voffB[i] = (unsigned)(Rb * K + C) * 2u; }
;     const size_t kstep = (size_t)(BK * 2);
;     const size_t hstep = (size_t)HALF * K * 2;
;     const size_t tstep = 2 * hstep;
;     const unsigned ldsw = (unsigned)wid * 1024u;
;     const int aoff = lds_byte(wr * 64 + fr, fq * 8), boff = lds_byte(wc * 32 + fr, fq * 8);
;     ...
;         PG8_WAIT_V(2); PG8_BAR;
;         PG8_STAGE(PG8_SB(1, 0), cB + kstep, voffB); PG8_STAGE(PG8_SA(1, 0), cA + kstep, voffA); PG8_STAGE(PG8_SB(1, 1), cB + hstep + kstep, voffB);
;         PG8_WAIT_V(6); PG8_BAR;
.LBB0_2921:
	v_readlane_b32 s4, v254, 7
	v_readlane_b32 s5, v254, 8
	s_load_dwordx2 s[4:5], s[4:5], 0x108
	s_mov_b64 s[14:15], 0x80
	v_lshl_add_u64 v[6:7], v[6:7], 0, s[14:15]
	s_waitcnt vmcnt(2)
	s_barrier
	s_waitcnt lgkmcnt(0)
	s_add_u32 s8, s4, 0x22000000
	s_addc_u32 s9, s5, 0
	s_add_u32 s10, s4, 0x1a000000
	s_addc_u32 s11, s5, 0
	s_add_u32 s12, s4, 0x50000
	v_readlane_b32 s4, v254, 2
	s_addc_u32 s13, s5, 0
	s_lshl_b32 s4, s4, 5
	s_and_b32 s40, s4, 0x60
	s_add_i32 m0, s34, 0x18000
	s_lshl_b32 s39, s1, 6
	s_lshl_b32 s1, s1, 13
	s_lshr_b32 s16, s40, 3
	global_load_lds_dwordx4 v[6:7], off
	v_lshl_add_u64 v[4:5], v[4:5], 0, s[14:15]
	s_add_i32 m0, s34, 0x1a000
	s_add_i32 s41, s34, 0x8000
	s_add_i32 s42, s34, 0xa000
	global_load_lds_dwordx4 v[4:5], off
	v_lshl_add_u64 v[0:1], v[0:1], 0, s[14:15]
	s_mov_b32 m0, s41
	s_add_u32 s4, s24, 0x2b0080
	global_load_lds_dwordx4 v[0:1], off
	v_lshl_add_u64 v[0:1], v[2:3], 0, s[14:15]
	s_mov_b32 m0, s42
	s_addc_u32 s5, s25, 0
	global_load_lds_dwordx4 v[0:1], off
	s_add_i32 m0, s34, 0x1c000
	v_lshl_add_u64 v[0:1], s[4:5], 0, v[154:155]
	global_load_lds_dwordx4 v[0:1], off
	v_lshl_add_u64 v[0:1], s[4:5], 0, v[158:159]
	s_add_i32 m0, s34, 0x1e000
	v_lshlrev_b32_e32 v3, 6, v8
	global_load_lds_dwordx4 v[0:1], off
	v_ashrrev_i32_e32 v0, 6, v8
	v_and_b32_e32 v1, 48, v8
	v_lshl_add_u32 v2, v0, 10, s1
	s_movk_i32 s1, 0x3c0
	v_and_or_b32 v1, v3, s1, v1
	v_lshlrev_b32_e32 v3, 2, v8
	v_readlane_b32 s1, v254, 10
	v_and_b32_e32 v3, 32, v3
	v_add_lshl_u32 v0, v0, s16, 10
	s_cmpk_lt_u32 s1, 0x100
	v_readlane_b32 s1, v254, 9
	v_readlane_b32 s18, v254, 0
	v_bitop3_b32 v2, v1, v2, v3 bitop3:0xde
	v_bitop3_b32 v186, v1, v0, v3 bitop3:0xde
	s_cselect_b64 s[16:17], -1, 0
	s_ashr_i32 s43, s1, 31
	v_readlane_b32 s19, v254, 1
	v_lshrrev_b32_e32 v1, 1, v9
	v_mul_lo_u32 v0, v11, s0
	s_mov_b32 s1, 0x2b000
	s_ashr_i32 s44, s18, 31
	v_mad_u64_u32 v[0:1], s[18:19], v1, s1, v[0:1]
	v_or_b32_e32 v0, v0, v10
	s_mov_b64 s[4:5], 0x2b0080
	v_add_lshl_u32 v0, v0, v12, 1
	v_mov_b32_e32 v1, v155
	v_lshl_add_u64 v[160:161], v[0:1], 0, s[4:5]
	v_lshrrev_b32_e32 v1, 1, v13
	v_mul_lo_u32 v0, v14, s0
	v_mad_u64_u32 v[0:1], s[0:1], v1, s1, v[0:1]
	v_or_b32_e32 v0, v0, v15
	s_waitcnt vmcnt(6)
	s_mov_b32 s99, 0
	v_add_lshl_u32 v0, v0, v16, 1
	v_mov_b32_e32 v1, v155
	v_lshl_add_u64 v[162:163], v[0:1], 0, s[4:5]
	s_add_i32 s45, 0, 0x10000
	s_add_i32 s46, 0, 0x14000
	v_mbcnt_lo_u32_b32 v0, -1, 0
	v_mov_b64_e32 v[164:165], 0x400
	v_mov_b64_e32 v[166:167], 0x3ff
	v_add_u32_e32 v187, s45, v186
	v_add_u32_e32 v188, s46, v186
	v_add_u32_e32 v189, 0, v2
	v_mbcnt_hi_u32_b32 v190, -1, v0
	s_barrier
	s_branch .LBB0_2924

; #define PG8_STAGE(bufoff, gbase, voff) do { _Pragma("unroll") for (int _i = 0; _i < 2; ++_i) \
;         __builtin_amdgcn_global_load_lds((const unsigned*)((const char*)(gbase) + (voff)[_i]), (PG8_LAS unsigned*)(lds + (bufoff) + ldsw + _i * 8192), 16, 0, 0); } while (0)
; #define PG8_LDA(dst, b, h) do { _Pragma("unroll") for (int m = 0; m < 4; ++m) _Pragma("unroll") for (int k = 0; k < 2; ++k) dst[m][k] = *(const PG8_LAS bf16x8*)(lds + PG8_SA(b, h) + aoff + m * 2048 + k * 1024); } while (0)
; #define PG8_LDB(dst, b, h) do { _Pragma("unroll") for (int n = 0; n < 2; ++n) _Pragma("unroll") for (int k = 0; k < 2; ++k) dst[n][k] = *(const PG8_LAS bf16x8*)(lds + PG8_SB(b, h) + boff + n * 2048 + k * 1024); } while (0)
; #define PG8_MMA(ai, bj, At, Bt) do { __builtin_amdgcn_s_setprio(1); _Pragma("unroll") for (int m = 0; m < 4; ++m) _Pragma("unroll") for (int n = 0; n < 2; ++n) _Pragma("unroll") for (int k = 0; k < 2; ++k) \
;         acc[ai][bj][m][n] = __builtin_amdgcn_mfma_f32_16x16x32_bf16(Bt[n][k], At[m][k], acc[ai][bj][m][n], 0, 0, 0); __builtin_amdgcn_s_setprio(0); } while (0)
; #define PG8_WAIT_V(n) asm volatile("s_waitcnt vmcnt(" #n ")" ::: "memory")
; #define PG8_WAIT_L(n) asm volatile("s_waitcnt lgkmcnt(" #n ")" ::: "memory")
; #define PG8_BAR __builtin_amdgcn_s_barrier()
; #define PG8_SCHED __builtin_amdgcn_sched_barrier(0)
; template <class Epi, class Sched, bool ALIGN_EPI = false, bool SP2 = false>
; __device__ __forceinline__ void gemm_phase(PG8_LAS unsigned char* lds, const Gemm g, const Sched& S, const Epi& E, const int wid) {
;     ...
;             const bool last = (t == nt - 2);
;             const char* a1 = cA + (size_t)(t + 1) * kstep;
;             const char* a2 = last ? nA : cA + (size_t)(t + 2) * kstep; const char* b2 = last ? nB : cB + (size_t)(t + 2) * kstep;
;             const char* a3 = a2 + kstep; const char* b3 = b2 + kstep;
;             if (last && has_next) S.a_ready(nxt);
;             if constexpr (SP2) {
;             PG8_LDB(B0, 0, 0); PG8_LDB(B1, 0, 1); PG8_SCHED; PG8_LDA(At, 0, 0); PG8_STAGE(PG8_SA(1, 1), a1 + hstep, voffA);
;             PG8_WAIT_V(8); PG8_WAIT_L(0); PG8_BAR; PG8_MMA(0, 0, At, B0); PG8_MMA(0, 1, At, B1); PG8_BAR; PG8_SCHED;
;             PG8_LDA(At, 0, 1); PG8_STAGE(PG8_SB(0, 0), b2, voffB); PG8_STAGE(PG8_SB(0, 1), b2 + hstep, voffB); PG8_STAGE(PG8_SA(0, 0), a2, voffA);
.LBB0_2935:
	ds_read_b128 v[128:131], v187
	ds_read_b128 v[132:135], v187 offset:1024
	ds_read_b128 v[136:139], v187 offset:2048
	ds_read_b128 v[140:143], v187 offset:3072
	ds_read_b128 v[144:147], v188
	ds_read_b128 v[148:151], v188 offset:1024
	ds_read_b128 v[168:171], v188 offset:2048
	ds_read_b128 v[172:175], v188 offset:3072
	s_add_u32 s0, s22, 0x100
	s_addc_u32 s1, s23, 0
	s_cmpk_eq_i32 s53, 0xa8
	s_cselect_b32 s27, s19, s1
	s_cselect_b32 s26, s18, s0
	s_cselect_b32 s25, s21, s52
	s_cselect_b32 s24, s20, s51
	v_lshl_add_u64 v[184:185], s[22:23], 0, v[160:161]
	s_add_i32 m0, s34, 0xc000
	ds_read_b128 v[176:179], v189
	ds_read_b128 v[180:183], v189 offset:1024
	ds_read_b128 v[192:195], v189 offset:2048
	ds_read_b128 v[196:199], v189 offset:3072
	ds_read_b128 v[200:203], v189 offset:4096
	ds_read_b128 v[204:207], v189 offset:5120
	ds_read_b128 v[208:211], v189 offset:6144
	ds_read_b128 v[212:215], v189 offset:7168
	global_load_lds_dwordx4 v[184:185], off
	v_lshl_add_u64 v[184:185], s[22:23], 0, v[162:163]
	s_add_i32 m0, s34, 0xe000
	s_nop 0
	global_load_lds_dwordx4 v[184:185], off
	s_cmp_lg_u32 s99, 0
	s_cbranch_scc1 .Lg2935_skip1
	s_waitcnt vmcnt(8)
.Lg2935_skip1:
	s_waitcnt lgkmcnt(0)
	s_barrier
	s_setprio 1
	s_waitcnt lgkmcnt(0)
	v_mfma_f32_16x16x32_bf16 v[124:127], v[128:131], v[176:179], v[124:127]
	v_mfma_f32_16x16x32_bf16 v[120:123], v[136:139], v[176:179], v[120:123]
	v_mfma_f32_16x16x32_bf16 v[108:111], v[128:131], v[192:195], v[108:111]
	v_mfma_f32_16x16x32_bf16 v[104:107], v[136:139], v[192:195], v[104:107]
	v_mfma_f32_16x16x32_bf16 v[92:95], v[128:131], v[200:203], v[92:95]
	v_mfma_f32_16x16x32_bf16 v[88:91], v[136:139], v[200:203], v[88:91]
	v_mfma_f32_16x16x32_bf16 v[76:79], v[128:131], v[208:211], v[76:79]
	v_mfma_f32_16x16x32_bf16 v[72:75], v[136:139], v[208:211], v[72:75]
	v_mfma_f32_16x16x32_bf16 v[124:127], v[132:135], v[180:183], v[124:127]
	v_mfma_f32_16x16x32_bf16 v[120:123], v[140:143], v[180:183], v[120:123]
	v_mfma_f32_16x16x32_bf16 v[108:111], v[132:135], v[196:199], v[108:111]
	v_mfma_f32_16x16x32_bf16 v[104:107], v[140:143], v[196:199], v[104:107]
	v_mfma_f32_16x16x32_bf16 v[92:95], v[132:135], v[204:207], v[92:95]
	v_mfma_f32_16x16x32_bf16 v[88:91], v[140:143], v[204:207], v[88:91]
	v_mfma_f32_16x16x32_bf16 v[76:79], v[132:135], v[212:215], v[76:79]
	v_mfma_f32_16x16x32_bf16 v[72:75], v[140:143], v[212:215], v[72:75]
	s_setprio 0
	s_setprio 1
	v_mfma_f32_16x16x32_bf16 v[116:119], v[144:147], v[176:179], v[116:119]
	v_mfma_f32_16x16x32_bf16 v[112:115], v[168:171], v[176:179], v[112:115]
	v_mfma_f32_16x16x32_bf16 v[100:103], v[144:147], v[192:195], v[100:103]
	v_mfma_f32_16x16x32_bf16 v[96:99], v[168:171], v[192:195], v[96:99]
	v_mfma_f32_16x16x32_bf16 v[84:87], v[144:147], v[200:203], v[84:87]
	v_mfma_f32_16x16x32_bf16 v[80:83], v[168:171], v[200:203], v[80:83]
	v_mfma_f32_16x16x32_bf16 v[68:71], v[144:147], v[208:211], v[68:71]
	v_mfma_f32_16x16x32_bf16 v[64:67], v[168:171], v[208:211], v[64:67]
	v_mfma_f32_16x16x32_bf16 v[116:119], v[148:151], v[180:183], v[116:119]
	v_mfma_f32_16x16x32_bf16 v[112:115], v[172:175], v[180:183], v[112:115]
	v_mfma_f32_16x16x32_bf16 v[100:103], v[148:151], v[196:199], v[100:103]
	v_mfma_f32_16x16x32_bf16 v[96:99], v[172:175], v[196:199], v[96:99]
	v_mfma_f32_16x16x32_bf16 v[84:87], v[148:151], v[204:207], v[84:87]
	v_mfma_f32_16x16x32_bf16 v[80:83], v[172:175], v[204:207], v[80:83]
	v_mfma_f32_16x16x32_bf16 v[68:71], v[148:151], v[212:215], v[68:71]
	v_mfma_f32_16x16x32_bf16 v[64:67], v[172:175], v[212:215], v[64:67]
	s_setprio 0
	s_barrier
	s_add_i32 s22, s45, s33
	v_lshl_add_u64 v[184:185], s[24:25], 0, v[154:155]
	s_mov_b32 m0, s22
	ds_read_b128 v[176:179], v189 offset:16384
	ds_read_b128 v[180:183], v189 offset:17408
	ds_read_b128 v[192:195], v189 offset:18432
	ds_read_b128 v[196:199], v189 offset:19456
	ds_read_b128 v[200:203], v189 offset:20480
	ds_read_b128 v[204:207], v189 offset:21504
	ds_read_b128 v[208:211], v189 offset:22528
	ds_read_b128 v[212:215], v189 offset:23552
	global_load_lds_dwordx4 v[184:185], off
	s_add_i32 m0, s22, 0x2000
	s_add_u32 s22, s24, 0x2b0000
	v_lshl_add_u64 v[216:217], s[24:25], 0, v[158:159]
	s_addc_u32 s23, s25, 0
	s_add_i32 s54, s46, s33
	global_load_lds_dwordx4 v[216:217], off
	v_lshl_add_u64 v[218:219], s[22:23], 0, v[154:155]
	s_mov_b32 m0, s54
	v_lshl_add_u64 v[220:221], s[26:27], 0, v[156:157]
	global_load_lds_dwordx4 v[218:219], off
	v_lshl_add_u64 v[218:219], s[22:23], 0, v[158:159]
	s_add_i32 m0, s54, 0x2000
	s_nop 0
	global_load_lds_dwordx4 v[218:219], off
	v_lshl_add_u64 v[218:219], s[26:27], 0, v[152:153]
	s_mov_b32 m0, s34
	s_nop 0
	global_load_lds_dwordx4 v[218:219], off
	s_mov_b32 m0, s35
	s_nop 0
	global_load_lds_dwordx4 v[220:221], off
	s_cmp_lg_u32 s99, 0
	s_cbranch_scc1 .Lg2935_skip2
	s_waitcnt vmcnt(8)
; #define PG8_STAGE(bufoff, gbase, voff) do { _Pragma("unroll") for (int _i = 0; _i < 2; ++_i) \
;         __builtin_amdgcn_global_load_lds((const unsigned*)((const char*)(gbase) + (voff)[_i]), (PG8_LAS unsigned*)(lds + (bufoff) + ldsw + _i * 8192), 16, 0, 0); } while (0)
; #define PG8_LDA(dst, b, h) do { _Pragma("unroll") for (int m = 0; m < 4; ++m) _Pragma("unroll") for (int k = 0; k < 2; ++k) dst[m][k] = *(const PG8_LAS bf16x8*)(lds + PG8_SA(b, h) + aoff + m * 2048 + k * 1024); } while (0)
; #define PG8_LDB(dst, b, h) do { _Pragma("unroll") for (int n = 0; n < 2; ++n) _Pragma("unroll") for (int k = 0; k < 2; ++k) dst[n][k] = *(const PG8_LAS bf16x8*)(lds + PG8_SB(b, h) + boff + n * 2048 + k * 1024); } while (0)
; #define PG8_MMA(ai, bj, At, Bt) do { __builtin_amdgcn_s_setprio(1); _Pragma("unroll") for (int m = 0; m < 4; ++m) _Pragma("unroll") for (int n = 0; n < 2; ++n) _Pragma("unroll") for (int k = 0; k < 2; ++k) \
;         acc[ai][bj][m][n] = __builtin_amdgcn_mfma_f32_16x16x32_bf16(Bt[n][k], At[m][k], acc[ai][bj][m][n], 0, 0, 0); __builtin_amdgcn_s_setprio(0); } while (0)
; #define PG8_WAIT_V(n) asm volatile("s_waitcnt vmcnt(" #n ")" ::: "memory")
; #define PG8_WAIT_L(n) asm volatile("s_waitcnt lgkmcnt(" #n ")" ::: "memory")
; #define PG8_BAR __builtin_amdgcn_s_barrier()
; #define PG8_SCHED __builtin_amdgcn_sched_barrier(0)
; template <class Epi, class Sched, bool ALIGN_EPI = false, bool SP2 = false>
; __device__ __forceinline__ void gemm_phase(PG8_LAS unsigned char* lds, const Gemm g, const Sched& S, const Epi& E, const int wid) {
;     ...
;             PG8_WAIT_V(8); PG8_WAIT_L(0); PG8_BAR; PG8_MMA(1, 0, At, B0); PG8_MMA(1, 1, At, B1); PG8_BAR; PG8_SCHED;
;             PG8_LDB(B0, 1, 0); PG8_LDB(B1, 1, 1); PG8_SCHED; PG8_LDA(At, 1, 0); PG8_STAGE(PG8_SA(0, 1), a2 + hstep, voffA);
;             PG8_WAIT_V(8); PG8_WAIT_L(0); PG8_BAR; PG8_MMA(0, 0, At, B0); PG8_MMA(0, 1, At, B1); PG8_BAR; PG8_SCHED;
.Lg2935_skip2:
	s_mov_b32 s99, 0
	s_waitcnt lgkmcnt(0)
	s_barrier
	s_setprio 1
	s_waitcnt lgkmcnt(0)
	v_mfma_f32_16x16x32_bf16 v[60:63], v[128:131], v[176:179], v[60:63]
	v_mfma_f32_16x16x32_bf16 v[56:59], v[136:139], v[176:179], v[56:59]
	v_mfma_f32_16x16x32_bf16 v[44:47], v[128:131], v[192:195], v[44:47]
	v_mfma_f32_16x16x32_bf16 v[40:43], v[136:139], v[192:195], v[40:43]
	v_mfma_f32_16x16x32_bf16 v[28:31], v[128:131], v[200:203], v[28:31]
	v_mfma_f32_16x16x32_bf16 v[24:27], v[136:139], v[200:203], v[24:27]
	v_mfma_f32_16x16x32_bf16 v[12:15], v[128:131], v[208:211], v[12:15]
	v_mfma_f32_16x16x32_bf16 v[8:11], v[136:139], v[208:211], v[8:11]
	v_mfma_f32_16x16x32_bf16 v[60:63], v[132:135], v[180:183], v[60:63]
	v_mfma_f32_16x16x32_bf16 v[56:59], v[140:143], v[180:183], v[56:59]
	v_mfma_f32_16x16x32_bf16 v[44:47], v[132:135], v[196:199], v[44:47]
	v_mfma_f32_16x16x32_bf16 v[40:43], v[140:143], v[196:199], v[40:43]
	v_mfma_f32_16x16x32_bf16 v[28:31], v[132:135], v[204:207], v[28:31]
	v_mfma_f32_16x16x32_bf16 v[24:27], v[140:143], v[204:207], v[24:27]
	v_mfma_f32_16x16x32_bf16 v[12:15], v[132:135], v[212:215], v[12:15]
	v_mfma_f32_16x16x32_bf16 v[8:11], v[140:143], v[212:215], v[8:11]
	s_setprio 0
	s_setprio 1
	v_mfma_f32_16x16x32_bf16 v[52:55], v[144:147], v[176:179], v[52:55]
	v_mfma_f32_16x16x32_bf16 v[48:51], v[168:171], v[176:179], v[48:51]
	v_mfma_f32_16x16x32_bf16 v[36:39], v[144:147], v[192:195], v[36:39]
	v_mfma_f32_16x16x32_bf16 v[32:35], v[168:171], v[192:195], v[32:35]
	v_mfma_f32_16x16x32_bf16 v[20:23], v[144:147], v[200:203], v[20:23]
	v_mfma_f32_16x16x32_bf16 v[16:19], v[168:171], v[200:203], v[16:19]
	v_mfma_f32_16x16x32_bf16 v[4:7], v[144:147], v[208:211], v[4:7]
	v_mfma_f32_16x16x32_bf16 v[0:3], v[168:171], v[208:211], v[0:3]
	v_mfma_f32_16x16x32_bf16 v[52:55], v[148:151], v[180:183], v[52:55]
	v_mfma_f32_16x16x32_bf16 v[48:51], v[172:175], v[180:183], v[48:51]
	v_mfma_f32_16x16x32_bf16 v[36:39], v[148:151], v[196:199], v[36:39]
	v_mfma_f32_16x16x32_bf16 v[32:35], v[172:175], v[196:199], v[32:35]
	v_mfma_f32_16x16x32_bf16 v[20:23], v[148:151], v[204:207], v[20:23]
	v_mfma_f32_16x16x32_bf16 v[16:19], v[172:175], v[204:207], v[16:19]
	v_mfma_f32_16x16x32_bf16 v[4:7], v[148:151], v[212:215], v[4:7]
	v_mfma_f32_16x16x32_bf16 v[0:3], v[172:175], v[212:215], v[0:3]
	s_setprio 0
	s_barrier
	s_add_i32 s54, 0, 0x18000
	s_add_i32 s55, 0, 0x1c000
	v_add_u32_e32 v140, s54, v186
	v_add_u32_e32 v172, s55, v186
	ds_read_b128 v[128:131], v140
	ds_read_b128 v[132:135], v140 offset:1024
	ds_read_b128 v[136:139], v140 offset:2048
	ds_read_b128 v[140:143], v140 offset:3072
	ds_read_b128 v[144:147], v172
	ds_read_b128 v[148:151], v172 offset:1024
	ds_read_b128 v[168:171], v172 offset:2048
	ds_read_b128 v[172:175], v172 offset:3072
	s_add_u32 s22, s26, 0x2b0000
	s_addc_u32 s23, s27, 0
	s_mov_b32 m0, s36
	v_lshl_add_u64 v[222:223], s[22:23], 0, v[152:153]
	ds_read_b128 v[176:179], v189 offset:32768
	ds_read_b128 v[180:183], v189 offset:33792
	ds_read_b128 v[192:195], v189 offset:34816
	ds_read_b128 v[196:199], v189 offset:35840
	ds_read_b128 v[200:203], v189 offset:36864
	ds_read_b128 v[204:207], v189 offset:37888
	ds_read_b128 v[208:211], v189 offset:38912
	ds_read_b128 v[212:215], v189 offset:39936
	global_load_lds_dwordx4 v[222:223], off
	v_lshl_add_u64 v[222:223], s[22:23], 0, v[156:157]
	s_mov_b32 m0, s37
	s_nop 0
	global_load_lds_dwordx4 v[222:223], off
	s_waitcnt vmcnt(8)
	s_waitcnt lgkmcnt(0)
	s_barrier
	s_setprio 1
	s_waitcnt lgkmcnt(0)
	v_mfma_f32_16x16x32_bf16 v[124:127], v[128:131], v[176:179], v[124:127]
	v_mfma_f32_16x16x32_bf16 v[120:123], v[136:139], v[176:179], v[120:123]
	v_mfma_f32_16x16x32_bf16 v[108:111], v[128:131], v[192:195], v[108:111]
	v_mfma_f32_16x16x32_bf16 v[104:107], v[136:139], v[192:195], v[104:107]
	v_mfma_f32_16x16x32_bf16 v[92:95], v[128:131], v[200:203], v[92:95]
	v_mfma_f32_16x16x32_bf16 v[88:91], v[136:139], v[200:203], v[88:91]
	v_mfma_f32_16x16x32_bf16 v[76:79], v[128:131], v[208:211], v[76:79]
	v_mfma_f32_16x16x32_bf16 v[72:75], v[136:139], v[208:211], v[72:75]
	v_mfma_f32_16x16x32_bf16 v[124:127], v[132:135], v[180:183], v[124:127]
	v_mfma_f32_16x16x32_bf16 v[120:123], v[140:143], v[180:183], v[120:123]
	v_mfma_f32_16x16x32_bf16 v[108:111], v[132:135], v[196:199], v[108:111]
	v_mfma_f32_16x16x32_bf16 v[104:107], v[140:143], v[196:199], v[104:107]
	v_mfma_f32_16x16x32_bf16 v[92:95], v[132:135], v[204:207], v[92:95]
	v_mfma_f32_16x16x32_bf16 v[88:91], v[140:143], v[204:207], v[88:91]
	v_mfma_f32_16x16x32_bf16 v[76:79], v[132:135], v[212:215], v[76:79]
	v_mfma_f32_16x16x32_bf16 v[72:75], v[140:143], v[212:215], v[72:75]
	s_setprio 0
	s_setprio 1
	v_mfma_f32_16x16x32_bf16 v[116:119], v[144:147], v[176:179], v[116:119]
	v_mfma_f32_16x16x32_bf16 v[112:115], v[168:171], v[176:179], v[112:115]
	v_mfma_f32_16x16x32_bf16 v[100:103], v[144:147], v[192:195], v[100:103]
	v_mfma_f32_16x16x32_bf16 v[96:99], v[168:171], v[192:195], v[96:99]
	v_mfma_f32_16x16x32_bf16 v[84:87], v[144:147], v[200:203], v[84:87]
	v_mfma_f32_16x16x32_bf16 v[80:83], v[168:171], v[200:203], v[80:83]
	v_mfma_f32_16x16x32_bf16 v[68:71], v[144:147], v[208:211], v[68:71]
	v_mfma_f32_16x16x32_bf16 v[64:67], v[168:171], v[208:211], v[64:67]
	v_mfma_f32_16x16x32_bf16 v[116:119], v[148:151], v[180:183], v[116:119]
	v_mfma_f32_16x16x32_bf16 v[112:115], v[172:175], v[180:183], v[112:115]
	v_mfma_f32_16x16x32_bf16 v[100:103], v[148:151], v[196:199], v[100:103]
	v_mfma_f32_16x16x32_bf16 v[96:99], v[172:175], v[196:199], v[96:99]
	v_mfma_f32_16x16x32_bf16 v[84:87], v[148:151], v[204:207], v[84:87]
	v_mfma_f32_16x16x32_bf16 v[80:83], v[172:175], v[204:207], v[80:83]
	v_mfma_f32_16x16x32_bf16 v[68:71], v[148:151], v[212:215], v[68:71]
	v_mfma_f32_16x16x32_bf16 v[64:67], v[172:175], v[212:215], v[64:67]
	s_setprio 0
	s_barrier
; #define PG8_STAGE(bufoff, gbase, voff) do { _Pragma("unroll") for (int _i = 0; _i < 2; ++_i) \
;         __builtin_amdgcn_global_load_lds((const unsigned*)((const char*)(gbase) + (voff)[_i]), (PG8_LAS unsigned*)(lds + (bufoff) + ldsw + _i * 8192), 16, 0, 0); } while (0)
; #define PG8_LDA(dst, b, h) do { _Pragma("unroll") for (int m = 0; m < 4; ++m) _Pragma("unroll") for (int k = 0; k < 2; ++k) dst[m][k] = *(const PG8_LAS bf16x8*)(lds + PG8_SA(b, h) + aoff + m * 2048 + k * 1024); } while (0)
; #define PG8_MMA(ai, bj, At, Bt) do { __builtin_amdgcn_s_setprio(1); _Pragma("unroll") for (int m = 0; m < 4; ++m) _Pragma("unroll") for (int n = 0; n < 2; ++n) _Pragma("unroll") for (int k = 0; k < 2; ++k) \
;         acc[ai][bj][m][n] = __builtin_amdgcn_mfma_f32_16x16x32_bf16(Bt[n][k], At[m][k], acc[ai][bj][m][n], 0, 0, 0); __builtin_amdgcn_s_setprio(0); } while (0)
; #define PG8_WAIT_V(n) asm volatile("s_waitcnt vmcnt(" #n ")" ::: "memory")
; #define PG8_WAIT_L(n) asm volatile("s_waitcnt lgkmcnt(" #n ")" ::: "memory")
; #define PG8_BAR __builtin_amdgcn_s_barrier()
; #define PG8_SCHED __builtin_amdgcn_sched_barrier(0)
; template <class Epi, class Sched, bool ALIGN_EPI = false, bool SP2 = false>
; __device__ __forceinline__ void gemm_phase(PG8_LAS unsigned char* lds, const Gemm g, const Sched& S, const Epi& E, const int wid) {
;     ...
;         for (int t = 0; t < nt; t += 2) {
;             const bool last = (t == nt - 2);
;     ...
;             PG8_LDA(At, 1, 1); PG8_STAGE(PG8_SB(1, 0), b3, voffB); PG8_STAGE(PG8_SB(1, 1), b3 + hstep, voffB); PG8_STAGE(PG8_SA(1, 0), a3, voffA);
;             PG8_WAIT_V(8); PG8_WAIT_L(0); PG8_BAR; PG8_MMA(1, 0, At, B0); PG8_MMA(1, 1, At, B1); PG8_BAR; PG8_SCHED;
	s_add_i32 s22, s54, s33
	v_lshl_add_u64 v[184:185], v[184:185], 0, s[14:15]
	s_mov_b32 m0, s22
	ds_read_b128 v[176:179], v189 offset:49152
	ds_read_b128 v[180:183], v189 offset:50176
	ds_read_b128 v[192:195], v189 offset:51200
	ds_read_b128 v[196:199], v189 offset:52224
	ds_read_b128 v[200:203], v189 offset:53248
	ds_read_b128 v[204:207], v189 offset:54272
	ds_read_b128 v[208:211], v189 offset:55296
	ds_read_b128 v[212:215], v189 offset:56320
	global_load_lds_dwordx4 v[184:185], off
	s_add_i32 m0, s22, 0x2000
	s_add_u32 s22, s24, 0x2b0080
	v_lshl_add_u64 v[184:185], v[216:217], 0, s[14:15]
	s_addc_u32 s23, s25, 0
	s_add_i32 s24, s55, s33
	global_load_lds_dwordx4 v[184:185], off
	v_lshl_add_u64 v[184:185], s[22:23], 0, v[154:155]
	s_mov_b32 m0, s24
	s_nop 0
	global_load_lds_dwordx4 v[184:185], off
	v_lshl_add_u64 v[184:185], s[22:23], 0, v[158:159]
	s_add_i32 m0, s24, 0x2000
	s_nop 0
	global_load_lds_dwordx4 v[184:185], off
	v_lshl_add_u64 v[184:185], v[218:219], 0, s[14:15]
	s_mov_b32 m0, s41
	s_nop 0
	global_load_lds_dwordx4 v[184:185], off
	v_lshl_add_u64 v[184:185], v[220:221], 0, s[14:15]
	s_mov_b32 m0, s42
	s_nop 0
	global_load_lds_dwordx4 v[184:185], off
	s_waitcnt vmcnt(8)
	s_waitcnt lgkmcnt(0)
	s_barrier
	s_setprio 1
	s_waitcnt lgkmcnt(0)
	v_mfma_f32_16x16x32_bf16 v[60:63], v[128:131], v[176:179], v[60:63]
	v_mfma_f32_16x16x32_bf16 v[56:59], v[136:139], v[176:179], v[56:59]
	v_mfma_f32_16x16x32_bf16 v[44:47], v[128:131], v[192:195], v[44:47]
	v_mfma_f32_16x16x32_bf16 v[40:43], v[136:139], v[192:195], v[40:43]
	v_mfma_f32_16x16x32_bf16 v[28:31], v[128:131], v[200:203], v[28:31]
	v_mfma_f32_16x16x32_bf16 v[24:27], v[136:139], v[200:203], v[24:27]
	v_mfma_f32_16x16x32_bf16 v[12:15], v[128:131], v[208:211], v[12:15]
	v_mfma_f32_16x16x32_bf16 v[8:11], v[136:139], v[208:211], v[8:11]
	v_mfma_f32_16x16x32_bf16 v[60:63], v[132:135], v[180:183], v[60:63]
	v_mfma_f32_16x16x32_bf16 v[56:59], v[140:143], v[180:183], v[56:59]
	v_mfma_f32_16x16x32_bf16 v[44:47], v[132:135], v[196:199], v[44:47]
	v_mfma_f32_16x16x32_bf16 v[40:43], v[140:143], v[196:199], v[40:43]
	v_mfma_f32_16x16x32_bf16 v[28:31], v[132:135], v[204:207], v[28:31]
	v_mfma_f32_16x16x32_bf16 v[24:27], v[140:143], v[204:207], v[24:27]
	v_mfma_f32_16x16x32_bf16 v[12:15], v[132:135], v[212:215], v[12:15]
	v_mfma_f32_16x16x32_bf16 v[8:11], v[140:143], v[212:215], v[8:11]
	s_setprio 0
	s_setprio 1
	v_mfma_f32_16x16x32_bf16 v[52:55], v[144:147], v[176:179], v[52:55]
	v_mfma_f32_16x16x32_bf16 v[48:51], v[168:171], v[176:179], v[48:51]
	v_mfma_f32_16x16x32_bf16 v[36:39], v[144:147], v[192:195], v[36:39]
	v_mfma_f32_16x16x32_bf16 v[32:35], v[168:171], v[192:195], v[32:35]
	v_mfma_f32_16x16x32_bf16 v[20:23], v[144:147], v[200:203], v[20:23]
	v_mfma_f32_16x16x32_bf16 v[16:19], v[168:171], v[200:203], v[16:19]
	v_mfma_f32_16x16x32_bf16 v[4:7], v[144:147], v[208:211], v[4:7]
	v_mfma_f32_16x16x32_bf16 v[0:3], v[168:171], v[208:211], v[0:3]
	v_mfma_f32_16x16x32_bf16 v[52:55], v[148:151], v[180:183], v[52:55]
	v_mfma_f32_16x16x32_bf16 v[48:51], v[172:175], v[180:183], v[48:51]
	v_mfma_f32_16x16x32_bf16 v[36:39], v[148:151], v[196:199], v[36:39]
	v_mfma_f32_16x16x32_bf16 v[32:35], v[172:175], v[196:199], v[32:35]
	v_mfma_f32_16x16x32_bf16 v[20:23], v[148:151], v[204:207], v[20:23]
	v_mfma_f32_16x16x32_bf16 v[16:19], v[172:175], v[204:207], v[16:19]
	v_mfma_f32_16x16x32_bf16 v[4:7], v[148:151], v[212:215], v[4:7]
	v_mfma_f32_16x16x32_bf16 v[0:3], v[172:175], v[212:215], v[0:3]
	s_setprio 0
	s_barrier
	s_add_i32 s53, s53, 2
	s_add_u32 s51, s51, 0x100
	s_addc_u32 s52, s52, 0
	s_cmpk_gt_u32 s53, 0xa9
	s_mov_b64 s[22:23], s[0:1]
	s_cbranch_scc0 .LBB0_2935
	s_mov_b32 s99, 1
	s_and_b64 vcc, exec, s[16:17]
	s_cbranch_vccz .LBB0_2938
	s_barrier

; #define PG8_STAGE(bufoff, gbase, voff) do { _Pragma("unroll") for (int _i = 0; _i < 2; ++_i) \
;         __builtin_amdgcn_global_load_lds((const unsigned*)((const char*)(gbase) + (voff)[_i]), (PG8_LAS unsigned*)(lds + (bufoff) + ldsw + _i * 8192), 16, 0, 0); } while (0)
; #define PG8_WAIT_V(n) asm volatile("s_waitcnt vmcnt(" #n ")" ::: "memory")
; #define PG8_BAR __builtin_amdgcn_s_barrier()
; template <class Epi, class Sched, bool ALIGN_EPI = false, bool SP2 = false>
; __device__ __forceinline__ void gemm_phase(PG8_LAS unsigned char* lds, const Gemm g, const Sched& S, const Epi& E, const int wid) {
;     ...
;     for (int i = 0; i < 2; ++i) { int R, C; stage_rc(tid * 16 + i * 8192, R, C); const int Rb = Epi::PERM ? ((R & ~31) + perm32(R & 31)) : R;
;         voffA[i] = (unsigned)(R * K + C) * 2u; voffB[i] = (unsigned)(Rb * K + C) * 2u; }
;     const size_t kstep = (size_t)(BK * 2);
;     const size_t hstep = (size_t)HALF * K * 2;
;     const size_t tstep = 2 * hstep;
;     const unsigned ldsw = (unsigned)wid * 1024u;
;     const int aoff = lds_byte(wr * 64 + fr, fq * 8), boff = lds_byte(wc * 32 + fr, fq * 8);
;     ...
;         PG8_WAIT_V(2); PG8_BAR;
;         PG8_STAGE(PG8_SB(1, 0), cB + kstep, voffB); PG8_STAGE(PG8_SA(1, 0), cA + kstep, voffA); PG8_STAGE(PG8_SB(1, 1), cB + hstep + kstep, voffB);
;         PG8_WAIT_V(6); PG8_BAR;
.LBB0_3020:
	v_readlane_b32 s12, v254, 7
	v_readlane_b32 s13, v254, 8
	s_load_dwordx2 s[18:19], s[12:13], 0x108
	s_mov_b64 s[20:21], 0x80
	v_lshl_add_u64 v[6:7], v[6:7], 0, s[20:21]
	s_waitcnt vmcnt(2)
	s_barrier
	s_waitcnt lgkmcnt(0)
	s_add_u32 s12, s18, 0x22000000
	s_addc_u32 s13, s19, 0
	s_add_u32 s14, s18, 0x42400000
	s_addc_u32 s15, s19, 0
	s_add_u32 s16, s18, 0x50000
	s_addc_u32 s17, s19, 0
	s_add_u32 s18, s18, 0x60000
	s_addc_u32 s19, s19, 0
	s_lshl_b32 s47, s4, 6
	s_lshl_b32 s1, s4, 13
	v_readlane_b32 s4, v254, 2
	s_lshl_b32 s4, s4, 5
	s_and_b32 s48, s4, 0x60
	s_add_i32 m0, s42, 0x18000
	s_lshr_b32 s7, s48, 3
	global_load_lds_dwordx4 v[6:7], off
	v_lshl_add_u64 v[4:5], v[4:5], 0, s[20:21]
	s_add_i32 m0, s42, 0x1a000
	s_add_i32 s49, s42, 0x8000
	s_add_i32 s50, s42, 0xa000
	global_load_lds_dwordx4 v[4:5], off
	v_lshl_add_u64 v[0:1], v[0:1], 0, s[20:21]
	s_mov_b32 m0, s49
	s_add_u32 s4, s36, 0x100080
	global_load_lds_dwordx4 v[0:1], off
	v_lshl_add_u64 v[0:1], v[2:3], 0, s[20:21]
	s_mov_b32 m0, s50
	s_addc_u32 s5, s37, 0
	global_load_lds_dwordx4 v[0:1], off
	s_add_i32 m0, s42, 0x1c000
	v_lshl_add_u64 v[0:1], s[4:5], 0, v[154:155]
	global_load_lds_dwordx4 v[0:1], off
	v_lshl_add_u64 v[0:1], s[4:5], 0, v[158:159]
	s_add_i32 m0, s42, 0x1e000
	v_lshlrev_b32_e32 v3, 6, v8
	global_load_lds_dwordx4 v[0:1], off
	v_ashrrev_i32_e32 v0, 6, v8
	v_and_b32_e32 v1, 48, v8
	v_lshl_add_u32 v2, v0, 10, s1
	s_movk_i32 s1, 0x3c0
	v_and_or_b32 v1, v3, s1, v1
	v_lshlrev_b32_e32 v3, 2, v8
	v_and_b32_e32 v3, 32, v3
	v_add_lshl_u32 v0, v0, s7, 10
	v_bitop3_b32 v180, v1, v0, v3 bitop3:0xde
	v_lshlrev_b32_e32 v0, 16, v9
	v_and_b32_e32 v0, 0xfffe0000, v0
	v_bitop3_b32 v2, v1, v2, v3 bitop3:0xde
	v_lshl_add_u32 v0, v10, 13, v0
	v_and_b32_e32 v1, 1, v9
	v_lshl_or_b32 v0, v1, 6, v0
	v_lshl_add_u32 v160, v11, 1, v0
	v_lshlrev_b32_e32 v0, 16, v12
	v_and_b32_e32 v0, 0xfffe0000, v0
	v_readlane_b32 s1, v254, 10
	v_lshl_add_u32 v0, v13, 13, v0
	v_and_b32_e32 v1, 1, v12
	s_waitcnt vmcnt(6)
	s_mov_b32 s99, 0
	s_cmpk_lt_u32 s1, 0x100
	v_lshl_or_b32 v0, v1, 6, v0
	s_cselect_b64 s[22:23], -1, 0
	v_readlane_b32 s1, v254, 9
	v_readlane_b32 s4, v254, 0
	v_lshl_add_u32 v162, v14, 1, v0
	s_add_i32 s53, 0, 0x10000
	s_add_i32 s54, 0, 0x14000
	v_mbcnt_lo_u32_b32 v0, -1, 0
	s_ashr_i32 s51, s1, 31
	s_ashr_i32 s52, s4, 31
	v_mov_b32_e32 v161, v155
	v_mov_b32_e32 v163, v155
	v_mov_b64_e32 v[164:165], 0x400
	v_mov_b64_e32 v[166:167], 0x3ff
	v_add_u32_e32 v181, s53, v180
	v_add_u32_e32 v182, s54, v180
	v_add_u32_e32 v183, 0, v2
	v_mov_b32_e32 v184, 0x358637bd
	v_mbcnt_hi_u32_b32 v185, -1, v0
	s_barrier
	v_readlane_b32 s5, v254, 1
	s_branch .LBB0_3023

; #define PG8_STAGE(bufoff, gbase, voff) do { _Pragma("unroll") for (int _i = 0; _i < 2; ++_i) \
;         __builtin_amdgcn_global_load_lds((const unsigned*)((const char*)(gbase) + (voff)[_i]), (PG8_LAS unsigned*)(lds + (bufoff) + ldsw + _i * 8192), 16, 0, 0); } while (0)
; #define PG8_LDA(dst, b, h) do { _Pragma("unroll") for (int m = 0; m < 4; ++m) _Pragma("unroll") for (int k = 0; k < 2; ++k) dst[m][k] = *(const PG8_LAS bf16x8*)(lds + PG8_SA(b, h) + aoff + m * 2048 + k * 1024); } while (0)
; #define PG8_LDB(dst, b, h) do { _Pragma("unroll") for (int n = 0; n < 2; ++n) _Pragma("unroll") for (int k = 0; k < 2; ++k) dst[n][k] = *(const PG8_LAS bf16x8*)(lds + PG8_SB(b, h) + boff + n * 2048 + k * 1024); } while (0)
; #define PG8_MMA(ai, bj, At, Bt) do { __builtin_amdgcn_s_setprio(1); _Pragma("unroll") for (int m = 0; m < 4; ++m) _Pragma("unroll") for (int n = 0; n < 2; ++n) _Pragma("unroll") for (int k = 0; k < 2; ++k) \
;         acc[ai][bj][m][n] = __builtin_amdgcn_mfma_f32_16x16x32_bf16(Bt[n][k], At[m][k], acc[ai][bj][m][n], 0, 0, 0); __builtin_amdgcn_s_setprio(0); } while (0)
; #define PG8_WAIT_V(n) asm volatile("s_waitcnt vmcnt(" #n ")" ::: "memory")
; #define PG8_WAIT_L(n) asm volatile("s_waitcnt lgkmcnt(" #n ")" ::: "memory")
; #define PG8_BAR __builtin_amdgcn_s_barrier()
; #define PG8_SCHED __builtin_amdgcn_sched_barrier(0)
; template <class Epi, class Sched, bool ALIGN_EPI = false, bool SP2 = false>
; __device__ __forceinline__ void gemm_phase(PG8_LAS unsigned char* lds, const Gemm g, const Sched& S, const Epi& E, const int wid) {
;     ...
;             const bool last = (t == nt - 2);
;             const char* a1 = cA + (size_t)(t + 1) * kstep;
;             const char* a2 = last ? nA : cA + (size_t)(t + 2) * kstep; const char* b2 = last ? nB : cB + (size_t)(t + 2) * kstep;
;             const char* a3 = a2 + kstep; const char* b3 = b2 + kstep;
;             if (last && has_next) S.a_ready(nxt);
;             if constexpr (SP2) {
;             PG8_LDB(B0, 0, 0); PG8_LDB(B1, 0, 1); PG8_SCHED; PG8_LDA(At, 0, 0); PG8_STAGE(PG8_SA(1, 1), a1 + hstep, voffA);
;             PG8_WAIT_V(8); PG8_WAIT_L(0); PG8_BAR; PG8_MMA(0, 0, At, B0); PG8_MMA(0, 1, At, B1); PG8_BAR; PG8_SCHED;
;             PG8_LDA(At, 0, 1); PG8_STAGE(PG8_SB(0, 0), b2, voffB); PG8_STAGE(PG8_SB(0, 1), b2 + hstep, voffB); PG8_STAGE(PG8_SA(0, 0), a2, voffA);
.LBB0_3030:
	ds_read_b128 v[128:131], v181
	ds_read_b128 v[132:135], v181 offset:1024
	ds_read_b128 v[136:139], v181 offset:2048
	ds_read_b128 v[140:143], v181 offset:3072
	ds_read_b128 v[144:147], v182
	ds_read_b128 v[148:151], v182 offset:1024
	ds_read_b128 v[168:171], v182 offset:2048
	ds_read_b128 v[172:175], v182 offset:3072
	s_add_u32 s36, s34, 0xfff00080
	s_addc_u32 s37, s35, -1
	s_cmp_eq_u32 s57, 60
	s_cselect_b32 s39, s1, s37
	s_cselect_b32 s38, s7, s36
	s_cselect_b32 s37, s25, s56
	s_cselect_b32 s36, s27, s55
	v_lshl_add_u64 v[214:215], s[34:35], 0, v[160:161]
	s_add_i32 m0, s42, 0xc000
	ds_read_b128 v[176:179], v183
	ds_read_b128 v[186:189], v183 offset:1024
	ds_read_b128 v[190:193], v183 offset:2048
	ds_read_b128 v[194:197], v183 offset:3072
	ds_read_b128 v[198:201], v183 offset:4096
	ds_read_b128 v[202:205], v183 offset:5120
	ds_read_b128 v[206:209], v183 offset:6144
	ds_read_b128 v[210:213], v183 offset:7168
	global_load_lds_dwordx4 v[214:215], off
	v_lshl_add_u64 v[214:215], s[34:35], 0, v[162:163]
	s_add_i32 m0, s42, 0xe000
	s_nop 0
	global_load_lds_dwordx4 v[214:215], off
	s_cmp_lg_u32 s99, 0
	s_cbranch_scc1 .Lg3030_skip1
	s_waitcnt vmcnt(8)
.Lg3030_skip1:
	s_waitcnt lgkmcnt(0)
	s_barrier
	s_setprio 1
	s_waitcnt lgkmcnt(0)
	v_mfma_f32_16x16x32_bf16 v[124:127], v[128:131], v[176:179], v[124:127]
	v_mfma_f32_16x16x32_bf16 v[120:123], v[136:139], v[176:179], v[120:123]
	v_mfma_f32_16x16x32_bf16 v[108:111], v[128:131], v[190:193], v[108:111]
	v_mfma_f32_16x16x32_bf16 v[104:107], v[136:139], v[190:193], v[104:107]
	v_mfma_f32_16x16x32_bf16 v[92:95], v[128:131], v[198:201], v[92:95]
	v_mfma_f32_16x16x32_bf16 v[88:91], v[136:139], v[198:201], v[88:91]
	v_mfma_f32_16x16x32_bf16 v[76:79], v[128:131], v[206:209], v[76:79]
	v_mfma_f32_16x16x32_bf16 v[72:75], v[136:139], v[206:209], v[72:75]
	v_mfma_f32_16x16x32_bf16 v[124:127], v[132:135], v[186:189], v[124:127]
	v_mfma_f32_16x16x32_bf16 v[120:123], v[140:143], v[186:189], v[120:123]
	v_mfma_f32_16x16x32_bf16 v[108:111], v[132:135], v[194:197], v[108:111]
	v_mfma_f32_16x16x32_bf16 v[104:107], v[140:143], v[194:197], v[104:107]
	v_mfma_f32_16x16x32_bf16 v[92:95], v[132:135], v[202:205], v[92:95]
	v_mfma_f32_16x16x32_bf16 v[88:91], v[140:143], v[202:205], v[88:91]
	v_mfma_f32_16x16x32_bf16 v[76:79], v[132:135], v[210:213], v[76:79]
	v_mfma_f32_16x16x32_bf16 v[72:75], v[140:143], v[210:213], v[72:75]
	s_setprio 0
	s_setprio 1
	v_mfma_f32_16x16x32_bf16 v[116:119], v[144:147], v[176:179], v[116:119]
	v_mfma_f32_16x16x32_bf16 v[112:115], v[168:171], v[176:179], v[112:115]
	v_mfma_f32_16x16x32_bf16 v[100:103], v[144:147], v[190:193], v[100:103]
	v_mfma_f32_16x16x32_bf16 v[96:99], v[168:171], v[190:193], v[96:99]
	v_mfma_f32_16x16x32_bf16 v[84:87], v[144:147], v[198:201], v[84:87]
	v_mfma_f32_16x16x32_bf16 v[80:83], v[168:171], v[198:201], v[80:83]
	v_mfma_f32_16x16x32_bf16 v[68:71], v[144:147], v[206:209], v[68:71]
	v_mfma_f32_16x16x32_bf16 v[64:67], v[168:171], v[206:209], v[64:67]
	v_mfma_f32_16x16x32_bf16 v[116:119], v[148:151], v[186:189], v[116:119]
	v_mfma_f32_16x16x32_bf16 v[112:115], v[172:175], v[186:189], v[112:115]
	v_mfma_f32_16x16x32_bf16 v[100:103], v[148:151], v[194:197], v[100:103]
	v_mfma_f32_16x16x32_bf16 v[96:99], v[172:175], v[194:197], v[96:99]
	v_mfma_f32_16x16x32_bf16 v[84:87], v[148:151], v[202:205], v[84:87]
	v_mfma_f32_16x16x32_bf16 v[80:83], v[172:175], v[202:205], v[80:83]
	v_mfma_f32_16x16x32_bf16 v[68:71], v[148:151], v[210:213], v[68:71]
	v_mfma_f32_16x16x32_bf16 v[64:67], v[172:175], v[210:213], v[64:67]
	s_setprio 0
	s_barrier
	s_add_i32 s58, s53, s41
	v_lshl_add_u64 v[214:215], s[36:37], 0, v[154:155]
	s_mov_b32 m0, s58
	ds_read_b128 v[176:179], v183 offset:16384
	ds_read_b128 v[186:189], v183 offset:17408
	ds_read_b128 v[190:193], v183 offset:18432
	ds_read_b128 v[194:197], v183 offset:19456
	ds_read_b128 v[198:201], v183 offset:20480
	ds_read_b128 v[202:205], v183 offset:21504
	ds_read_b128 v[206:209], v183 offset:22528
	ds_read_b128 v[210:213], v183 offset:23552
	global_load_lds_dwordx4 v[214:215], off
	s_add_i32 m0, s58, 0x2000
	s_add_u32 s58, s36, 0x100000
	v_lshl_add_u64 v[216:217], s[36:37], 0, v[158:159]
	s_addc_u32 s59, s37, 0
	s_add_i32 s60, s54, s41
	global_load_lds_dwordx4 v[216:217], off
	v_lshl_add_u64 v[218:219], s[58:59], 0, v[154:155]
	s_mov_b32 m0, s60
	v_lshl_add_u64 v[220:221], s[38:39], 0, v[156:157]
	global_load_lds_dwordx4 v[218:219], off
	v_lshl_add_u64 v[218:219], s[58:59], 0, v[158:159]
	s_add_i32 m0, s60, 0x2000
	s_nop 0
	global_load_lds_dwordx4 v[218:219], off
	v_lshl_add_u64 v[218:219], s[38:39], 0, v[152:153]
	s_mov_b32 m0, s42
	s_nop 0
	global_load_lds_dwordx4 v[218:219], off
	s_mov_b32 m0, s43
	s_nop 0
	global_load_lds_dwordx4 v[220:221], off
	s_cmp_lg_u32 s99, 0
	s_cbranch_scc1 .Lg3030_skip2
	s_waitcnt vmcnt(8)
; #define PG8_STAGE(bufoff, gbase, voff) do { _Pragma("unroll") for (int _i = 0; _i < 2; ++_i) \
;         __builtin_amdgcn_global_load_lds((const unsigned*)((const char*)(gbase) + (voff)[_i]), (PG8_LAS unsigned*)(lds + (bufoff) + ldsw + _i * 8192), 16, 0, 0); } while (0)
; #define PG8_LDA(dst, b, h) do { _Pragma("unroll") for (int m = 0; m < 4; ++m) _Pragma("unroll") for (int k = 0; k < 2; ++k) dst[m][k] = *(const PG8_LAS bf16x8*)(lds + PG8_SA(b, h) + aoff + m * 2048 + k * 1024); } while (0)
; #define PG8_LDB(dst, b, h) do { _Pragma("unroll") for (int n = 0; n < 2; ++n) _Pragma("unroll") for (int k = 0; k < 2; ++k) dst[n][k] = *(const PG8_LAS bf16x8*)(lds + PG8_SB(b, h) + boff + n * 2048 + k * 1024); } while (0)
; #define PG8_MMA(ai, bj, At, Bt) do { __builtin_amdgcn_s_setprio(1); _Pragma("unroll") for (int m = 0; m < 4; ++m) _Pragma("unroll") for (int n = 0; n < 2; ++n) _Pragma("unroll") for (int k = 0; k < 2; ++k) \
;         acc[ai][bj][m][n] = __builtin_amdgcn_mfma_f32_16x16x32_bf16(Bt[n][k], At[m][k], acc[ai][bj][m][n], 0, 0, 0); __builtin_amdgcn_s_setprio(0); } while (0)
; #define PG8_WAIT_V(n) asm volatile("s_waitcnt vmcnt(" #n ")" ::: "memory")
; #define PG8_WAIT_L(n) asm volatile("s_waitcnt lgkmcnt(" #n ")" ::: "memory")
; #define PG8_BAR __builtin_amdgcn_s_barrier()
; #define PG8_SCHED __builtin_amdgcn_sched_barrier(0)
; template <class Epi, class Sched, bool ALIGN_EPI = false, bool SP2 = false>
; __device__ __forceinline__ void gemm_phase(PG8_LAS unsigned char* lds, const Gemm g, const Sched& S, const Epi& E, const int wid) {
;     ...
;             PG8_WAIT_V(8); PG8_WAIT_L(0); PG8_BAR; PG8_MMA(1, 0, At, B0); PG8_MMA(1, 1, At, B1); PG8_BAR; PG8_SCHED;
;             PG8_LDB(B0, 1, 0); PG8_LDB(B1, 1, 1); PG8_SCHED; PG8_LDA(At, 1, 0); PG8_STAGE(PG8_SA(0, 1), a2 + hstep, voffA);
;             PG8_WAIT_V(8); PG8_WAIT_L(0); PG8_BAR; PG8_MMA(0, 0, At, B0); PG8_MMA(0, 1, At, B1); PG8_BAR; PG8_SCHED;
.Lg3030_skip2:
	s_mov_b32 s99, 0
	s_waitcnt lgkmcnt(0)
	s_barrier
	s_setprio 1
	s_waitcnt lgkmcnt(0)
	v_mfma_f32_16x16x32_bf16 v[60:63], v[128:131], v[176:179], v[60:63]
	v_mfma_f32_16x16x32_bf16 v[56:59], v[136:139], v[176:179], v[56:59]
	v_mfma_f32_16x16x32_bf16 v[44:47], v[128:131], v[190:193], v[44:47]
	v_mfma_f32_16x16x32_bf16 v[40:43], v[136:139], v[190:193], v[40:43]
	v_mfma_f32_16x16x32_bf16 v[28:31], v[128:131], v[198:201], v[28:31]
	v_mfma_f32_16x16x32_bf16 v[24:27], v[136:139], v[198:201], v[24:27]
	v_mfma_f32_16x16x32_bf16 v[12:15], v[128:131], v[206:209], v[12:15]
	v_mfma_f32_16x16x32_bf16 v[8:11], v[136:139], v[206:209], v[8:11]
	v_mfma_f32_16x16x32_bf16 v[60:63], v[132:135], v[186:189], v[60:63]
	v_mfma_f32_16x16x32_bf16 v[56:59], v[140:143], v[186:189], v[56:59]
	v_mfma_f32_16x16x32_bf16 v[44:47], v[132:135], v[194:197], v[44:47]
	v_mfma_f32_16x16x32_bf16 v[40:43], v[140:143], v[194:197], v[40:43]
	v_mfma_f32_16x16x32_bf16 v[28:31], v[132:135], v[202:205], v[28:31]
	v_mfma_f32_16x16x32_bf16 v[24:27], v[140:143], v[202:205], v[24:27]
	v_mfma_f32_16x16x32_bf16 v[12:15], v[132:135], v[210:213], v[12:15]
	v_mfma_f32_16x16x32_bf16 v[8:11], v[140:143], v[210:213], v[8:11]
	s_setprio 0
	s_setprio 1
	v_mfma_f32_16x16x32_bf16 v[52:55], v[144:147], v[176:179], v[52:55]
	v_mfma_f32_16x16x32_bf16 v[48:51], v[168:171], v[176:179], v[48:51]
	v_mfma_f32_16x16x32_bf16 v[36:39], v[144:147], v[190:193], v[36:39]
	v_mfma_f32_16x16x32_bf16 v[32:35], v[168:171], v[190:193], v[32:35]
	v_mfma_f32_16x16x32_bf16 v[20:23], v[144:147], v[198:201], v[20:23]
	v_mfma_f32_16x16x32_bf16 v[16:19], v[168:171], v[198:201], v[16:19]
	v_mfma_f32_16x16x32_bf16 v[4:7], v[144:147], v[206:209], v[4:7]
	v_mfma_f32_16x16x32_bf16 v[0:3], v[168:171], v[206:209], v[0:3]
	v_mfma_f32_16x16x32_bf16 v[52:55], v[148:151], v[186:189], v[52:55]
	v_mfma_f32_16x16x32_bf16 v[48:51], v[172:175], v[186:189], v[48:51]
	v_mfma_f32_16x16x32_bf16 v[36:39], v[148:151], v[194:197], v[36:39]
	v_mfma_f32_16x16x32_bf16 v[32:35], v[172:175], v[194:197], v[32:35]
	v_mfma_f32_16x16x32_bf16 v[20:23], v[148:151], v[202:205], v[20:23]
	v_mfma_f32_16x16x32_bf16 v[16:19], v[172:175], v[202:205], v[16:19]
	v_mfma_f32_16x16x32_bf16 v[4:7], v[148:151], v[210:213], v[4:7]
	v_mfma_f32_16x16x32_bf16 v[0:3], v[172:175], v[210:213], v[0:3]
	s_setprio 0
	s_barrier
	s_add_i32 s58, 0, 0x18000
	s_add_i32 s59, 0, 0x1c000
	v_add_u32_e32 v140, s58, v180
	v_add_u32_e32 v172, s59, v180
	ds_read_b128 v[128:131], v140
	ds_read_b128 v[132:135], v140 offset:1024
	ds_read_b128 v[136:139], v140 offset:2048
	ds_read_b128 v[140:143], v140 offset:3072
	ds_read_b128 v[144:147], v172
	ds_read_b128 v[148:151], v172 offset:1024
	ds_read_b128 v[168:171], v172 offset:2048
	ds_read_b128 v[172:175], v172 offset:3072
	s_add_u32 s38, s38, 0x100000
	s_addc_u32 s39, s39, 0
	s_mov_b32 m0, s44
	v_lshl_add_u64 v[222:223], s[38:39], 0, v[152:153]
	ds_read_b128 v[176:179], v183 offset:32768
	ds_read_b128 v[186:189], v183 offset:33792
	ds_read_b128 v[190:193], v183 offset:34816
	ds_read_b128 v[194:197], v183 offset:35840
	ds_read_b128 v[198:201], v183 offset:36864
	ds_read_b128 v[202:205], v183 offset:37888
	ds_read_b128 v[206:209], v183 offset:38912
	ds_read_b128 v[210:213], v183 offset:39936
	global_load_lds_dwordx4 v[222:223], off
	v_lshl_add_u64 v[222:223], s[38:39], 0, v[156:157]
	s_mov_b32 m0, s45
	s_nop 0
	global_load_lds_dwordx4 v[222:223], off
	s_waitcnt vmcnt(8)
	s_waitcnt lgkmcnt(0)
	s_barrier
	s_setprio 1
	s_waitcnt lgkmcnt(0)
	v_mfma_f32_16x16x32_bf16 v[124:127], v[128:131], v[176:179], v[124:127]
	v_mfma_f32_16x16x32_bf16 v[120:123], v[136:139], v[176:179], v[120:123]
	v_mfma_f32_16x16x32_bf16 v[108:111], v[128:131], v[190:193], v[108:111]
	v_mfma_f32_16x16x32_bf16 v[104:107], v[136:139], v[190:193], v[104:107]
	v_mfma_f32_16x16x32_bf16 v[92:95], v[128:131], v[198:201], v[92:95]
	v_mfma_f32_16x16x32_bf16 v[88:91], v[136:139], v[198:201], v[88:91]
	v_mfma_f32_16x16x32_bf16 v[76:79], v[128:131], v[206:209], v[76:79]
	v_mfma_f32_16x16x32_bf16 v[72:75], v[136:139], v[206:209], v[72:75]
	v_mfma_f32_16x16x32_bf16 v[124:127], v[132:135], v[186:189], v[124:127]
	v_mfma_f32_16x16x32_bf16 v[120:123], v[140:143], v[186:189], v[120:123]
	v_mfma_f32_16x16x32_bf16 v[108:111], v[132:135], v[194:197], v[108:111]
	v_mfma_f32_16x16x32_bf16 v[104:107], v[140:143], v[194:197], v[104:107]
	v_mfma_f32_16x16x32_bf16 v[92:95], v[132:135], v[202:205], v[92:95]
	v_mfma_f32_16x16x32_bf16 v[88:91], v[140:143], v[202:205], v[88:91]
	v_mfma_f32_16x16x32_bf16 v[76:79], v[132:135], v[210:213], v[76:79]
	v_mfma_f32_16x16x32_bf16 v[72:75], v[140:143], v[210:213], v[72:75]
	s_setprio 0
	s_setprio 1
	v_mfma_f32_16x16x32_bf16 v[116:119], v[144:147], v[176:179], v[116:119]
	v_mfma_f32_16x16x32_bf16 v[112:115], v[168:171], v[176:179], v[112:115]
	v_mfma_f32_16x16x32_bf16 v[100:103], v[144:147], v[190:193], v[100:103]
	v_mfma_f32_16x16x32_bf16 v[96:99], v[168:171], v[190:193], v[96:99]
	v_mfma_f32_16x16x32_bf16 v[84:87], v[144:147], v[198:201], v[84:87]
	v_mfma_f32_16x16x32_bf16 v[80:83], v[168:171], v[198:201], v[80:83]
	v_mfma_f32_16x16x32_bf16 v[68:71], v[144:147], v[206:209], v[68:71]
	v_mfma_f32_16x16x32_bf16 v[64:67], v[168:171], v[206:209], v[64:67]
	v_mfma_f32_16x16x32_bf16 v[116:119], v[148:151], v[186:189], v[116:119]
	v_mfma_f32_16x16x32_bf16 v[112:115], v[172:175], v[186:189], v[112:115]
	v_mfma_f32_16x16x32_bf16 v[100:103], v[148:151], v[194:197], v[100:103]
	v_mfma_f32_16x16x32_bf16 v[96:99], v[172:175], v[194:197], v[96:99]
	v_mfma_f32_16x16x32_bf16 v[84:87], v[148:151], v[202:205], v[84:87]
	v_mfma_f32_16x16x32_bf16 v[80:83], v[172:175], v[202:205], v[80:83]
	v_mfma_f32_16x16x32_bf16 v[68:71], v[148:151], v[210:213], v[68:71]
	v_mfma_f32_16x16x32_bf16 v[64:67], v[172:175], v[210:213], v[64:67]
	s_setprio 0
	s_barrier
; #define PG8_STAGE(bufoff, gbase, voff) do { _Pragma("unroll") for (int _i = 0; _i < 2; ++_i) \
;         __builtin_amdgcn_global_load_lds((const unsigned*)((const char*)(gbase) + (voff)[_i]), (PG8_LAS unsigned*)(lds + (bufoff) + ldsw + _i * 8192), 16, 0, 0); } while (0)
; #define PG8_LDA(dst, b, h) do { _Pragma("unroll") for (int m = 0; m < 4; ++m) _Pragma("unroll") for (int k = 0; k < 2; ++k) dst[m][k] = *(const PG8_LAS bf16x8*)(lds + PG8_SA(b, h) + aoff + m * 2048 + k * 1024); } while (0)
; #define PG8_MMA(ai, bj, At, Bt) do { __builtin_amdgcn_s_setprio(1); _Pragma("unroll") for (int m = 0; m < 4; ++m) _Pragma("unroll") for (int n = 0; n < 2; ++n) _Pragma("unroll") for (int k = 0; k < 2; ++k) \
;         acc[ai][bj][m][n] = __builtin_amdgcn_mfma_f32_16x16x32_bf16(Bt[n][k], At[m][k], acc[ai][bj][m][n], 0, 0, 0); __builtin_amdgcn_s_setprio(0); } while (0)
; #define PG8_WAIT_V(n) asm volatile("s_waitcnt vmcnt(" #n ")" ::: "memory")
; #define PG8_WAIT_L(n) asm volatile("s_waitcnt lgkmcnt(" #n ")" ::: "memory")
; #define PG8_BAR __builtin_amdgcn_s_barrier()
; #define PG8_SCHED __builtin_amdgcn_sched_barrier(0)
; template <class Epi, class Sched, bool ALIGN_EPI = false, bool SP2 = false>
; __device__ __forceinline__ void gemm_phase(PG8_LAS unsigned char* lds, const Gemm g, const Sched& S, const Epi& E, const int wid) {
;     ...
;         for (int t = 0; t < nt; t += 2) {
;             const bool last = (t == nt - 2);
;     ...
;             PG8_LDA(At, 1, 1); PG8_STAGE(PG8_SB(1, 0), b3, voffB); PG8_STAGE(PG8_SB(1, 1), b3 + hstep, voffB); PG8_STAGE(PG8_SA(1, 0), a3, voffA);
;             PG8_WAIT_V(8); PG8_WAIT_L(0); PG8_BAR; PG8_MMA(1, 0, At, B0); PG8_MMA(1, 1, At, B1); PG8_BAR; PG8_SCHED;
	s_add_i32 s38, s58, s41
	v_lshl_add_u64 v[214:215], v[214:215], 0, s[20:21]
	s_mov_b32 m0, s38
	ds_read_b128 v[176:179], v183 offset:49152
	ds_read_b128 v[186:189], v183 offset:50176
	ds_read_b128 v[190:193], v183 offset:51200
	ds_read_b128 v[194:197], v183 offset:52224
	ds_read_b128 v[198:201], v183 offset:53248
	ds_read_b128 v[202:205], v183 offset:54272
	ds_read_b128 v[206:209], v183 offset:55296
	ds_read_b128 v[210:213], v183 offset:56320
	global_load_lds_dwordx4 v[214:215], off
	s_add_i32 m0, s38, 0x2000
	s_add_u32 s36, s36, 0x100080
	v_lshl_add_u64 v[214:215], v[216:217], 0, s[20:21]
	s_addc_u32 s37, s37, 0
	s_add_i32 s38, s59, s41
	global_load_lds_dwordx4 v[214:215], off
	v_lshl_add_u64 v[214:215], s[36:37], 0, v[154:155]
	s_mov_b32 m0, s38
	s_nop 0
	global_load_lds_dwordx4 v[214:215], off
	v_lshl_add_u64 v[214:215], s[36:37], 0, v[158:159]
	s_add_i32 m0, s38, 0x2000
	s_nop 0
	global_load_lds_dwordx4 v[214:215], off
	v_lshl_add_u64 v[214:215], v[218:219], 0, s[20:21]
	s_mov_b32 m0, s49
	s_nop 0
	global_load_lds_dwordx4 v[214:215], off
	v_lshl_add_u64 v[214:215], v[220:221], 0, s[20:21]
	s_mov_b32 m0, s50
	s_nop 0
	global_load_lds_dwordx4 v[214:215], off
	s_waitcnt vmcnt(8)
	s_waitcnt lgkmcnt(0)
	s_barrier
	s_setprio 1
	s_waitcnt lgkmcnt(0)
	v_mfma_f32_16x16x32_bf16 v[60:63], v[128:131], v[176:179], v[60:63]
	v_mfma_f32_16x16x32_bf16 v[56:59], v[136:139], v[176:179], v[56:59]
	v_mfma_f32_16x16x32_bf16 v[44:47], v[128:131], v[190:193], v[44:47]
	v_mfma_f32_16x16x32_bf16 v[40:43], v[136:139], v[190:193], v[40:43]
	v_mfma_f32_16x16x32_bf16 v[28:31], v[128:131], v[198:201], v[28:31]
	v_mfma_f32_16x16x32_bf16 v[24:27], v[136:139], v[198:201], v[24:27]
	v_mfma_f32_16x16x32_bf16 v[12:15], v[128:131], v[206:209], v[12:15]
	v_mfma_f32_16x16x32_bf16 v[8:11], v[136:139], v[206:209], v[8:11]
	v_mfma_f32_16x16x32_bf16 v[60:63], v[132:135], v[186:189], v[60:63]
	v_mfma_f32_16x16x32_bf16 v[56:59], v[140:143], v[186:189], v[56:59]
	v_mfma_f32_16x16x32_bf16 v[44:47], v[132:135], v[194:197], v[44:47]
	v_mfma_f32_16x16x32_bf16 v[40:43], v[140:143], v[194:197], v[40:43]
	v_mfma_f32_16x16x32_bf16 v[28:31], v[132:135], v[202:205], v[28:31]
	v_mfma_f32_16x16x32_bf16 v[24:27], v[140:143], v[202:205], v[24:27]
	v_mfma_f32_16x16x32_bf16 v[12:15], v[132:135], v[210:213], v[12:15]
	v_mfma_f32_16x16x32_bf16 v[8:11], v[140:143], v[210:213], v[8:11]
	s_setprio 0
	s_setprio 1
	v_mfma_f32_16x16x32_bf16 v[52:55], v[144:147], v[176:179], v[52:55]
	v_mfma_f32_16x16x32_bf16 v[48:51], v[168:171], v[176:179], v[48:51]
	v_mfma_f32_16x16x32_bf16 v[36:39], v[144:147], v[190:193], v[36:39]
	v_mfma_f32_16x16x32_bf16 v[32:35], v[168:171], v[190:193], v[32:35]
	v_mfma_f32_16x16x32_bf16 v[20:23], v[144:147], v[198:201], v[20:23]
	v_mfma_f32_16x16x32_bf16 v[16:19], v[168:171], v[198:201], v[16:19]
	v_mfma_f32_16x16x32_bf16 v[4:7], v[144:147], v[206:209], v[4:7]
	v_mfma_f32_16x16x32_bf16 v[0:3], v[168:171], v[206:209], v[0:3]
	v_mfma_f32_16x16x32_bf16 v[52:55], v[148:151], v[186:189], v[52:55]
	v_mfma_f32_16x16x32_bf16 v[48:51], v[172:175], v[186:189], v[48:51]
	v_mfma_f32_16x16x32_bf16 v[36:39], v[148:151], v[194:197], v[36:39]
	v_mfma_f32_16x16x32_bf16 v[32:35], v[172:175], v[194:197], v[32:35]
	v_mfma_f32_16x16x32_bf16 v[20:23], v[148:151], v[202:205], v[20:23]
	v_mfma_f32_16x16x32_bf16 v[16:19], v[172:175], v[202:205], v[16:19]
	v_mfma_f32_16x16x32_bf16 v[4:7], v[148:151], v[210:213], v[4:7]
	v_mfma_f32_16x16x32_bf16 v[0:3], v[172:175], v[210:213], v[0:3]
	s_setprio 0
	s_barrier
	s_add_i32 s57, s57, 2
	s_add_u32 s34, s34, 0x100
	s_addc_u32 s35, s35, 0
	s_add_u32 s55, s55, 0x100
	s_addc_u32 s56, s56, 0
	s_cmp_gt_u32 s57, 61
	s_cbranch_scc0 .LBB0_3030
	s_mov_b32 s99, 1
	s_and_b64 vcc, exec, s[22:23]
	s_cbranch_vccz .LBB0_3033
	s_barrier
